# first K-iteration of all 7 GEMM loops peeled (first MFMA per accumulator takes C=0), the 128 accumulator-zeroing v_mov per unit removed
# speedup vs baseline: 1.0115x; 1.0035x over previous
; #define PG8_STAGE(bufoff, gbase, voff) do { _Pragma("unroll") for (int _i = 0; _i < 2; ++_i) \
;         __builtin_amdgcn_global_load_lds((const unsigned*)((const char*)(gbase) + (voff)[_i]), (PG8_LAS unsigned*)(lds + (bufoff) + ldsw + _i * 8192), 16, 0, 0); } while (0)
; #define PG8_LDA(dst, b, h) do { _Pragma("unroll") for (int m = 0; m < 4; ++m) _Pragma("unroll") for (int k = 0; k < 2; ++k) dst[m][k] = *(const PG8_LAS bf16x8*)(lds + PG8_SA(b, h) + aoff + m * 2048 + k * 1024); } while (0)
; #define PG8_LDB(dst, b, h) do { _Pragma("unroll") for (int n = 0; n < 2; ++n) _Pragma("unroll") for (int k = 0; k < 2; ++k) dst[n][k] = *(const PG8_LAS bf16x8*)(lds + PG8_SB(b, h) + boff + n * 2048 + k * 1024); } while (0)
; #define PG8_WAIT_V(n) asm volatile("s_waitcnt vmcnt(" #n ")" ::: "memory")
; #define PG8_WAIT_L(n) asm volatile("s_waitcnt lgkmcnt(" #n ")" ::: "memory")
; #define PG8_BAR __builtin_amdgcn_s_barrier()
; #define PG8_SCHED __builtin_amdgcn_sched_barrier(0)
; template <class Epi, class Sched, bool ALIGN_EPI = false, bool SP2 = false, bool I8 = false>
; __device__ __forceinline__ void gemm_phase(PG8_LAS unsigned char* lds, const Gemm g, const Sched& S, const Epi& E) {
;     ...
;         const char* nA = has_next ? (const char*)g.A + (size_t)nxt.pm * tstep : cA; const char* nB = has_next ? (const char*)g.Bt + (size_t)nxt.pn * tstep : cB;
;         for (int t = 0; t < nt; t += 2) {
;             const bool last = (t == nt - 2);
;             const char* a1 = cA + (size_t)(t + 1) * kstep;
;             const char* a2 = last ? nA : cA + (size_t)(t + 2) * kstep; const char* b2 = last ? nB : cB + (size_t)(t + 2) * kstep;
;             const char* a3 = a2 + kstep; const char* b3 = b2 + kstep;
;             if (last && has_next) S.a_ready(nxt);
;             if constexpr (SP2) {
;             PG8_LDB(B0, 0, 0); PG8_LDB(B1, 0, 1); PG8_SCHED; PG8_LDA(At, 0, 0); PG8_STAGE(PG8_SA(1, 1), a1 + hstep, voffA);
;             PG8_WAIT_V(8); PG8_WAIT_L(0); PG8_BAR; PG8_MMA(0, 0, At, B0); PG8_MMA(0, 1, At, B1); PG8_BAR; PG8_SCHED;
;             PG8_LDA(At, 0, 1); PG8_STAGE(PG8_SB(0, 0), b2, voffB); PG8_STAGE(PG8_SB(0, 1), b2 + hstep, voffB); PG8_STAGE(PG8_SA(0, 0), a2, voffA);
;             PG8_WAIT_V(8); PG8_WAIT_L(0); PG8_BAR; PG8_MMA(1, 0, At, B0); PG8_MMA(1, 1, At, B1); PG8_BAR; PG8_SCHED;
.LBB0_207:
	s_ashr_i32 s19, s18, 31
	s_lshl_b64 s[22:23], s[18:19], 20
	s_add_u32 s22, s28, s22
	s_addc_u32 s23, s34, s23
	s_and_b64 s[24:25], s[6:7], exec
	s_cselect_b32 s19, s23, s27
	s_cselect_b32 s64, s22, s26
	s_ashr_i32 s17, s16, 31
	s_lshl_b64 s[24:25], s[16:17], 20
	s_add_u32 s24, s35, s24
	s_addc_u32 s25, s42, s25
	s_and_b64 s[40:41], s[6:7], exec
	s_cselect_b32 s17, s25, s37
	s_cselect_b32 s65, s24, s36
	s_add_u32 s26, s26, 0x80080
	s_addc_u32 s27, s27, 0
	s_add_u32 s72, s36, 0x100
	s_addc_u32 s73, s37, 0
	s_mov_b32 s76, -2
	s_add_u32 s36, s26, 0xfff80080
	s_addc_u32 s37, s27, -1
	s_add_i32 s50, 0, 0x10000
	s_cmp_eq_u32 s76, 28
	s_cselect_b32 s41, s19, s37
	s_cselect_b32 s40, s64, s36
	s_cselect_b32 s37, s17, s73
	s_cselect_b32 s36, s65, s72
	s_add_i32 s56, 0, 0x14000
	v_add_u32_e32 v136, s50, v175
	v_add_u32_e32 v172, s56, v175
	ds_read_b128 v[116:119], v136
	ds_read_b128 v[124:127], v136 offset:1024
	ds_read_b128 v[132:135], v136 offset:2048
	ds_read_b128 v[136:139], v136 offset:3072
	ds_read_b128 v[160:163], v172
	ds_read_b128 v[164:167], v172 offset:1024
	ds_read_b128 v[168:171], v172 offset:2048
	ds_read_b128 v[178:181], v172 offset:3072
	v_lshl_add_u64 v[172:173], s[26:27], 0, v[156:157]
	s_add_i32 m0, s44, 0xc000
	ds_read_b128 v[182:185], v177
	ds_read_b128 v[186:189], v177 offset:1024
	ds_read_b128 v[204:207], v177 offset:2048
	ds_read_b128 v[208:211], v177 offset:3072
	ds_read_b128 v[212:215], v177 offset:4096
	ds_read_b128 v[216:219], v177 offset:5120
	ds_read_b128 v[220:223], v177 offset:6144
	ds_read_b128 v[224:227], v177 offset:7168
	global_load_lds_dwordx4 v[172:173], off
	v_lshl_add_u64 v[172:173], s[26:27], 0, v[158:159]
	s_add_i32 m0, s44, 0xe000
	s_nop 0
	global_load_lds_dwordx4 v[172:173], off
	s_waitcnt vmcnt(8)
	s_waitcnt lgkmcnt(0)
	s_barrier
	s_setprio 1
	s_waitcnt lgkmcnt(0)
	v_mfma_i32_16x16x64_i8 v[144:147], v[116:119], v[182:185], 0
	v_mfma_i32_16x16x64_i8 v[140:143], v[132:135], v[182:185], 0
	v_mfma_i32_16x16x64_i8 v[112:115], v[116:119], v[204:207], 0
	v_mfma_i32_16x16x64_i8 v[108:111], v[132:135], v[204:207], 0
	v_mfma_i32_16x16x64_i8 v[96:99], v[116:119], v[212:215], 0
	v_mfma_i32_16x16x64_i8 v[92:95], v[132:135], v[212:215], 0
	v_mfma_i32_16x16x64_i8 v[80:83], v[116:119], v[220:223], 0
	v_mfma_i32_16x16x64_i8 v[76:79], v[132:135], v[220:223], 0
	v_mfma_i32_16x16x64_i8 v[144:147], v[124:127], v[186:189], v[144:147]
	v_mfma_i32_16x16x64_i8 v[140:143], v[136:139], v[186:189], v[140:143]
	v_mfma_i32_16x16x64_i8 v[112:115], v[124:127], v[208:211], v[112:115]
	v_mfma_i32_16x16x64_i8 v[108:111], v[136:139], v[208:211], v[108:111]
	v_mfma_i32_16x16x64_i8 v[96:99], v[124:127], v[216:219], v[96:99]
	v_mfma_i32_16x16x64_i8 v[92:95], v[136:139], v[216:219], v[92:95]
	v_mfma_i32_16x16x64_i8 v[80:83], v[124:127], v[224:227], v[80:83]
	v_mfma_i32_16x16x64_i8 v[76:79], v[136:139], v[224:227], v[76:79]
	s_setprio 0
	s_setprio 1
	v_mfma_i32_16x16x64_i8 v[128:131], v[160:163], v[182:185], 0
	v_mfma_i32_16x16x64_i8 v[120:123], v[168:171], v[182:185], 0
	v_mfma_i32_16x16x64_i8 v[104:107], v[160:163], v[204:207], 0
	v_mfma_i32_16x16x64_i8 v[100:103], v[168:171], v[204:207], 0
	v_mfma_i32_16x16x64_i8 v[88:91], v[160:163], v[212:215], 0
	v_mfma_i32_16x16x64_i8 v[84:87], v[168:171], v[212:215], 0
	v_mfma_i32_16x16x64_i8 v[72:75], v[160:163], v[220:223], 0
	v_mfma_i32_16x16x64_i8 v[68:71], v[168:171], v[220:223], 0
	v_mfma_i32_16x16x64_i8 v[128:131], v[164:167], v[186:189], v[128:131]
	v_mfma_i32_16x16x64_i8 v[120:123], v[178:181], v[186:189], v[120:123]
	v_mfma_i32_16x16x64_i8 v[104:107], v[164:167], v[208:211], v[104:107]
	v_mfma_i32_16x16x64_i8 v[100:103], v[178:181], v[208:211], v[100:103]
	v_mfma_i32_16x16x64_i8 v[88:91], v[164:167], v[216:219], v[88:91]
	v_mfma_i32_16x16x64_i8 v[84:87], v[178:181], v[216:219], v[84:87]
	v_mfma_i32_16x16x64_i8 v[72:75], v[164:167], v[224:227], v[72:75]
	v_mfma_i32_16x16x64_i8 v[68:71], v[178:181], v[224:227], v[68:71]
	s_setprio 0
	s_barrier
	s_add_i32 s50, s50, s43
	v_lshl_add_u64 v[172:173], s[36:37], 0, v[2:3]
	s_mov_b32 m0, s50
	ds_read_b128 v[182:185], v177 offset:16384
	ds_read_b128 v[186:189], v177 offset:17408
	ds_read_b128 v[204:207], v177 offset:18432
	ds_read_b128 v[208:211], v177 offset:19456
	ds_read_b128 v[212:215], v177 offset:20480
	ds_read_b128 v[216:219], v177 offset:21504
	ds_read_b128 v[220:223], v177 offset:22528
	ds_read_b128 v[224:227], v177 offset:23552
	global_load_lds_dwordx4 v[172:173], off
	s_add_i32 m0, s50, 0x2000
	s_add_u32 s50, s36, 0x80000
	v_lshl_add_u64 v[190:191], s[36:37], 0, v[148:149]
	s_addc_u32 s51, s37, 0
	s_add_i32 s56, s56, s43
	global_load_lds_dwordx4 v[190:191], off
	v_lshl_add_u64 v[228:229], s[50:51], 0, v[2:3]
	s_mov_b32 m0, s56
	v_lshl_add_u64 v[240:241], s[40:41], 0, v[150:151]
	global_load_lds_dwordx4 v[228:229], off
	v_lshl_add_u64 v[228:229], s[50:51], 0, v[148:149]
	s_add_i32 m0, s56, 0x2000
	s_nop 0
	global_load_lds_dwordx4 v[228:229], off
	v_lshl_add_u64 v[228:229], s[40:41], 0, v[152:153]
	s_mov_b32 m0, s44
	s_nop 0
	global_load_lds_dwordx4 v[228:229], off
	s_mov_b32 m0, s45
	s_nop 0
	global_load_lds_dwordx4 v[240:241], off
	s_waitcnt vmcnt(8)
	s_waitcnt lgkmcnt(0)
	s_barrier
; #define PG8_STAGE(bufoff, gbase, voff) do { _Pragma("unroll") for (int _i = 0; _i < 2; ++_i) \
;         __builtin_amdgcn_global_load_lds((const unsigned*)((const char*)(gbase) + (voff)[_i]), (PG8_LAS unsigned*)(lds + (bufoff) + ldsw + _i * 8192), 16, 0, 0); } while (0)
; #define PG8_LDA(dst, b, h) do { _Pragma("unroll") for (int m = 0; m < 4; ++m) _Pragma("unroll") for (int k = 0; k < 2; ++k) dst[m][k] = *(const PG8_LAS bf16x8*)(lds + PG8_SA(b, h) + aoff + m * 2048 + k * 1024); } while (0)
; #define PG8_LDB(dst, b, h) do { _Pragma("unroll") for (int n = 0; n < 2; ++n) _Pragma("unroll") for (int k = 0; k < 2; ++k) dst[n][k] = *(const PG8_LAS bf16x8*)(lds + PG8_SB(b, h) + boff + n * 2048 + k * 1024); } while (0)
; #define PG8_WAIT_V(n) asm volatile("s_waitcnt vmcnt(" #n ")" ::: "memory")
; #define PG8_WAIT_L(n) asm volatile("s_waitcnt lgkmcnt(" #n ")" ::: "memory")
; #define PG8_BAR __builtin_amdgcn_s_barrier()
; #define PG8_SCHED __builtin_amdgcn_sched_barrier(0)
; template <class Epi, class Sched, bool ALIGN_EPI = false, bool SP2 = false, bool I8 = false>
; __device__ __forceinline__ void gemm_phase(PG8_LAS unsigned char* lds, const Gemm g, const Sched& S, const Epi& E) {
;     ...
;             PG8_WAIT_V(8); PG8_WAIT_L(0); PG8_BAR; PG8_MMA(1, 0, At, B0); PG8_MMA(1, 1, At, B1); PG8_BAR; PG8_SCHED;
;             PG8_LDB(B0, 1, 0); PG8_LDB(B1, 1, 1); PG8_SCHED; PG8_LDA(At, 1, 0); PG8_STAGE(PG8_SA(0, 1), a2 + hstep, voffA);
;             PG8_WAIT_V(8); PG8_WAIT_L(0); PG8_BAR; PG8_MMA(0, 0, At, B0); PG8_MMA(0, 1, At, B1); PG8_BAR; PG8_SCHED;
	s_setprio 1
	s_waitcnt lgkmcnt(0)
	v_mfma_i32_16x16x64_i8 v[64:67], v[116:119], v[182:185], 0
	v_mfma_i32_16x16x64_i8 v[60:63], v[132:135], v[182:185], 0
	v_mfma_i32_16x16x64_i8 v[48:51], v[116:119], v[204:207], 0
	v_mfma_i32_16x16x64_i8 v[44:47], v[132:135], v[204:207], 0
	v_mfma_i32_16x16x64_i8 v[32:35], v[116:119], v[212:215], 0
	v_mfma_i32_16x16x64_i8 v[28:31], v[132:135], v[212:215], 0
	v_mfma_i32_16x16x64_i8 v[16:19], v[116:119], v[220:223], 0
	v_mfma_i32_16x16x64_i8 v[12:15], v[132:135], v[220:223], 0
	v_mfma_i32_16x16x64_i8 v[64:67], v[124:127], v[186:189], v[64:67]
	v_mfma_i32_16x16x64_i8 v[60:63], v[136:139], v[186:189], v[60:63]
	v_mfma_i32_16x16x64_i8 v[48:51], v[124:127], v[208:211], v[48:51]
	v_mfma_i32_16x16x64_i8 v[44:47], v[136:139], v[208:211], v[44:47]
	v_mfma_i32_16x16x64_i8 v[32:35], v[124:127], v[216:219], v[32:35]
	v_mfma_i32_16x16x64_i8 v[28:31], v[136:139], v[216:219], v[28:31]
	v_mfma_i32_16x16x64_i8 v[16:19], v[124:127], v[224:227], v[16:19]
	v_mfma_i32_16x16x64_i8 v[12:15], v[136:139], v[224:227], v[12:15]
	s_setprio 0
	s_setprio 1
	v_mfma_i32_16x16x64_i8 v[56:59], v[160:163], v[182:185], 0
	v_mfma_i32_16x16x64_i8 v[52:55], v[168:171], v[182:185], 0
	v_mfma_i32_16x16x64_i8 v[40:43], v[160:163], v[204:207], 0
	v_mfma_i32_16x16x64_i8 v[36:39], v[168:171], v[204:207], 0
	v_mfma_i32_16x16x64_i8 v[24:27], v[160:163], v[212:215], 0
	v_mfma_i32_16x16x64_i8 v[20:23], v[168:171], v[212:215], 0
	v_mfma_i32_16x16x64_i8 v[8:11], v[160:163], v[220:223], 0
	v_mfma_i32_16x16x64_i8 v[4:7], v[168:171], v[220:223], 0
	v_mfma_i32_16x16x64_i8 v[56:59], v[164:167], v[186:189], v[56:59]
	v_mfma_i32_16x16x64_i8 v[52:55], v[178:181], v[186:189], v[52:55]
	v_mfma_i32_16x16x64_i8 v[40:43], v[164:167], v[208:211], v[40:43]
	v_mfma_i32_16x16x64_i8 v[36:39], v[178:181], v[208:211], v[36:39]
	v_mfma_i32_16x16x64_i8 v[24:27], v[164:167], v[216:219], v[24:27]
	v_mfma_i32_16x16x64_i8 v[20:23], v[178:181], v[216:219], v[20:23]
	v_mfma_i32_16x16x64_i8 v[8:11], v[164:167], v[224:227], v[8:11]
	v_mfma_i32_16x16x64_i8 v[4:7], v[178:181], v[224:227], v[4:7]
	s_setprio 0
	s_barrier
	s_add_i32 s50, 0, 0x18000
	s_add_i32 s51, 0, 0x1c000
	v_add_u32_e32 v136, s50, v175
	v_add_u32_e32 v178, s51, v175
	ds_read_b128 v[116:119], v136
	ds_read_b128 v[124:127], v136 offset:1024
	ds_read_b128 v[132:135], v136 offset:2048
	ds_read_b128 v[136:139], v136 offset:3072
	ds_read_b128 v[160:163], v178
	ds_read_b128 v[164:167], v178 offset:1024
	ds_read_b128 v[168:171], v178 offset:2048
	ds_read_b128 v[178:181], v178 offset:3072
	s_add_u32 s40, s40, 0x80000
	s_addc_u32 s41, s41, 0
	s_mov_b32 m0, s46
	v_lshl_add_u64 v[242:243], s[40:41], 0, v[152:153]
	ds_read_b128 v[182:185], v177 offset:32768
	ds_read_b128 v[186:189], v177 offset:33792
	ds_read_b128 v[204:207], v177 offset:34816
	ds_read_b128 v[208:211], v177 offset:35840
	ds_read_b128 v[212:215], v177 offset:36864
	ds_read_b128 v[216:219], v177 offset:37888
	ds_read_b128 v[220:223], v177 offset:38912
	ds_read_b128 v[224:227], v177 offset:39936
	global_load_lds_dwordx4 v[242:243], off
	v_lshl_add_u64 v[242:243], s[40:41], 0, v[150:151]
	s_mov_b32 m0, s47
	s_nop 0
	global_load_lds_dwordx4 v[242:243], off
	s_waitcnt vmcnt(8)
	s_waitcnt lgkmcnt(0)
	s_barrier
	s_setprio 1
	s_waitcnt lgkmcnt(0)
	v_mfma_i32_16x16x64_i8 v[144:147], v[116:119], v[182:185], v[144:147]
	v_mfma_i32_16x16x64_i8 v[140:143], v[132:135], v[182:185], v[140:143]
	v_mfma_i32_16x16x64_i8 v[112:115], v[116:119], v[204:207], v[112:115]
	v_mfma_i32_16x16x64_i8 v[108:111], v[132:135], v[204:207], v[108:111]
	v_mfma_i32_16x16x64_i8 v[96:99], v[116:119], v[212:215], v[96:99]
	v_mfma_i32_16x16x64_i8 v[92:95], v[132:135], v[212:215], v[92:95]
	v_mfma_i32_16x16x64_i8 v[80:83], v[116:119], v[220:223], v[80:83]
	v_mfma_i32_16x16x64_i8 v[76:79], v[132:135], v[220:223], v[76:79]
	v_mfma_i32_16x16x64_i8 v[144:147], v[124:127], v[186:189], v[144:147]
	v_mfma_i32_16x16x64_i8 v[140:143], v[136:139], v[186:189], v[140:143]
	v_mfma_i32_16x16x64_i8 v[112:115], v[124:127], v[208:211], v[112:115]
	v_mfma_i32_16x16x64_i8 v[108:111], v[136:139], v[208:211], v[108:111]
	v_mfma_i32_16x16x64_i8 v[96:99], v[124:127], v[216:219], v[96:99]
	v_mfma_i32_16x16x64_i8 v[92:95], v[136:139], v[216:219], v[92:95]
	v_mfma_i32_16x16x64_i8 v[80:83], v[124:127], v[224:227], v[80:83]
	v_mfma_i32_16x16x64_i8 v[76:79], v[136:139], v[224:227], v[76:79]
	s_setprio 0
	s_setprio 1
	v_mfma_i32_16x16x64_i8 v[128:131], v[160:163], v[182:185], v[128:131]
	v_mfma_i32_16x16x64_i8 v[120:123], v[168:171], v[182:185], v[120:123]
	v_mfma_i32_16x16x64_i8 v[104:107], v[160:163], v[204:207], v[104:107]
	v_mfma_i32_16x16x64_i8 v[100:103], v[168:171], v[204:207], v[100:103]
	v_mfma_i32_16x16x64_i8 v[88:91], v[160:163], v[212:215], v[88:91]
	v_mfma_i32_16x16x64_i8 v[84:87], v[168:171], v[212:215], v[84:87]
	v_mfma_i32_16x16x64_i8 v[72:75], v[160:163], v[220:223], v[72:75]
	v_mfma_i32_16x16x64_i8 v[68:71], v[168:171], v[220:223], v[68:71]
	v_mfma_i32_16x16x64_i8 v[128:131], v[164:167], v[186:189], v[128:131]
	v_mfma_i32_16x16x64_i8 v[120:123], v[178:181], v[186:189], v[120:123]
	v_mfma_i32_16x16x64_i8 v[104:107], v[164:167], v[208:211], v[104:107]
	v_mfma_i32_16x16x64_i8 v[100:103], v[178:181], v[208:211], v[100:103]
	v_mfma_i32_16x16x64_i8 v[88:91], v[164:167], v[216:219], v[88:91]
	v_mfma_i32_16x16x64_i8 v[84:87], v[178:181], v[216:219], v[84:87]
	v_mfma_i32_16x16x64_i8 v[72:75], v[164:167], v[224:227], v[72:75]
	v_mfma_i32_16x16x64_i8 v[68:71], v[178:181], v[224:227], v[68:71]
	s_setprio 0
	s_barrier
; #define PG8_STAGE(bufoff, gbase, voff) do { _Pragma("unroll") for (int _i = 0; _i < 2; ++_i) \
;         __builtin_amdgcn_global_load_lds((const unsigned*)((const char*)(gbase) + (voff)[_i]), (PG8_LAS unsigned*)(lds + (bufoff) + ldsw + _i * 8192), 16, 0, 0); } while (0)
; #define PG8_LDA(dst, b, h) do { _Pragma("unroll") for (int m = 0; m < 4; ++m) _Pragma("unroll") for (int k = 0; k < 2; ++k) dst[m][k] = *(const PG8_LAS bf16x8*)(lds + PG8_SA(b, h) + aoff + m * 2048 + k * 1024); } while (0)
; #define PG8_WAIT_V(n) asm volatile("s_waitcnt vmcnt(" #n ")" ::: "memory")
; #define PG8_WAIT_L(n) asm volatile("s_waitcnt lgkmcnt(" #n ")" ::: "memory")
; #define PG8_BAR __builtin_amdgcn_s_barrier()
; #define PG8_SCHED __builtin_amdgcn_sched_barrier(0)
; template <class Epi, class Sched, bool ALIGN_EPI = false, bool SP2 = false, bool I8 = false>
; __device__ __forceinline__ void gemm_phase(PG8_LAS unsigned char* lds, const Gemm g, const Sched& S, const Epi& E) {
;     ...
;             PG8_LDA(At, 1, 1); PG8_STAGE(PG8_SB(1, 0), b3, voffB); PG8_STAGE(PG8_SB(1, 1), b3 + hstep, voffB); PG8_STAGE(PG8_SA(1, 0), a3, voffA);
;             PG8_WAIT_V(8); PG8_WAIT_L(0); PG8_BAR; PG8_MMA(1, 0, At, B0); PG8_MMA(1, 1, At, B1); PG8_BAR; PG8_SCHED;
	s_add_i32 s40, s50, s43
	v_lshl_add_u64 v[172:173], v[172:173], 0, s[84:85]
	s_mov_b32 m0, s40
	ds_read_b128 v[182:185], v177 offset:49152
	ds_read_b128 v[186:189], v177 offset:50176
	ds_read_b128 v[204:207], v177 offset:51200
	ds_read_b128 v[208:211], v177 offset:52224
	ds_read_b128 v[212:215], v177 offset:53248
	ds_read_b128 v[216:219], v177 offset:54272
	ds_read_b128 v[220:223], v177 offset:55296
	ds_read_b128 v[224:227], v177 offset:56320
	global_load_lds_dwordx4 v[172:173], off
	s_add_i32 m0, s40, 0x2000
	s_add_u32 s36, s36, 0x80080
	v_lshl_add_u64 v[172:173], v[190:191], 0, s[84:85]
	s_addc_u32 s37, s37, 0
	s_add_i32 s40, s51, s43
	global_load_lds_dwordx4 v[172:173], off
	v_lshl_add_u64 v[172:173], s[36:37], 0, v[2:3]
	s_mov_b32 m0, s40
	s_nop 0
	global_load_lds_dwordx4 v[172:173], off
	v_lshl_add_u64 v[172:173], s[36:37], 0, v[148:149]
	s_add_i32 m0, s40, 0x2000
	s_nop 0
	global_load_lds_dwordx4 v[172:173], off
	v_lshl_add_u64 v[172:173], v[228:229], 0, s[84:85]
	s_mov_b32 m0, s52
	s_nop 0
	global_load_lds_dwordx4 v[172:173], off
	v_lshl_add_u64 v[172:173], v[240:241], 0, s[84:85]
	s_mov_b32 m0, s53
	s_nop 0
	global_load_lds_dwordx4 v[172:173], off
	s_waitcnt vmcnt(8)
	s_waitcnt lgkmcnt(0)
	s_barrier
	s_setprio 1
	s_waitcnt lgkmcnt(0)
	v_mfma_i32_16x16x64_i8 v[64:67], v[116:119], v[182:185], v[64:67]
	v_mfma_i32_16x16x64_i8 v[60:63], v[132:135], v[182:185], v[60:63]
	v_mfma_i32_16x16x64_i8 v[48:51], v[116:119], v[204:207], v[48:51]
	v_mfma_i32_16x16x64_i8 v[44:47], v[132:135], v[204:207], v[44:47]
	v_mfma_i32_16x16x64_i8 v[32:35], v[116:119], v[212:215], v[32:35]
	v_mfma_i32_16x16x64_i8 v[28:31], v[132:135], v[212:215], v[28:31]
	v_mfma_i32_16x16x64_i8 v[16:19], v[116:119], v[220:223], v[16:19]
	v_mfma_i32_16x16x64_i8 v[12:15], v[132:135], v[220:223], v[12:15]
	v_mfma_i32_16x16x64_i8 v[64:67], v[124:127], v[186:189], v[64:67]
	v_mfma_i32_16x16x64_i8 v[60:63], v[136:139], v[186:189], v[60:63]
	v_mfma_i32_16x16x64_i8 v[48:51], v[124:127], v[208:211], v[48:51]
	v_mfma_i32_16x16x64_i8 v[44:47], v[136:139], v[208:211], v[44:47]
	v_mfma_i32_16x16x64_i8 v[32:35], v[124:127], v[216:219], v[32:35]
	v_mfma_i32_16x16x64_i8 v[28:31], v[136:139], v[216:219], v[28:31]
	v_mfma_i32_16x16x64_i8 v[16:19], v[124:127], v[224:227], v[16:19]
	v_mfma_i32_16x16x64_i8 v[12:15], v[136:139], v[224:227], v[12:15]
	s_setprio 0
	s_setprio 1
	v_mfma_i32_16x16x64_i8 v[56:59], v[160:163], v[182:185], v[56:59]
	v_mfma_i32_16x16x64_i8 v[52:55], v[168:171], v[182:185], v[52:55]
	v_mfma_i32_16x16x64_i8 v[40:43], v[160:163], v[204:207], v[40:43]
	v_mfma_i32_16x16x64_i8 v[36:39], v[168:171], v[204:207], v[36:39]
	v_mfma_i32_16x16x64_i8 v[24:27], v[160:163], v[212:215], v[24:27]
	v_mfma_i32_16x16x64_i8 v[20:23], v[168:171], v[212:215], v[20:23]
	v_mfma_i32_16x16x64_i8 v[8:11], v[160:163], v[220:223], v[8:11]
	v_mfma_i32_16x16x64_i8 v[4:7], v[168:171], v[220:223], v[4:7]
	v_mfma_i32_16x16x64_i8 v[56:59], v[164:167], v[186:189], v[56:59]
	v_mfma_i32_16x16x64_i8 v[52:55], v[178:181], v[186:189], v[52:55]
	v_mfma_i32_16x16x64_i8 v[40:43], v[164:167], v[208:211], v[40:43]
	v_mfma_i32_16x16x64_i8 v[36:39], v[178:181], v[208:211], v[36:39]
	v_mfma_i32_16x16x64_i8 v[24:27], v[164:167], v[216:219], v[24:27]
	v_mfma_i32_16x16x64_i8 v[20:23], v[178:181], v[216:219], v[20:23]
	v_mfma_i32_16x16x64_i8 v[8:11], v[164:167], v[224:227], v[8:11]
	v_mfma_i32_16x16x64_i8 v[4:7], v[178:181], v[224:227], v[4:7]
	s_setprio 0
	s_barrier
	s_add_i32 s76, s76, 2
	s_add_u32 s26, s26, 0x100
	s_addc_u32 s27, s27, 0
	s_add_u32 s72, s72, 0x100
	s_addc_u32 s73, s73, 0
	s_cmp_gt_u32 s76, 29
	s_cbranch_scc1 .Lkloop_exit_0

; #define PG8_BAR __builtin_amdgcn_s_barrier()
; template <class Epi, class Sched, bool ALIGN_EPI = false, bool SP2 = false, bool I8 = false>
; __device__ __forceinline__ void gemm_phase(PG8_LAS unsigned char* lds, const Gemm g, const Sched& S, const Epi& E) {
;     ...
;         }
;         if constexpr (ALIGN_EPI) { if (wr == 0) PG8_BAR; }
;         if constexpr (!Epi::AFTER_DRAIN) { E(acc, cur, wr, wc, fr, fq); S.done(cur); }
.Lkloop_exit_0:
	s_and_b64 vcc, exec, s[14:15]
	s_cbranch_vccz .LBB0_211
	s_barrier

; #define PG8_STAGE(bufoff, gbase, voff) do { _Pragma("unroll") for (int _i = 0; _i < 2; ++_i) \
;         __builtin_amdgcn_global_load_lds((const unsigned*)((const char*)(gbase) + (voff)[_i]), (PG8_LAS unsigned*)(lds + (bufoff) + ldsw + _i * 8192), 16, 0, 0); } while (0)
; #define PG8_LDA(dst, b, h) do { _Pragma("unroll") for (int m = 0; m < 4; ++m) _Pragma("unroll") for (int k = 0; k < 2; ++k) dst[m][k] = *(const PG8_LAS bf16x8*)(lds + PG8_SA(b, h) + aoff + m * 2048 + k * 1024); } while (0)
; #define PG8_LDB(dst, b, h) do { _Pragma("unroll") for (int n = 0; n < 2; ++n) _Pragma("unroll") for (int k = 0; k < 2; ++k) dst[n][k] = *(const PG8_LAS bf16x8*)(lds + PG8_SB(b, h) + boff + n * 2048 + k * 1024); } while (0)
; #define PG8_WAIT_V(n) asm volatile("s_waitcnt vmcnt(" #n ")" ::: "memory")
; #define PG8_WAIT_L(n) asm volatile("s_waitcnt lgkmcnt(" #n ")" ::: "memory")
; #define PG8_BAR __builtin_amdgcn_s_barrier()
; #define PG8_SCHED __builtin_amdgcn_sched_barrier(0)
; template <class Epi, class Sched, bool ALIGN_EPI = false, bool SP2 = false, bool I8 = false>
; __device__ __forceinline__ void gemm_phase(PG8_LAS unsigned char* lds, const Gemm g, const Sched& S, const Epi& E) {
;     ...
;         const char* nA = has_next ? (const char*)g.A + (size_t)nxt.pm * tstep : cA; const char* nB = has_next ? (const char*)g.Bt + (size_t)nxt.pn * tstep : cB;
;         for (int t = 0; t < nt; t += 2) {
;             const bool last = (t == nt - 2);
;             const char* a1 = cA + (size_t)(t + 1) * kstep;
;             const char* a2 = last ? nA : cA + (size_t)(t + 2) * kstep; const char* b2 = last ? nB : cB + (size_t)(t + 2) * kstep;
;             const char* a3 = a2 + kstep; const char* b3 = b2 + kstep;
;             if (last && has_next) S.a_ready(nxt);
;             if constexpr (SP2) {
;             PG8_LDB(B0, 0, 0); PG8_LDB(B1, 0, 1); PG8_SCHED; PG8_LDA(At, 0, 0); PG8_STAGE(PG8_SA(1, 1), a1 + hstep, voffA);
;             PG8_WAIT_V(8); PG8_WAIT_L(0); PG8_BAR; PG8_MMA(0, 0, At, B0); PG8_MMA(0, 1, At, B1); PG8_BAR; PG8_SCHED;
;             PG8_LDA(At, 0, 1); PG8_STAGE(PG8_SB(0, 0), b2, voffB); PG8_STAGE(PG8_SB(0, 1), b2 + hstep, voffB); PG8_STAGE(PG8_SA(0, 0), a2, voffA);
;             PG8_WAIT_V(8); PG8_WAIT_L(0); PG8_BAR; PG8_MMA(1, 0, At, B0); PG8_MMA(1, 1, At, B1); PG8_BAR; PG8_SCHED;
.LBB0_229:
	s_ashr_i32 s37, s36, 31
	s_lshl_b64 s[34:35], s[36:37], 21
	s_add_u32 s40, s42, s34
	s_addc_u32 s41, s43, s35
	s_and_b64 s[34:35], s[8:9], exec
	s_cselect_b32 s11, s41, s13
	s_cselect_b32 s34, s40, s12
	s_ashr_i32 s27, s26, 31
	s_lshl_b64 s[50:51], s[26:27], 21
	s_add_u32 s54, s44, s50
	s_addc_u32 s55, s45, s51
	s_and_b64 s[50:51], s[8:9], exec
	s_cselect_b32 s27, s55, s73
	s_cselect_b32 s35, s54, s72
	s_add_u32 s12, s12, 0x100080
	s_addc_u32 s13, s13, 0
	s_add_u32 s37, s72, 0x100
	s_addc_u32 s61, s73, 0
	s_mov_b32 s97, -2
	s_add_u32 s50, s12, 0xfff00080
	s_addc_u32 s51, s13, -1
	s_add_i32 s56, 0, 0x10000
	s_cmp_eq_u32 s97, 60
	s_cselect_b32 s77, s11, s51
	s_cselect_b32 s76, s34, s50
	s_cselect_b32 s73, s27, s61
	s_cselect_b32 s72, s35, s37
	s_add_i32 s57, 0, 0x14000
	v_add_u32_e32 v156, s56, v171
	v_add_u32_e32 v168, s57, v171
	s_waitcnt vmcnt(0)
	ds_read_b128 v[112:115], v156
	ds_read_b128 v[120:123], v156 offset:1024
	ds_read_b128 v[152:155], v156 offset:2048
	ds_read_b128 v[156:159], v156 offset:3072
	ds_read_b128 v[160:163], v168
	ds_read_b128 v[164:167], v168 offset:1024
	s_waitcnt lgkmcnt(0)
	ds_read_b128 v[176:179], v168 offset:2048
	ds_read_b128 v[180:183], v168 offset:3072
	v_lshl_add_u64 v[168:169], s[12:13], 0, v[148:149]
	s_add_i32 m0, s47, 0xc000
	ds_read_b128 v[184:187], v173
	ds_read_b128 v[188:191], v173 offset:1024
	ds_read_b128 v[204:207], v173 offset:2048
	ds_read_b128 v[208:211], v173 offset:3072
	ds_read_b128 v[212:215], v173 offset:4096
	ds_read_b128 v[216:219], v173 offset:5120
	ds_read_b128 v[220:223], v173 offset:6144
	ds_read_b128 v[224:227], v173 offset:7168
	global_load_lds_dwordx4 v[168:169], off
	v_lshl_add_u64 v[168:169], s[12:13], 0, v[150:151]
	s_add_i32 m0, s47, 0xe000
	s_nop 0
	global_load_lds_dwordx4 v[168:169], off
	s_waitcnt vmcnt(8)
	s_waitcnt lgkmcnt(0)
	s_barrier
	s_setprio 1
	s_waitcnt lgkmcnt(0)
	v_mfma_f32_16x16x32_bf16 v[136:139], v[112:115], v[184:187], 0
	v_mfma_f32_16x16x32_bf16 v[132:135], v[152:155], v[184:187], 0
	v_mfma_f32_16x16x32_bf16 v[116:119], v[112:115], v[204:207], 0
	v_mfma_f32_16x16x32_bf16 v[108:111], v[152:155], v[204:207], 0
	v_mfma_f32_16x16x32_bf16 v[96:99], v[112:115], v[212:215], 0
	v_mfma_f32_16x16x32_bf16 v[92:95], v[152:155], v[212:215], 0
	v_mfma_f32_16x16x32_bf16 v[80:83], v[112:115], v[220:223], 0
	v_mfma_f32_16x16x32_bf16 v[76:79], v[152:155], v[220:223], 0
	v_mfma_f32_16x16x32_bf16 v[136:139], v[120:123], v[188:191], v[136:139]
	v_mfma_f32_16x16x32_bf16 v[132:135], v[156:159], v[188:191], v[132:135]
	v_mfma_f32_16x16x32_bf16 v[116:119], v[120:123], v[208:211], v[116:119]
	v_mfma_f32_16x16x32_bf16 v[108:111], v[156:159], v[208:211], v[108:111]
	v_mfma_f32_16x16x32_bf16 v[96:99], v[120:123], v[216:219], v[96:99]
	v_mfma_f32_16x16x32_bf16 v[92:95], v[156:159], v[216:219], v[92:95]
	v_mfma_f32_16x16x32_bf16 v[80:83], v[120:123], v[224:227], v[80:83]
	v_mfma_f32_16x16x32_bf16 v[76:79], v[156:159], v[224:227], v[76:79]
	s_setprio 0
	s_setprio 1
	v_mfma_f32_16x16x32_bf16 v[128:131], v[160:163], v[184:187], 0
	v_mfma_f32_16x16x32_bf16 v[124:127], v[176:179], v[184:187], 0
	v_mfma_f32_16x16x32_bf16 v[104:107], v[160:163], v[204:207], 0
	v_mfma_f32_16x16x32_bf16 v[100:103], v[176:179], v[204:207], 0
	v_mfma_f32_16x16x32_bf16 v[88:91], v[160:163], v[212:215], 0
	v_mfma_f32_16x16x32_bf16 v[84:87], v[176:179], v[212:215], 0
	v_mfma_f32_16x16x32_bf16 v[72:75], v[160:163], v[220:223], 0
	v_mfma_f32_16x16x32_bf16 v[68:71], v[176:179], v[220:223], 0
	v_mfma_f32_16x16x32_bf16 v[128:131], v[164:167], v[188:191], v[128:131]
	v_mfma_f32_16x16x32_bf16 v[124:127], v[180:183], v[188:191], v[124:127]
	v_mfma_f32_16x16x32_bf16 v[104:107], v[164:167], v[208:211], v[104:107]
	v_mfma_f32_16x16x32_bf16 v[100:103], v[180:183], v[208:211], v[100:103]
	v_mfma_f32_16x16x32_bf16 v[88:91], v[164:167], v[216:219], v[88:91]
	v_mfma_f32_16x16x32_bf16 v[84:87], v[180:183], v[216:219], v[84:87]
	v_mfma_f32_16x16x32_bf16 v[72:75], v[164:167], v[224:227], v[72:75]
	v_mfma_f32_16x16x32_bf16 v[68:71], v[180:183], v[224:227], v[68:71]
	s_setprio 0
	s_barrier
	s_add_i32 s50, s56, s46
	v_lshl_add_u64 v[168:169], s[72:73], 0, v[2:3]
	s_mov_b32 m0, s50
	ds_read_b128 v[184:187], v173 offset:16384
	ds_read_b128 v[188:191], v173 offset:17408
	ds_read_b128 v[204:207], v173 offset:18432
	ds_read_b128 v[208:211], v173 offset:19456
	ds_read_b128 v[212:215], v173 offset:20480
	ds_read_b128 v[216:219], v173 offset:21504
	ds_read_b128 v[220:223], v173 offset:22528
	ds_read_b128 v[224:227], v173 offset:23552
	global_load_lds_dwordx4 v[168:169], off
	s_add_i32 m0, s50, 0x2000
	s_add_u32 s50, s72, 0x100000
	v_lshl_add_u64 v[228:229], s[72:73], 0, v[144:145]
	s_addc_u32 s51, s73, 0
	s_add_i32 s56, s57, s46
	global_load_lds_dwordx4 v[228:229], off
	v_lshl_add_u64 v[240:241], s[50:51], 0, v[2:3]
	s_mov_b32 m0, s56
	v_lshl_add_u64 v[242:243], s[76:77], 0, v[142:143]
	global_load_lds_dwordx4 v[240:241], off
	v_lshl_add_u64 v[240:241], s[50:51], 0, v[144:145]
	s_add_i32 m0, s56, 0x2000
	s_nop 0
	global_load_lds_dwordx4 v[240:241], off
	v_lshl_add_u64 v[240:241], s[76:77], 0, v[140:141]
	s_mov_b32 m0, s47
	s_nop 0
	global_load_lds_dwordx4 v[240:241], off
	s_mov_b32 m0, s52
	s_nop 0
	global_load_lds_dwordx4 v[242:243], off
	s_waitcnt vmcnt(8)
	s_waitcnt lgkmcnt(0)
	s_barrier
; #define PG8_STAGE(bufoff, gbase, voff) do { _Pragma("unroll") for (int _i = 0; _i < 2; ++_i) \
;         __builtin_amdgcn_global_load_lds((const unsigned*)((const char*)(gbase) + (voff)[_i]), (PG8_LAS unsigned*)(lds + (bufoff) + ldsw + _i * 8192), 16, 0, 0); } while (0)
; #define PG8_LDA(dst, b, h) do { _Pragma("unroll") for (int m = 0; m < 4; ++m) _Pragma("unroll") for (int k = 0; k < 2; ++k) dst[m][k] = *(const PG8_LAS bf16x8*)(lds + PG8_SA(b, h) + aoff + m * 2048 + k * 1024); } while (0)
; #define PG8_LDB(dst, b, h) do { _Pragma("unroll") for (int n = 0; n < 2; ++n) _Pragma("unroll") for (int k = 0; k < 2; ++k) dst[n][k] = *(const PG8_LAS bf16x8*)(lds + PG8_SB(b, h) + boff + n * 2048 + k * 1024); } while (0)
; #define PG8_WAIT_V(n) asm volatile("s_waitcnt vmcnt(" #n ")" ::: "memory")
; #define PG8_WAIT_L(n) asm volatile("s_waitcnt lgkmcnt(" #n ")" ::: "memory")
; #define PG8_BAR __builtin_amdgcn_s_barrier()
; #define PG8_SCHED __builtin_amdgcn_sched_barrier(0)
; template <class Epi, class Sched, bool ALIGN_EPI = false, bool SP2 = false, bool I8 = false>
; __device__ __forceinline__ void gemm_phase(PG8_LAS unsigned char* lds, const Gemm g, const Sched& S, const Epi& E) {
;     ...
;             PG8_WAIT_V(8); PG8_WAIT_L(0); PG8_BAR; PG8_MMA(1, 0, At, B0); PG8_MMA(1, 1, At, B1); PG8_BAR; PG8_SCHED;
;             PG8_LDB(B0, 1, 0); PG8_LDB(B1, 1, 1); PG8_SCHED; PG8_LDA(At, 1, 0); PG8_STAGE(PG8_SA(0, 1), a2 + hstep, voffA);
;             PG8_WAIT_V(8); PG8_WAIT_L(0); PG8_BAR; PG8_MMA(0, 0, At, B0); PG8_MMA(0, 1, At, B1); PG8_BAR; PG8_SCHED;
	s_setprio 1
	s_waitcnt lgkmcnt(0)
	v_mfma_f32_16x16x32_bf16 v[64:67], v[112:115], v[184:187], 0
	v_mfma_f32_16x16x32_bf16 v[60:63], v[152:155], v[184:187], 0
	v_mfma_f32_16x16x32_bf16 v[48:51], v[112:115], v[204:207], 0
	v_mfma_f32_16x16x32_bf16 v[44:47], v[152:155], v[204:207], 0
	v_mfma_f32_16x16x32_bf16 v[32:35], v[112:115], v[212:215], 0
	v_mfma_f32_16x16x32_bf16 v[28:31], v[152:155], v[212:215], 0
	v_mfma_f32_16x16x32_bf16 v[16:19], v[112:115], v[220:223], 0
	v_mfma_f32_16x16x32_bf16 v[12:15], v[152:155], v[220:223], 0
	v_mfma_f32_16x16x32_bf16 v[64:67], v[120:123], v[188:191], v[64:67]
	v_mfma_f32_16x16x32_bf16 v[60:63], v[156:159], v[188:191], v[60:63]
	v_mfma_f32_16x16x32_bf16 v[48:51], v[120:123], v[208:211], v[48:51]
	v_mfma_f32_16x16x32_bf16 v[44:47], v[156:159], v[208:211], v[44:47]
	v_mfma_f32_16x16x32_bf16 v[32:35], v[120:123], v[216:219], v[32:35]
	v_mfma_f32_16x16x32_bf16 v[28:31], v[156:159], v[216:219], v[28:31]
	v_mfma_f32_16x16x32_bf16 v[16:19], v[120:123], v[224:227], v[16:19]
	v_mfma_f32_16x16x32_bf16 v[12:15], v[156:159], v[224:227], v[12:15]
	s_setprio 0
	s_setprio 1
	v_mfma_f32_16x16x32_bf16 v[56:59], v[160:163], v[184:187], 0
	v_mfma_f32_16x16x32_bf16 v[52:55], v[176:179], v[184:187], 0
	v_mfma_f32_16x16x32_bf16 v[40:43], v[160:163], v[204:207], 0
	v_mfma_f32_16x16x32_bf16 v[36:39], v[176:179], v[204:207], 0
	v_mfma_f32_16x16x32_bf16 v[24:27], v[160:163], v[212:215], 0
	v_mfma_f32_16x16x32_bf16 v[20:23], v[176:179], v[212:215], 0
	v_mfma_f32_16x16x32_bf16 v[8:11], v[160:163], v[220:223], 0
	v_mfma_f32_16x16x32_bf16 v[4:7], v[176:179], v[220:223], 0
	v_mfma_f32_16x16x32_bf16 v[56:59], v[164:167], v[188:191], v[56:59]
	v_mfma_f32_16x16x32_bf16 v[52:55], v[180:183], v[188:191], v[52:55]
	v_mfma_f32_16x16x32_bf16 v[40:43], v[164:167], v[208:211], v[40:43]
	v_mfma_f32_16x16x32_bf16 v[36:39], v[180:183], v[208:211], v[36:39]
	v_mfma_f32_16x16x32_bf16 v[24:27], v[164:167], v[216:219], v[24:27]
	v_mfma_f32_16x16x32_bf16 v[20:23], v[180:183], v[216:219], v[20:23]
	v_mfma_f32_16x16x32_bf16 v[8:11], v[164:167], v[224:227], v[8:11]
	v_mfma_f32_16x16x32_bf16 v[4:7], v[180:183], v[224:227], v[4:7]
	s_setprio 0
	s_barrier
	s_add_i32 s56, 0, 0x18000
	s_add_i32 s57, 0, 0x1c000
	v_add_u32_e32 v156, s56, v171
	v_add_u32_e32 v175, s57, v171
	ds_read_b128 v[112:115], v156
	ds_read_b128 v[120:123], v156 offset:1024
	ds_read_b128 v[152:155], v156 offset:2048
	ds_read_b128 v[156:159], v156 offset:3072
	ds_read_b128 v[160:163], v175
	ds_read_b128 v[164:167], v175 offset:1024
	ds_read_b128 v[176:179], v175 offset:2048
	ds_read_b128 v[180:183], v175 offset:3072
	s_add_u32 s50, s76, 0x100000
	s_addc_u32 s51, s77, 0
	s_mov_b32 m0, s53
	v_lshl_add_u64 v[244:245], s[50:51], 0, v[140:141]
	ds_read_b128 v[184:187], v173 offset:32768
	ds_read_b128 v[188:191], v173 offset:33792
	ds_read_b128 v[204:207], v173 offset:34816
	ds_read_b128 v[208:211], v173 offset:35840
	ds_read_b128 v[212:215], v173 offset:36864
	ds_read_b128 v[216:219], v173 offset:37888
	ds_read_b128 v[220:223], v173 offset:38912
	ds_read_b128 v[224:227], v173 offset:39936
	global_load_lds_dwordx4 v[244:245], off
	v_lshl_add_u64 v[244:245], s[50:51], 0, v[142:143]
	s_mov_b32 m0, s64
	s_nop 0
	global_load_lds_dwordx4 v[244:245], off
	s_waitcnt vmcnt(8)
	s_waitcnt lgkmcnt(0)
	s_barrier
	s_setprio 1
	s_waitcnt lgkmcnt(0)
	v_mfma_f32_16x16x32_bf16 v[136:139], v[112:115], v[184:187], v[136:139]
	v_mfma_f32_16x16x32_bf16 v[132:135], v[152:155], v[184:187], v[132:135]
	v_mfma_f32_16x16x32_bf16 v[116:119], v[112:115], v[204:207], v[116:119]
	v_mfma_f32_16x16x32_bf16 v[108:111], v[152:155], v[204:207], v[108:111]
	v_mfma_f32_16x16x32_bf16 v[96:99], v[112:115], v[212:215], v[96:99]
	v_mfma_f32_16x16x32_bf16 v[92:95], v[152:155], v[212:215], v[92:95]
	v_mfma_f32_16x16x32_bf16 v[80:83], v[112:115], v[220:223], v[80:83]
	v_mfma_f32_16x16x32_bf16 v[76:79], v[152:155], v[220:223], v[76:79]
	v_mfma_f32_16x16x32_bf16 v[136:139], v[120:123], v[188:191], v[136:139]
	v_mfma_f32_16x16x32_bf16 v[132:135], v[156:159], v[188:191], v[132:135]
	v_mfma_f32_16x16x32_bf16 v[116:119], v[120:123], v[208:211], v[116:119]
	v_mfma_f32_16x16x32_bf16 v[108:111], v[156:159], v[208:211], v[108:111]
	v_mfma_f32_16x16x32_bf16 v[96:99], v[120:123], v[216:219], v[96:99]
	v_mfma_f32_16x16x32_bf16 v[92:95], v[156:159], v[216:219], v[92:95]
	v_mfma_f32_16x16x32_bf16 v[80:83], v[120:123], v[224:227], v[80:83]
	v_mfma_f32_16x16x32_bf16 v[76:79], v[156:159], v[224:227], v[76:79]
	s_setprio 0
	s_setprio 1
	v_mfma_f32_16x16x32_bf16 v[128:131], v[160:163], v[184:187], v[128:131]
	v_mfma_f32_16x16x32_bf16 v[124:127], v[176:179], v[184:187], v[124:127]
	v_mfma_f32_16x16x32_bf16 v[104:107], v[160:163], v[204:207], v[104:107]
	v_mfma_f32_16x16x32_bf16 v[100:103], v[176:179], v[204:207], v[100:103]
	v_mfma_f32_16x16x32_bf16 v[88:91], v[160:163], v[212:215], v[88:91]
	v_mfma_f32_16x16x32_bf16 v[84:87], v[176:179], v[212:215], v[84:87]
	v_mfma_f32_16x16x32_bf16 v[72:75], v[160:163], v[220:223], v[72:75]
	v_mfma_f32_16x16x32_bf16 v[68:71], v[176:179], v[220:223], v[68:71]
	v_mfma_f32_16x16x32_bf16 v[128:131], v[164:167], v[188:191], v[128:131]
	v_mfma_f32_16x16x32_bf16 v[124:127], v[180:183], v[188:191], v[124:127]
	v_mfma_f32_16x16x32_bf16 v[104:107], v[164:167], v[208:211], v[104:107]
	v_mfma_f32_16x16x32_bf16 v[100:103], v[180:183], v[208:211], v[100:103]
	v_mfma_f32_16x16x32_bf16 v[88:91], v[164:167], v[216:219], v[88:91]
	v_mfma_f32_16x16x32_bf16 v[84:87], v[180:183], v[216:219], v[84:87]
	v_mfma_f32_16x16x32_bf16 v[72:75], v[164:167], v[224:227], v[72:75]
	v_mfma_f32_16x16x32_bf16 v[68:71], v[180:183], v[224:227], v[68:71]
	s_setprio 0
	s_barrier
; #define PG8_STAGE(bufoff, gbase, voff) do { _Pragma("unroll") for (int _i = 0; _i < 2; ++_i) \
;         __builtin_amdgcn_global_load_lds((const unsigned*)((const char*)(gbase) + (voff)[_i]), (PG8_LAS unsigned*)(lds + (bufoff) + ldsw + _i * 8192), 16, 0, 0); } while (0)
; #define PG8_LDA(dst, b, h) do { _Pragma("unroll") for (int m = 0; m < 4; ++m) _Pragma("unroll") for (int k = 0; k < 2; ++k) dst[m][k] = *(const PG8_LAS bf16x8*)(lds + PG8_SA(b, h) + aoff + m * 2048 + k * 1024); } while (0)
; #define PG8_WAIT_V(n) asm volatile("s_waitcnt vmcnt(" #n ")" ::: "memory")
; #define PG8_WAIT_L(n) asm volatile("s_waitcnt lgkmcnt(" #n ")" ::: "memory")
; #define PG8_BAR __builtin_amdgcn_s_barrier()
; #define PG8_SCHED __builtin_amdgcn_sched_barrier(0)
; template <class Epi, class Sched, bool ALIGN_EPI = false, bool SP2 = false, bool I8 = false>
; __device__ __forceinline__ void gemm_phase(PG8_LAS unsigned char* lds, const Gemm g, const Sched& S, const Epi& E) {
;     ...
;             PG8_LDA(At, 1, 1); PG8_STAGE(PG8_SB(1, 0), b3, voffB); PG8_STAGE(PG8_SB(1, 1), b3 + hstep, voffB); PG8_STAGE(PG8_SA(1, 0), a3, voffA);
;             PG8_WAIT_V(8); PG8_WAIT_L(0); PG8_BAR; PG8_MMA(1, 0, At, B0); PG8_MMA(1, 1, At, B1); PG8_BAR; PG8_SCHED;
	s_add_i32 s50, s56, s46
	v_lshl_add_u64 v[168:169], v[168:169], 0, s[84:85]
	s_mov_b32 m0, s50
	ds_read_b128 v[184:187], v173 offset:49152
	ds_read_b128 v[188:191], v173 offset:50176
	ds_read_b128 v[204:207], v173 offset:51200
	ds_read_b128 v[208:211], v173 offset:52224
	ds_read_b128 v[212:215], v173 offset:53248
	ds_read_b128 v[216:219], v173 offset:54272
	ds_read_b128 v[220:223], v173 offset:55296
	ds_read_b128 v[224:227], v173 offset:56320
	global_load_lds_dwordx4 v[168:169], off
	s_add_i32 m0, s50, 0x2000
	s_add_u32 s50, s72, 0x100080
	v_lshl_add_u64 v[168:169], v[228:229], 0, s[84:85]
	s_addc_u32 s51, s73, 0
	s_add_i32 s56, s57, s46
	global_load_lds_dwordx4 v[168:169], off
	v_lshl_add_u64 v[168:169], s[50:51], 0, v[2:3]
	s_mov_b32 m0, s56
	s_nop 0
	global_load_lds_dwordx4 v[168:169], off
	v_lshl_add_u64 v[168:169], s[50:51], 0, v[144:145]
	s_add_i32 m0, s56, 0x2000
	s_nop 0
	global_load_lds_dwordx4 v[168:169], off
	v_lshl_add_u64 v[168:169], v[240:241], 0, s[84:85]
	s_mov_b32 m0, s28
	s_nop 0
	global_load_lds_dwordx4 v[168:169], off
	v_lshl_add_u64 v[168:169], v[242:243], 0, s[84:85]
	s_mov_b32 m0, s65
	s_nop 0
	global_load_lds_dwordx4 v[168:169], off
	s_waitcnt vmcnt(8)
	s_waitcnt lgkmcnt(0)
	s_barrier
	s_setprio 1
	s_waitcnt lgkmcnt(0)
	v_mfma_f32_16x16x32_bf16 v[64:67], v[112:115], v[184:187], v[64:67]
	v_mfma_f32_16x16x32_bf16 v[60:63], v[152:155], v[184:187], v[60:63]
	v_mfma_f32_16x16x32_bf16 v[48:51], v[112:115], v[204:207], v[48:51]
	v_mfma_f32_16x16x32_bf16 v[44:47], v[152:155], v[204:207], v[44:47]
	v_mfma_f32_16x16x32_bf16 v[32:35], v[112:115], v[212:215], v[32:35]
	v_mfma_f32_16x16x32_bf16 v[28:31], v[152:155], v[212:215], v[28:31]
	v_mfma_f32_16x16x32_bf16 v[16:19], v[112:115], v[220:223], v[16:19]
	v_mfma_f32_16x16x32_bf16 v[12:15], v[152:155], v[220:223], v[12:15]
	v_mfma_f32_16x16x32_bf16 v[64:67], v[120:123], v[188:191], v[64:67]
	v_mfma_f32_16x16x32_bf16 v[60:63], v[156:159], v[188:191], v[60:63]
	v_mfma_f32_16x16x32_bf16 v[48:51], v[120:123], v[208:211], v[48:51]
	v_mfma_f32_16x16x32_bf16 v[44:47], v[156:159], v[208:211], v[44:47]
	v_mfma_f32_16x16x32_bf16 v[32:35], v[120:123], v[216:219], v[32:35]
	v_mfma_f32_16x16x32_bf16 v[28:31], v[156:159], v[216:219], v[28:31]
	v_mfma_f32_16x16x32_bf16 v[16:19], v[120:123], v[224:227], v[16:19]
	v_mfma_f32_16x16x32_bf16 v[12:15], v[156:159], v[224:227], v[12:15]
	s_setprio 0
	s_setprio 1
	v_mfma_f32_16x16x32_bf16 v[56:59], v[160:163], v[184:187], v[56:59]
	v_mfma_f32_16x16x32_bf16 v[52:55], v[176:179], v[184:187], v[52:55]
	v_mfma_f32_16x16x32_bf16 v[40:43], v[160:163], v[204:207], v[40:43]
	v_mfma_f32_16x16x32_bf16 v[36:39], v[176:179], v[204:207], v[36:39]
	v_mfma_f32_16x16x32_bf16 v[24:27], v[160:163], v[212:215], v[24:27]
	v_mfma_f32_16x16x32_bf16 v[20:23], v[176:179], v[212:215], v[20:23]
	v_mfma_f32_16x16x32_bf16 v[8:11], v[160:163], v[220:223], v[8:11]
	v_mfma_f32_16x16x32_bf16 v[4:7], v[176:179], v[220:223], v[4:7]
	v_mfma_f32_16x16x32_bf16 v[56:59], v[164:167], v[188:191], v[56:59]
	v_mfma_f32_16x16x32_bf16 v[52:55], v[180:183], v[188:191], v[52:55]
	v_mfma_f32_16x16x32_bf16 v[40:43], v[164:167], v[208:211], v[40:43]
	v_mfma_f32_16x16x32_bf16 v[36:39], v[180:183], v[208:211], v[36:39]
	v_mfma_f32_16x16x32_bf16 v[24:27], v[164:167], v[216:219], v[24:27]
	v_mfma_f32_16x16x32_bf16 v[20:23], v[180:183], v[216:219], v[20:23]
	v_mfma_f32_16x16x32_bf16 v[8:11], v[164:167], v[224:227], v[8:11]
	v_mfma_f32_16x16x32_bf16 v[4:7], v[180:183], v[224:227], v[4:7]
	s_setprio 0
	s_barrier
	s_add_i32 s97, s97, 2
	s_add_u32 s12, s12, 0x100
	s_addc_u32 s13, s13, 0
	s_add_u32 s37, s37, 0x100
	s_addc_u32 s61, s61, 0
	s_cmp_gt_u32 s97, 61
	s_cbranch_scc1 .Lkloop_exit_1

; #define PG8_BAR __builtin_amdgcn_s_barrier()
; template <class Epi, class Sched, bool ALIGN_EPI = false, bool SP2 = false, bool I8 = false>
; __device__ __forceinline__ void gemm_phase(PG8_LAS unsigned char* lds, const Gemm g, const Sched& S, const Epi& E) {
;     ...
;         }
;         if constexpr (ALIGN_EPI) { if (wr == 0) PG8_BAR; }
;         if constexpr (!Epi::AFTER_DRAIN) { E(acc, cur, wr, wc, fr, fq); S.done(cur); }
.Lkloop_exit_1:
	s_and_b64 vcc, exec, s[24:25]
	s_cbranch_vccz .LBB0_233
	s_barrier

; #define PG8_STAGE(bufoff, gbase, voff) do { _Pragma("unroll") for (int _i = 0; _i < 2; ++_i) \
;         __builtin_amdgcn_global_load_lds((const unsigned*)((const char*)(gbase) + (voff)[_i]), (PG8_LAS unsigned*)(lds + (bufoff) + ldsw + _i * 8192), 16, 0, 0); } while (0)
; #define PG8_LDA(dst, b, h) do { _Pragma("unroll") for (int m = 0; m < 4; ++m) _Pragma("unroll") for (int k = 0; k < 2; ++k) dst[m][k] = *(const PG8_LAS bf16x8*)(lds + PG8_SA(b, h) + aoff + m * 2048 + k * 1024); } while (0)
; #define PG8_LDB(dst, b, h) do { _Pragma("unroll") for (int n = 0; n < 2; ++n) _Pragma("unroll") for (int k = 0; k < 2; ++k) dst[n][k] = *(const PG8_LAS bf16x8*)(lds + PG8_SB(b, h) + boff + n * 2048 + k * 1024); } while (0)
; #define PG8_WAIT_V(n) asm volatile("s_waitcnt vmcnt(" #n ")" ::: "memory")
; #define PG8_WAIT_L(n) asm volatile("s_waitcnt lgkmcnt(" #n ")" ::: "memory")
; #define PG8_BAR __builtin_amdgcn_s_barrier()
; #define PG8_SCHED __builtin_amdgcn_sched_barrier(0)
; template <class Epi, class Sched, bool ALIGN_EPI = false, bool SP2 = false, bool I8 = false>
; __device__ __forceinline__ void gemm_phase(PG8_LAS unsigned char* lds, const Gemm g, const Sched& S, const Epi& E) {
;     ...
;         const char* nA = has_next ? (const char*)g.A + (size_t)nxt.pm * tstep : cA; const char* nB = has_next ? (const char*)g.Bt + (size_t)nxt.pn * tstep : cB;
;         for (int t = 0; t < nt; t += 2) {
;             const bool last = (t == nt - 2);
;             const char* a1 = cA + (size_t)(t + 1) * kstep;
;             const char* a2 = last ? nA : cA + (size_t)(t + 2) * kstep; const char* b2 = last ? nB : cB + (size_t)(t + 2) * kstep;
;             const char* a3 = a2 + kstep; const char* b3 = b2 + kstep;
;             if (last && has_next) S.a_ready(nxt);
;             if constexpr (SP2) {
;             PG8_LDB(B0, 0, 0); PG8_LDB(B1, 0, 1); PG8_SCHED; PG8_LDA(At, 0, 0); PG8_STAGE(PG8_SA(1, 1), a1 + hstep, voffA);
;             PG8_WAIT_V(8); PG8_WAIT_L(0); PG8_BAR; PG8_MMA(0, 0, At, B0); PG8_MMA(0, 1, At, B1); PG8_BAR; PG8_SCHED;
;             PG8_LDA(At, 0, 1); PG8_STAGE(PG8_SB(0, 0), b2, voffB); PG8_STAGE(PG8_SB(0, 1), b2 + hstep, voffB); PG8_STAGE(PG8_SA(0, 0), a2, voffA);
;             PG8_WAIT_V(8); PG8_WAIT_L(0); PG8_BAR; PG8_MMA(1, 0, At, B0); PG8_MMA(1, 1, At, B1); PG8_BAR; PG8_SCHED;
.LBB0_1455:
	s_ashr_i32 s17, s16, 31
	s_lshl_b64 s[20:21], s[16:17], 21
	s_add_u32 s20, s28, s20
	s_addc_u32 s21, s34, s21
	s_and_b64 s[22:23], s[8:9], exec
	s_cselect_b32 s17, s21, s25
	s_cselect_b32 s51, s20, s24
	s_ashr_i32 s19, s18, 31
	s_lshl_b64 s[22:23], s[18:19], 21
	s_add_u32 s22, s35, s22
	s_addc_u32 s23, s39, s23
	s_and_b64 s[36:37], s[8:9], exec
	s_cselect_b32 s19, s23, s27
	s_cselect_b32 s52, s22, s26
	s_add_u32 s24, s24, 0x100080
	s_addc_u32 s25, s25, 0
	s_add_u32 s53, s26, 0x100
	s_addc_u32 s54, s27, 0
	s_mov_b32 s55, -2
	s_waitcnt vmcnt(0)
	s_add_u32 s26, s24, 0xfff00080
	s_addc_u32 s27, s25, -1
	s_add_i32 s56, 0, 0x10000
	s_cmp_eq_u32 s55, 60
	s_cselect_b32 s37, s17, s27
	s_cselect_b32 s36, s51, s26
	s_cselect_b32 s27, s19, s54
	s_cselect_b32 s26, s52, s53
	s_add_i32 s58, 0, 0x14000
	v_add_u32_e32 v144, s56, v240
	v_add_u32_e32 v160, s58, v240
	ds_read_b128 v[124:127], v144
	ds_read_b128 v[128:131], v144 offset:1024
	ds_read_b128 v[132:135], v144 offset:2048
	ds_read_b128 v[144:147], v144 offset:3072
	ds_read_b128 v[148:151], v160
	ds_read_b128 v[152:155], v160 offset:1024
	ds_read_b128 v[156:159], v160 offset:2048
	ds_read_b128 v[160:163], v160 offset:3072
	v_lshl_add_u64 v[218:219], s[24:25], 0, v[210:211]
	s_add_i32 m0, s41, 0xc000
	ds_read_b128 v[164:167], v242
	ds_read_b128 v[168:171], v242 offset:1024
	ds_read_b128 v[172:175], v242 offset:2048
	ds_read_b128 v[176:179], v242 offset:3072
	ds_read_b128 v[180:183], v242 offset:4096
	ds_read_b128 v[184:187], v242 offset:5120
	ds_read_b128 v[188:191], v242 offset:6144
	ds_read_b128 v[214:217], v242 offset:7168
	global_load_lds_dwordx4 v[218:219], off
	v_lshl_add_u64 v[218:219], s[24:25], 0, v[212:213]
	s_add_i32 m0, s41, 0xe000
	s_nop 0
	global_load_lds_dwordx4 v[218:219], off
	s_waitcnt vmcnt(8)
	s_waitcnt lgkmcnt(0)
	s_barrier
	s_setprio 1
	s_waitcnt lgkmcnt(0)
	v_mfma_f32_16x16x32_bf16 v[140:143], v[124:127], v[164:167], 0
	v_mfma_f32_16x16x32_bf16 v[136:139], v[132:135], v[164:167], 0
	v_mfma_f32_16x16x32_bf16 v[112:115], v[124:127], v[172:175], 0
	v_mfma_f32_16x16x32_bf16 v[108:111], v[132:135], v[172:175], 0
	v_mfma_f32_16x16x32_bf16 v[96:99], v[124:127], v[180:183], 0
	v_mfma_f32_16x16x32_bf16 v[92:95], v[132:135], v[180:183], 0
	v_mfma_f32_16x16x32_bf16 v[80:83], v[124:127], v[188:191], 0
	v_mfma_f32_16x16x32_bf16 v[76:79], v[132:135], v[188:191], 0
	v_mfma_f32_16x16x32_bf16 v[140:143], v[128:131], v[168:171], v[140:143]
	v_mfma_f32_16x16x32_bf16 v[136:139], v[144:147], v[168:171], v[136:139]
	v_mfma_f32_16x16x32_bf16 v[112:115], v[128:131], v[176:179], v[112:115]
	v_mfma_f32_16x16x32_bf16 v[108:111], v[144:147], v[176:179], v[108:111]
	v_mfma_f32_16x16x32_bf16 v[96:99], v[128:131], v[184:187], v[96:99]
	v_mfma_f32_16x16x32_bf16 v[92:95], v[144:147], v[184:187], v[92:95]
	v_mfma_f32_16x16x32_bf16 v[80:83], v[128:131], v[214:217], v[80:83]
	v_mfma_f32_16x16x32_bf16 v[76:79], v[144:147], v[214:217], v[76:79]
	s_setprio 0
	s_setprio 1
	v_mfma_f32_16x16x32_bf16 v[120:123], v[148:151], v[164:167], 0
	v_mfma_f32_16x16x32_bf16 v[116:119], v[156:159], v[164:167], 0
	v_mfma_f32_16x16x32_bf16 v[104:107], v[148:151], v[172:175], 0
	v_mfma_f32_16x16x32_bf16 v[100:103], v[156:159], v[172:175], 0
	v_mfma_f32_16x16x32_bf16 v[88:91], v[148:151], v[180:183], 0
	v_mfma_f32_16x16x32_bf16 v[84:87], v[156:159], v[180:183], 0
	v_mfma_f32_16x16x32_bf16 v[72:75], v[148:151], v[188:191], 0
	v_mfma_f32_16x16x32_bf16 v[68:71], v[156:159], v[188:191], 0
	v_mfma_f32_16x16x32_bf16 v[120:123], v[152:155], v[168:171], v[120:123]
	v_mfma_f32_16x16x32_bf16 v[116:119], v[160:163], v[168:171], v[116:119]
	v_mfma_f32_16x16x32_bf16 v[104:107], v[152:155], v[176:179], v[104:107]
	v_mfma_f32_16x16x32_bf16 v[100:103], v[160:163], v[176:179], v[100:103]
	v_mfma_f32_16x16x32_bf16 v[88:91], v[152:155], v[184:187], v[88:91]
	v_mfma_f32_16x16x32_bf16 v[84:87], v[160:163], v[184:187], v[84:87]
	v_mfma_f32_16x16x32_bf16 v[72:75], v[152:155], v[214:217], v[72:75]
	v_mfma_f32_16x16x32_bf16 v[68:71], v[160:163], v[214:217], v[68:71]
	s_setprio 0
	s_barrier
	s_add_i32 s56, s56, s40
	v_lshl_add_u64 v[218:219], s[26:27], 0, v[2:3]
	s_mov_b32 m0, s56
	ds_read_b128 v[164:167], v242 offset:16384
	ds_read_b128 v[168:171], v242 offset:17408
	ds_read_b128 v[172:175], v242 offset:18432
	ds_read_b128 v[176:179], v242 offset:19456
	ds_read_b128 v[180:183], v242 offset:20480
	ds_read_b128 v[184:187], v242 offset:21504
	ds_read_b128 v[188:191], v242 offset:22528
	ds_read_b128 v[214:217], v242 offset:23552
	global_load_lds_dwordx4 v[218:219], off
	s_add_i32 m0, s56, 0x2000
	s_add_u32 s56, s26, 0x100000
	v_lshl_add_u64 v[220:221], s[26:27], 0, v[204:205]
	s_addc_u32 s57, s27, 0
	s_add_i32 s58, s58, s40
	global_load_lds_dwordx4 v[220:221], off
	v_lshl_add_u64 v[222:223], s[56:57], 0, v[2:3]
	s_mov_b32 m0, s58
	v_lshl_add_u64 v[224:225], s[36:37], 0, v[206:207]
	global_load_lds_dwordx4 v[222:223], off
	v_lshl_add_u64 v[222:223], s[56:57], 0, v[204:205]
	s_add_i32 m0, s58, 0x2000
	s_nop 0
	global_load_lds_dwordx4 v[222:223], off
	v_lshl_add_u64 v[222:223], s[36:37], 0, v[208:209]
	s_mov_b32 m0, s41
	s_nop 0
	global_load_lds_dwordx4 v[222:223], off
	s_mov_b32 m0, s42
	s_nop 0
	global_load_lds_dwordx4 v[224:225], off
	s_waitcnt vmcnt(8)
	s_waitcnt lgkmcnt(0)
	s_barrier
; #define PG8_STAGE(bufoff, gbase, voff) do { _Pragma("unroll") for (int _i = 0; _i < 2; ++_i) \
;         __builtin_amdgcn_global_load_lds((const unsigned*)((const char*)(gbase) + (voff)[_i]), (PG8_LAS unsigned*)(lds + (bufoff) + ldsw + _i * 8192), 16, 0, 0); } while (0)
; #define PG8_LDA(dst, b, h) do { _Pragma("unroll") for (int m = 0; m < 4; ++m) _Pragma("unroll") for (int k = 0; k < 2; ++k) dst[m][k] = *(const PG8_LAS bf16x8*)(lds + PG8_SA(b, h) + aoff + m * 2048 + k * 1024); } while (0)
; #define PG8_LDB(dst, b, h) do { _Pragma("unroll") for (int n = 0; n < 2; ++n) _Pragma("unroll") for (int k = 0; k < 2; ++k) dst[n][k] = *(const PG8_LAS bf16x8*)(lds + PG8_SB(b, h) + boff + n * 2048 + k * 1024); } while (0)
; #define PG8_WAIT_V(n) asm volatile("s_waitcnt vmcnt(" #n ")" ::: "memory")
; #define PG8_WAIT_L(n) asm volatile("s_waitcnt lgkmcnt(" #n ")" ::: "memory")
; #define PG8_BAR __builtin_amdgcn_s_barrier()
; #define PG8_SCHED __builtin_amdgcn_sched_barrier(0)
; template <class Epi, class Sched, bool ALIGN_EPI = false, bool SP2 = false, bool I8 = false>
; __device__ __forceinline__ void gemm_phase(PG8_LAS unsigned char* lds, const Gemm g, const Sched& S, const Epi& E) {
;     ...
;             PG8_WAIT_V(8); PG8_WAIT_L(0); PG8_BAR; PG8_MMA(1, 0, At, B0); PG8_MMA(1, 1, At, B1); PG8_BAR; PG8_SCHED;
;             PG8_LDB(B0, 1, 0); PG8_LDB(B1, 1, 1); PG8_SCHED; PG8_LDA(At, 1, 0); PG8_STAGE(PG8_SA(0, 1), a2 + hstep, voffA);
;             PG8_WAIT_V(8); PG8_WAIT_L(0); PG8_BAR; PG8_MMA(0, 0, At, B0); PG8_MMA(0, 1, At, B1); PG8_BAR; PG8_SCHED;
	s_setprio 1
	s_waitcnt lgkmcnt(0)
	v_mfma_f32_16x16x32_bf16 v[64:67], v[124:127], v[164:167], 0
	v_mfma_f32_16x16x32_bf16 v[60:63], v[132:135], v[164:167], 0
	v_mfma_f32_16x16x32_bf16 v[48:51], v[124:127], v[172:175], 0
	v_mfma_f32_16x16x32_bf16 v[44:47], v[132:135], v[172:175], 0
	v_mfma_f32_16x16x32_bf16 v[32:35], v[124:127], v[180:183], 0
	v_mfma_f32_16x16x32_bf16 v[28:31], v[132:135], v[180:183], 0
	v_mfma_f32_16x16x32_bf16 v[16:19], v[124:127], v[188:191], 0
	v_mfma_f32_16x16x32_bf16 v[12:15], v[132:135], v[188:191], 0
	v_mfma_f32_16x16x32_bf16 v[64:67], v[128:131], v[168:171], v[64:67]
	v_mfma_f32_16x16x32_bf16 v[60:63], v[144:147], v[168:171], v[60:63]
	v_mfma_f32_16x16x32_bf16 v[48:51], v[128:131], v[176:179], v[48:51]
	v_mfma_f32_16x16x32_bf16 v[44:47], v[144:147], v[176:179], v[44:47]
	v_mfma_f32_16x16x32_bf16 v[32:35], v[128:131], v[184:187], v[32:35]
	v_mfma_f32_16x16x32_bf16 v[28:31], v[144:147], v[184:187], v[28:31]
	v_mfma_f32_16x16x32_bf16 v[16:19], v[128:131], v[214:217], v[16:19]
	v_mfma_f32_16x16x32_bf16 v[12:15], v[144:147], v[214:217], v[12:15]
	s_setprio 0
	s_setprio 1
	v_mfma_f32_16x16x32_bf16 v[56:59], v[148:151], v[164:167], 0
	v_mfma_f32_16x16x32_bf16 v[52:55], v[156:159], v[164:167], 0
	v_mfma_f32_16x16x32_bf16 v[40:43], v[148:151], v[172:175], 0
	v_mfma_f32_16x16x32_bf16 v[36:39], v[156:159], v[172:175], 0
	v_mfma_f32_16x16x32_bf16 v[24:27], v[148:151], v[180:183], 0
	v_mfma_f32_16x16x32_bf16 v[20:23], v[156:159], v[180:183], 0
	v_mfma_f32_16x16x32_bf16 v[8:11], v[148:151], v[188:191], 0
	v_mfma_f32_16x16x32_bf16 v[4:7], v[156:159], v[188:191], 0
	v_mfma_f32_16x16x32_bf16 v[56:59], v[152:155], v[168:171], v[56:59]
	v_mfma_f32_16x16x32_bf16 v[52:55], v[160:163], v[168:171], v[52:55]
	v_mfma_f32_16x16x32_bf16 v[40:43], v[152:155], v[176:179], v[40:43]
	v_mfma_f32_16x16x32_bf16 v[36:39], v[160:163], v[176:179], v[36:39]
	v_mfma_f32_16x16x32_bf16 v[24:27], v[152:155], v[184:187], v[24:27]
	v_mfma_f32_16x16x32_bf16 v[20:23], v[160:163], v[184:187], v[20:23]
	v_mfma_f32_16x16x32_bf16 v[8:11], v[152:155], v[214:217], v[8:11]
	v_mfma_f32_16x16x32_bf16 v[4:7], v[160:163], v[214:217], v[4:7]
	s_setprio 0
	s_barrier
	s_add_i32 s56, 0, 0x18000
	s_add_i32 s57, 0, 0x1c000
	v_add_u32_e32 v144, s56, v240
	v_add_u32_e32 v160, s57, v240
	ds_read_b128 v[124:127], v144
	ds_read_b128 v[128:131], v144 offset:1024
	ds_read_b128 v[132:135], v144 offset:2048
	ds_read_b128 v[144:147], v144 offset:3072
	ds_read_b128 v[148:151], v160
	ds_read_b128 v[152:155], v160 offset:1024
	ds_read_b128 v[156:159], v160 offset:2048
	ds_read_b128 v[160:163], v160 offset:3072
	s_add_u32 s36, s36, 0x100000
	s_addc_u32 s37, s37, 0
	s_mov_b32 m0, s43
	v_lshl_add_u64 v[226:227], s[36:37], 0, v[208:209]
	ds_read_b128 v[164:167], v242 offset:32768
	ds_read_b128 v[168:171], v242 offset:33792
	ds_read_b128 v[172:175], v242 offset:34816
	ds_read_b128 v[176:179], v242 offset:35840
	ds_read_b128 v[180:183], v242 offset:36864
	ds_read_b128 v[184:187], v242 offset:37888
	ds_read_b128 v[188:191], v242 offset:38912
	ds_read_b128 v[214:217], v242 offset:39936
	global_load_lds_dwordx4 v[226:227], off
	v_lshl_add_u64 v[226:227], s[36:37], 0, v[206:207]
	s_mov_b32 m0, s44
	s_nop 0
	global_load_lds_dwordx4 v[226:227], off
	s_waitcnt vmcnt(8)
	s_waitcnt lgkmcnt(0)
	s_barrier
	s_setprio 1
	s_waitcnt lgkmcnt(0)
	v_mfma_f32_16x16x32_bf16 v[140:143], v[124:127], v[164:167], v[140:143]
	v_mfma_f32_16x16x32_bf16 v[136:139], v[132:135], v[164:167], v[136:139]
	v_mfma_f32_16x16x32_bf16 v[112:115], v[124:127], v[172:175], v[112:115]
	v_mfma_f32_16x16x32_bf16 v[108:111], v[132:135], v[172:175], v[108:111]
	v_mfma_f32_16x16x32_bf16 v[96:99], v[124:127], v[180:183], v[96:99]
	v_mfma_f32_16x16x32_bf16 v[92:95], v[132:135], v[180:183], v[92:95]
	v_mfma_f32_16x16x32_bf16 v[80:83], v[124:127], v[188:191], v[80:83]
	v_mfma_f32_16x16x32_bf16 v[76:79], v[132:135], v[188:191], v[76:79]
	v_mfma_f32_16x16x32_bf16 v[140:143], v[128:131], v[168:171], v[140:143]
	v_mfma_f32_16x16x32_bf16 v[136:139], v[144:147], v[168:171], v[136:139]
	v_mfma_f32_16x16x32_bf16 v[112:115], v[128:131], v[176:179], v[112:115]
	v_mfma_f32_16x16x32_bf16 v[108:111], v[144:147], v[176:179], v[108:111]
	v_mfma_f32_16x16x32_bf16 v[96:99], v[128:131], v[184:187], v[96:99]
	v_mfma_f32_16x16x32_bf16 v[92:95], v[144:147], v[184:187], v[92:95]
	v_mfma_f32_16x16x32_bf16 v[80:83], v[128:131], v[214:217], v[80:83]
	v_mfma_f32_16x16x32_bf16 v[76:79], v[144:147], v[214:217], v[76:79]
	s_setprio 0
	s_setprio 1
	v_mfma_f32_16x16x32_bf16 v[120:123], v[148:151], v[164:167], v[120:123]
	v_mfma_f32_16x16x32_bf16 v[116:119], v[156:159], v[164:167], v[116:119]
	v_mfma_f32_16x16x32_bf16 v[104:107], v[148:151], v[172:175], v[104:107]
	v_mfma_f32_16x16x32_bf16 v[100:103], v[156:159], v[172:175], v[100:103]
	v_mfma_f32_16x16x32_bf16 v[88:91], v[148:151], v[180:183], v[88:91]
	v_mfma_f32_16x16x32_bf16 v[84:87], v[156:159], v[180:183], v[84:87]
	v_mfma_f32_16x16x32_bf16 v[72:75], v[148:151], v[188:191], v[72:75]
	v_mfma_f32_16x16x32_bf16 v[68:71], v[156:159], v[188:191], v[68:71]
	v_mfma_f32_16x16x32_bf16 v[120:123], v[152:155], v[168:171], v[120:123]
	v_mfma_f32_16x16x32_bf16 v[116:119], v[160:163], v[168:171], v[116:119]
	v_mfma_f32_16x16x32_bf16 v[104:107], v[152:155], v[176:179], v[104:107]
	v_mfma_f32_16x16x32_bf16 v[100:103], v[160:163], v[176:179], v[100:103]
	v_mfma_f32_16x16x32_bf16 v[88:91], v[152:155], v[184:187], v[88:91]
	v_mfma_f32_16x16x32_bf16 v[84:87], v[160:163], v[184:187], v[84:87]
	v_mfma_f32_16x16x32_bf16 v[72:75], v[152:155], v[214:217], v[72:75]
	v_mfma_f32_16x16x32_bf16 v[68:71], v[160:163], v[214:217], v[68:71]
	s_setprio 0
	s_barrier
; #define PG8_STAGE(bufoff, gbase, voff) do { _Pragma("unroll") for (int _i = 0; _i < 2; ++_i) \
;         __builtin_amdgcn_global_load_lds((const unsigned*)((const char*)(gbase) + (voff)[_i]), (PG8_LAS unsigned*)(lds + (bufoff) + ldsw + _i * 8192), 16, 0, 0); } while (0)
; #define PG8_LDA(dst, b, h) do { _Pragma("unroll") for (int m = 0; m < 4; ++m) _Pragma("unroll") for (int k = 0; k < 2; ++k) dst[m][k] = *(const PG8_LAS bf16x8*)(lds + PG8_SA(b, h) + aoff + m * 2048 + k * 1024); } while (0)
; #define PG8_WAIT_V(n) asm volatile("s_waitcnt vmcnt(" #n ")" ::: "memory")
; #define PG8_WAIT_L(n) asm volatile("s_waitcnt lgkmcnt(" #n ")" ::: "memory")
; #define PG8_BAR __builtin_amdgcn_s_barrier()
; #define PG8_SCHED __builtin_amdgcn_sched_barrier(0)
; template <class Epi, class Sched, bool ALIGN_EPI = false, bool SP2 = false, bool I8 = false>
; __device__ __forceinline__ void gemm_phase(PG8_LAS unsigned char* lds, const Gemm g, const Sched& S, const Epi& E) {
;     ...
;             PG8_LDA(At, 1, 1); PG8_STAGE(PG8_SB(1, 0), b3, voffB); PG8_STAGE(PG8_SB(1, 1), b3 + hstep, voffB); PG8_STAGE(PG8_SA(1, 0), a3, voffA);
;             PG8_WAIT_V(8); PG8_WAIT_L(0); PG8_BAR; PG8_MMA(1, 0, At, B0); PG8_MMA(1, 1, At, B1); PG8_BAR; PG8_SCHED;
	s_add_i32 s36, s56, s40
	v_lshl_add_u64 v[218:219], v[218:219], 0, s[84:85]
	s_mov_b32 m0, s36
	ds_read_b128 v[164:167], v242 offset:49152
	ds_read_b128 v[168:171], v242 offset:50176
	ds_read_b128 v[172:175], v242 offset:51200
	ds_read_b128 v[176:179], v242 offset:52224
	ds_read_b128 v[180:183], v242 offset:53248
	ds_read_b128 v[184:187], v242 offset:54272
	ds_read_b128 v[188:191], v242 offset:55296
	ds_read_b128 v[214:217], v242 offset:56320
	global_load_lds_dwordx4 v[218:219], off
	s_add_i32 m0, s36, 0x2000
	s_add_u32 s26, s26, 0x100080
	v_lshl_add_u64 v[218:219], v[220:221], 0, s[84:85]
	s_addc_u32 s27, s27, 0
	s_add_i32 s36, s57, s40
	global_load_lds_dwordx4 v[218:219], off
	v_lshl_add_u64 v[218:219], s[26:27], 0, v[2:3]
	s_mov_b32 m0, s36
	s_nop 0
	global_load_lds_dwordx4 v[218:219], off
	v_lshl_add_u64 v[218:219], s[26:27], 0, v[204:205]
	s_add_i32 m0, s36, 0x2000
	s_nop 0
	global_load_lds_dwordx4 v[218:219], off
	v_lshl_add_u64 v[218:219], v[222:223], 0, s[84:85]
	s_mov_b32 m0, s45
	s_nop 0
	global_load_lds_dwordx4 v[218:219], off
	v_lshl_add_u64 v[218:219], v[224:225], 0, s[84:85]
	s_mov_b32 m0, s46
	s_nop 0
	global_load_lds_dwordx4 v[218:219], off
	s_waitcnt vmcnt(8)
	s_waitcnt lgkmcnt(0)
	s_barrier
	s_setprio 1
	s_waitcnt lgkmcnt(0)
	v_mfma_f32_16x16x32_bf16 v[64:67], v[124:127], v[164:167], v[64:67]
	v_mfma_f32_16x16x32_bf16 v[60:63], v[132:135], v[164:167], v[60:63]
	v_mfma_f32_16x16x32_bf16 v[48:51], v[124:127], v[172:175], v[48:51]
	v_mfma_f32_16x16x32_bf16 v[44:47], v[132:135], v[172:175], v[44:47]
	v_mfma_f32_16x16x32_bf16 v[32:35], v[124:127], v[180:183], v[32:35]
	v_mfma_f32_16x16x32_bf16 v[28:31], v[132:135], v[180:183], v[28:31]
	v_mfma_f32_16x16x32_bf16 v[16:19], v[124:127], v[188:191], v[16:19]
	v_mfma_f32_16x16x32_bf16 v[12:15], v[132:135], v[188:191], v[12:15]
	v_mfma_f32_16x16x32_bf16 v[64:67], v[128:131], v[168:171], v[64:67]
	v_mfma_f32_16x16x32_bf16 v[60:63], v[144:147], v[168:171], v[60:63]
	v_mfma_f32_16x16x32_bf16 v[48:51], v[128:131], v[176:179], v[48:51]
	v_mfma_f32_16x16x32_bf16 v[44:47], v[144:147], v[176:179], v[44:47]
	v_mfma_f32_16x16x32_bf16 v[32:35], v[128:131], v[184:187], v[32:35]
	v_mfma_f32_16x16x32_bf16 v[28:31], v[144:147], v[184:187], v[28:31]
	v_mfma_f32_16x16x32_bf16 v[16:19], v[128:131], v[214:217], v[16:19]
	v_mfma_f32_16x16x32_bf16 v[12:15], v[144:147], v[214:217], v[12:15]
	s_setprio 0
	s_setprio 1
	v_mfma_f32_16x16x32_bf16 v[56:59], v[148:151], v[164:167], v[56:59]
	v_mfma_f32_16x16x32_bf16 v[52:55], v[156:159], v[164:167], v[52:55]
	v_mfma_f32_16x16x32_bf16 v[40:43], v[148:151], v[172:175], v[40:43]
	v_mfma_f32_16x16x32_bf16 v[36:39], v[156:159], v[172:175], v[36:39]
	v_mfma_f32_16x16x32_bf16 v[24:27], v[148:151], v[180:183], v[24:27]
	v_mfma_f32_16x16x32_bf16 v[20:23], v[156:159], v[180:183], v[20:23]
	v_mfma_f32_16x16x32_bf16 v[8:11], v[148:151], v[188:191], v[8:11]
	v_mfma_f32_16x16x32_bf16 v[4:7], v[156:159], v[188:191], v[4:7]
	v_mfma_f32_16x16x32_bf16 v[56:59], v[152:155], v[168:171], v[56:59]
	v_mfma_f32_16x16x32_bf16 v[52:55], v[160:163], v[168:171], v[52:55]
	v_mfma_f32_16x16x32_bf16 v[40:43], v[152:155], v[176:179], v[40:43]
	v_mfma_f32_16x16x32_bf16 v[36:39], v[160:163], v[176:179], v[36:39]
	v_mfma_f32_16x16x32_bf16 v[24:27], v[152:155], v[184:187], v[24:27]
	v_mfma_f32_16x16x32_bf16 v[20:23], v[160:163], v[184:187], v[20:23]
	v_mfma_f32_16x16x32_bf16 v[8:11], v[152:155], v[214:217], v[8:11]
	v_mfma_f32_16x16x32_bf16 v[4:7], v[160:163], v[214:217], v[4:7]
	s_setprio 0
	s_barrier
	s_add_i32 s55, s55, 2
	s_add_u32 s24, s24, 0x100
	s_addc_u32 s25, s25, 0
	s_add_u32 s53, s53, 0x100
	s_addc_u32 s54, s54, 0
	s_cmp_gt_u32 s55, 61
	s_cbranch_scc1 .Lkloop_exit_2

; #define PG8_STAGE(bufoff, gbase, voff) do { _Pragma("unroll") for (int _i = 0; _i < 2; ++_i) \
;         __builtin_amdgcn_global_load_lds((const unsigned*)((const char*)(gbase) + (voff)[_i]), (PG8_LAS unsigned*)(lds + (bufoff) + ldsw + _i * 8192), 16, 0, 0); } while (0)
; #define PG8_LDA(dst, b, h) do { _Pragma("unroll") for (int m = 0; m < 4; ++m) _Pragma("unroll") for (int k = 0; k < 2; ++k) dst[m][k] = *(const PG8_LAS bf16x8*)(lds + PG8_SA(b, h) + aoff + m * 2048 + k * 1024); } while (0)
; #define PG8_LDB(dst, b, h) do { _Pragma("unroll") for (int n = 0; n < 2; ++n) _Pragma("unroll") for (int k = 0; k < 2; ++k) dst[n][k] = *(const PG8_LAS bf16x8*)(lds + PG8_SB(b, h) + boff + n * 2048 + k * 1024); } while (0)
; #define PG8_WAIT_V(n) asm volatile("s_waitcnt vmcnt(" #n ")" ::: "memory")
; #define PG8_WAIT_L(n) asm volatile("s_waitcnt lgkmcnt(" #n ")" ::: "memory")
; #define PG8_BAR __builtin_amdgcn_s_barrier()
; #define PG8_SCHED __builtin_amdgcn_sched_barrier(0)
; template <class Epi, class Sched, bool ALIGN_EPI = false, bool SP2 = false, bool I8 = false>
; __device__ __forceinline__ void gemm_phase(PG8_LAS unsigned char* lds, const Gemm g, const Sched& S, const Epi& E) {
;     ...
;         const char* nA = has_next ? (const char*)g.A + (size_t)nxt.pm * tstep : cA; const char* nB = has_next ? (const char*)g.Bt + (size_t)nxt.pn * tstep : cB;
;         for (int t = 0; t < nt; t += 2) {
;             const bool last = (t == nt - 2);
;             const char* a1 = cA + (size_t)(t + 1) * kstep;
;             const char* a2 = last ? nA : cA + (size_t)(t + 2) * kstep; const char* b2 = last ? nB : cB + (size_t)(t + 2) * kstep;
;             const char* a3 = a2 + kstep; const char* b3 = b2 + kstep;
;             if (last && has_next) S.a_ready(nxt);
;             if constexpr (SP2) {
;             PG8_LDB(B0, 0, 0); PG8_LDB(B1, 0, 1); PG8_SCHED; PG8_LDA(At, 0, 0); PG8_STAGE(PG8_SA(1, 1), a1 + hstep, voffA);
;             PG8_WAIT_V(8); PG8_WAIT_L(0); PG8_BAR; PG8_MMA(0, 0, At, B0); PG8_MMA(0, 1, At, B1); PG8_BAR; PG8_SCHED;
;             PG8_LDA(At, 0, 1); PG8_STAGE(PG8_SB(0, 0), b2, voffB); PG8_STAGE(PG8_SB(0, 1), b2 + hstep, voffB); PG8_STAGE(PG8_SA(0, 0), a2, voffA);
;             PG8_WAIT_V(8); PG8_WAIT_L(0); PG8_BAR; PG8_MMA(1, 0, At, B0); PG8_MMA(1, 1, At, B1); PG8_BAR; PG8_SCHED;
.LBB0_1590:
	s_ashr_i32 s25, s24, 31
	s_lshl_b64 s[26:27], s[24:25], 20
	s_add_u32 s26, s28, s26
	s_addc_u32 s27, s42, s27
	s_and_b64 s[36:37], s[10:11], exec
	s_cselect_b32 s25, s27, s41
	s_cselect_b32 s57, s26, s40
	s_ashr_i32 s23, s22, 31
	s_lshl_b64 s[36:37], s[22:23], 20
	s_add_u32 s36, s43, s36
	s_addc_u32 s37, s46, s37
	s_and_b64 s[48:49], s[10:11], exec
	s_cselect_b32 s23, s37, s45
	s_cselect_b32 s58, s36, s44
	s_add_u32 s40, s40, 0x80080
	s_addc_u32 s41, s41, 0
	s_add_u32 s59, s44, 0x100
	s_addc_u32 s60, s45, 0
	s_mov_b32 s61, -2
	s_add_u32 s44, s40, 0xfff80080
	s_addc_u32 s45, s41, -1
	s_add_i32 s64, 0, 0x10000
	s_cmp_eq_u32 s61, 28
	s_cselect_b32 s49, s25, s45
	s_cselect_b32 s48, s57, s44
	s_cselect_b32 s45, s23, s60
	s_cselect_b32 s44, s58, s59
	s_add_i32 s67, 0, 0x14000
	v_add_u32_e32 v144, s64, v167
	v_add_u32_e32 v158, s67, v167
	ds_read_b128 v[36:39], v144
	ds_read_b128 v[44:47], v144 offset:1024
	ds_read_b128 v[140:143], v144 offset:2048
	ds_read_b128 v[144:147], v144 offset:3072
	ds_read_b128 v[160:163], v158
	ds_read_b128 v[172:175], v158 offset:1024
	ds_read_b128 v[176:179], v158 offset:2048
	ds_read_b128 v[180:183], v158 offset:3072
	v_lshl_add_u64 v[164:165], s[40:41], 0, v[154:155]
	s_add_i32 m0, s50, 0xc000
	ds_read_b128 v[184:187], v171
	ds_read_b128 v[188:191], v171 offset:1024
	ds_read_b128 v[204:207], v171 offset:2048
	ds_read_b128 v[208:211], v171 offset:3072
	ds_read_b128 v[212:215], v171 offset:4096
	ds_read_b128 v[216:219], v171 offset:5120
	ds_read_b128 v[220:223], v171 offset:6144
	ds_read_b128 v[224:227], v171 offset:7168
	global_load_lds_dwordx4 v[164:165], off
	v_lshl_add_u64 v[164:165], s[40:41], 0, v[156:157]
	s_add_i32 m0, s50, 0xe000
	s_nop 0
	global_load_lds_dwordx4 v[164:165], off
	s_waitcnt vmcnt(8)
	s_waitcnt lgkmcnt(0)
	s_barrier
	s_setprio 1
	s_waitcnt lgkmcnt(0)
	v_mfma_i32_16x16x64_i8 v[136:139], v[36:39], v[184:187], 0
	v_mfma_i32_16x16x64_i8 v[128:131], v[140:143], v[184:187], 0
	v_mfma_i32_16x16x64_i8 v[120:123], v[36:39], v[204:207], 0
	v_mfma_i32_16x16x64_i8 v[112:115], v[140:143], v[204:207], 0
	v_mfma_i32_16x16x64_i8 v[104:107], v[36:39], v[212:215], 0
	v_mfma_i32_16x16x64_i8 v[96:99], v[140:143], v[212:215], 0
	v_mfma_i32_16x16x64_i8 v[88:91], v[36:39], v[220:223], 0
	v_mfma_i32_16x16x64_i8 v[80:83], v[140:143], v[220:223], 0
	v_mfma_i32_16x16x64_i8 v[136:139], v[44:47], v[188:191], v[136:139]
	v_mfma_i32_16x16x64_i8 v[128:131], v[144:147], v[188:191], v[128:131]
	v_mfma_i32_16x16x64_i8 v[120:123], v[44:47], v[208:211], v[120:123]
	v_mfma_i32_16x16x64_i8 v[112:115], v[144:147], v[208:211], v[112:115]
	v_mfma_i32_16x16x64_i8 v[104:107], v[44:47], v[216:219], v[104:107]
	v_mfma_i32_16x16x64_i8 v[96:99], v[144:147], v[216:219], v[96:99]
	v_mfma_i32_16x16x64_i8 v[88:91], v[44:47], v[224:227], v[88:91]
	v_mfma_i32_16x16x64_i8 v[80:83], v[144:147], v[224:227], v[80:83]
	s_setprio 0
	s_setprio 1
	v_mfma_i32_16x16x64_i8 v[132:135], v[160:163], v[184:187], 0
	v_mfma_i32_16x16x64_i8 v[124:127], v[176:179], v[184:187], 0
	v_mfma_i32_16x16x64_i8 v[116:119], v[160:163], v[204:207], 0
	v_mfma_i32_16x16x64_i8 v[108:111], v[176:179], v[204:207], 0
	v_mfma_i32_16x16x64_i8 v[100:103], v[160:163], v[212:215], 0
	v_mfma_i32_16x16x64_i8 v[92:95], v[176:179], v[212:215], 0
	v_mfma_i32_16x16x64_i8 v[84:87], v[160:163], v[220:223], 0
	v_mfma_i32_16x16x64_i8 v[76:79], v[176:179], v[220:223], 0
	v_mfma_i32_16x16x64_i8 v[132:135], v[172:175], v[188:191], v[132:135]
	v_mfma_i32_16x16x64_i8 v[124:127], v[180:183], v[188:191], v[124:127]
	v_mfma_i32_16x16x64_i8 v[116:119], v[172:175], v[208:211], v[116:119]
	v_mfma_i32_16x16x64_i8 v[108:111], v[180:183], v[208:211], v[108:111]
	v_mfma_i32_16x16x64_i8 v[100:103], v[172:175], v[216:219], v[100:103]
	v_mfma_i32_16x16x64_i8 v[92:95], v[180:183], v[216:219], v[92:95]
	v_mfma_i32_16x16x64_i8 v[84:87], v[172:175], v[224:227], v[84:87]
	v_mfma_i32_16x16x64_i8 v[76:79], v[180:183], v[224:227], v[76:79]
	s_setprio 0
	s_barrier
	s_add_i32 s64, s64, s47
	v_lshl_add_u64 v[164:165], s[44:45], 0, v[2:3]
	s_mov_b32 m0, s64
	ds_read_b128 v[184:187], v171 offset:16384
	ds_read_b128 v[188:191], v171 offset:17408
	ds_read_b128 v[204:207], v171 offset:18432
	ds_read_b128 v[208:211], v171 offset:19456
	ds_read_b128 v[212:215], v171 offset:20480
	ds_read_b128 v[216:219], v171 offset:21504
	ds_read_b128 v[220:223], v171 offset:22528
	ds_read_b128 v[224:227], v171 offset:23552
	global_load_lds_dwordx4 v[164:165], off
	s_add_i32 m0, s64, 0x2000
	s_add_u32 s64, s44, 0x80000
	v_lshl_add_u64 v[228:229], s[44:45], 0, v[148:149]
	s_addc_u32 s65, s45, 0
	s_add_i32 s67, s67, s47
	global_load_lds_dwordx4 v[228:229], off
	v_lshl_add_u64 v[240:241], s[64:65], 0, v[2:3]
	s_mov_b32 m0, s67
	v_lshl_add_u64 v[242:243], s[48:49], 0, v[150:151]
	global_load_lds_dwordx4 v[240:241], off
	v_lshl_add_u64 v[240:241], s[64:65], 0, v[148:149]
	s_add_i32 m0, s67, 0x2000
	s_nop 0
	global_load_lds_dwordx4 v[240:241], off
	v_lshl_add_u64 v[240:241], s[48:49], 0, v[152:153]
	s_mov_b32 m0, s50
	s_nop 0
	global_load_lds_dwordx4 v[240:241], off
	s_mov_b32 m0, s51
	s_nop 0
	global_load_lds_dwordx4 v[242:243], off
	s_waitcnt vmcnt(8)
	s_waitcnt lgkmcnt(0)
	s_barrier
; #define PG8_STAGE(bufoff, gbase, voff) do { _Pragma("unroll") for (int _i = 0; _i < 2; ++_i) \
;         __builtin_amdgcn_global_load_lds((const unsigned*)((const char*)(gbase) + (voff)[_i]), (PG8_LAS unsigned*)(lds + (bufoff) + ldsw + _i * 8192), 16, 0, 0); } while (0)
; #define PG8_LDA(dst, b, h) do { _Pragma("unroll") for (int m = 0; m < 4; ++m) _Pragma("unroll") for (int k = 0; k < 2; ++k) dst[m][k] = *(const PG8_LAS bf16x8*)(lds + PG8_SA(b, h) + aoff + m * 2048 + k * 1024); } while (0)
; #define PG8_LDB(dst, b, h) do { _Pragma("unroll") for (int n = 0; n < 2; ++n) _Pragma("unroll") for (int k = 0; k < 2; ++k) dst[n][k] = *(const PG8_LAS bf16x8*)(lds + PG8_SB(b, h) + boff + n * 2048 + k * 1024); } while (0)
; #define PG8_WAIT_V(n) asm volatile("s_waitcnt vmcnt(" #n ")" ::: "memory")
; #define PG8_WAIT_L(n) asm volatile("s_waitcnt lgkmcnt(" #n ")" ::: "memory")
; #define PG8_BAR __builtin_amdgcn_s_barrier()
; #define PG8_SCHED __builtin_amdgcn_sched_barrier(0)
; template <class Epi, class Sched, bool ALIGN_EPI = false, bool SP2 = false, bool I8 = false>
; __device__ __forceinline__ void gemm_phase(PG8_LAS unsigned char* lds, const Gemm g, const Sched& S, const Epi& E) {
;     ...
;             PG8_WAIT_V(8); PG8_WAIT_L(0); PG8_BAR; PG8_MMA(1, 0, At, B0); PG8_MMA(1, 1, At, B1); PG8_BAR; PG8_SCHED;
;             PG8_LDB(B0, 1, 0); PG8_LDB(B1, 1, 1); PG8_SCHED; PG8_LDA(At, 1, 0); PG8_STAGE(PG8_SA(0, 1), a2 + hstep, voffA);
;             PG8_WAIT_V(8); PG8_WAIT_L(0); PG8_BAR; PG8_MMA(0, 0, At, B0); PG8_MMA(0, 1, At, B1); PG8_BAR; PG8_SCHED;
	s_setprio 1
	s_waitcnt lgkmcnt(0)
	v_mfma_i32_16x16x64_i8 v[72:75], v[36:39], v[184:187], 0
	v_mfma_i32_16x16x64_i8 v[64:67], v[140:143], v[184:187], 0
	v_mfma_i32_16x16x64_i8 v[56:59], v[36:39], v[204:207], 0
	v_mfma_i32_16x16x64_i8 v[48:51], v[140:143], v[204:207], 0
	v_mfma_i32_16x16x64_i8 v[32:35], v[36:39], v[212:215], 0
	v_mfma_i32_16x16x64_i8 v[24:27], v[140:143], v[212:215], 0
	v_mfma_i32_16x16x64_i8 v[16:19], v[36:39], v[220:223], 0
	v_mfma_i32_16x16x64_i8 v[8:11], v[140:143], v[220:223], 0
	v_mfma_i32_16x16x64_i8 v[72:75], v[44:47], v[188:191], v[72:75]
	v_mfma_i32_16x16x64_i8 v[64:67], v[144:147], v[188:191], v[64:67]
	v_mfma_i32_16x16x64_i8 v[56:59], v[44:47], v[208:211], v[56:59]
	v_mfma_i32_16x16x64_i8 v[48:51], v[144:147], v[208:211], v[48:51]
	v_mfma_i32_16x16x64_i8 v[32:35], v[44:47], v[216:219], v[32:35]
	v_mfma_i32_16x16x64_i8 v[24:27], v[144:147], v[216:219], v[24:27]
	v_mfma_i32_16x16x64_i8 v[16:19], v[44:47], v[224:227], v[16:19]
	v_mfma_i32_16x16x64_i8 v[8:11], v[144:147], v[224:227], v[8:11]
	s_setprio 0
	s_setprio 1
	v_mfma_i32_16x16x64_i8 v[52:55], v[160:163], v[204:207], 0
	v_mfma_i32_16x16x64_i8 v[40:43], v[176:179], v[204:207], 0
	v_mfma_i32_16x16x64_i8 v[28:31], v[160:163], v[212:215], 0
	v_mfma_i32_16x16x64_i8 v[20:23], v[176:179], v[212:215], 0
	v_mfma_i32_16x16x64_i8 v[12:15], v[160:163], v[220:223], 0
	v_mfma_i32_16x16x64_i8 v[4:7], v[176:179], v[220:223], 0
	v_mfma_i32_16x16x64_i8 v[36:39], v[160:163], v[184:187], 0
	v_mfma_i32_16x16x64_i8 v[44:47], v[176:179], v[184:187], 0
	v_mfma_i32_16x16x64_i8 v[52:55], v[172:175], v[208:211], v[52:55]
	v_mfma_i32_16x16x64_i8 v[40:43], v[180:183], v[208:211], v[40:43]
	v_mfma_i32_16x16x64_i8 v[28:31], v[172:175], v[216:219], v[28:31]
	v_mfma_i32_16x16x64_i8 v[20:23], v[180:183], v[216:219], v[20:23]
	v_mfma_i32_16x16x64_i8 v[12:15], v[172:175], v[224:227], v[12:15]
	v_mfma_i32_16x16x64_i8 v[4:7], v[180:183], v[224:227], v[4:7]
	v_mfma_i32_16x16x64_i8 v[36:39], v[172:175], v[188:191], v[36:39]
	v_mfma_i32_16x16x64_i8 v[44:47], v[180:183], v[188:191], v[44:47]
	s_setprio 0
	s_barrier
	s_add_i32 s64, 0, 0x18000
	s_add_i32 s65, 0, 0x1c000
	v_add_u32_e32 v144, s64, v167
	v_add_u32_e32 v158, s65, v167
	ds_read_b128 v[60:63], v144
	ds_read_b128 v[68:71], v144 offset:1024
	ds_read_b128 v[140:143], v144 offset:2048
	ds_read_b128 v[144:147], v144 offset:3072
	ds_read_b128 v[160:163], v158
	ds_read_b128 v[172:175], v158 offset:1024
	ds_read_b128 v[176:179], v158 offset:2048
	ds_read_b128 v[180:183], v158 offset:3072
	s_add_u32 s48, s48, 0x80000
	s_addc_u32 s49, s49, 0
	s_mov_b32 m0, s52
	v_lshl_add_u64 v[244:245], s[48:49], 0, v[152:153]
	ds_read_b128 v[184:187], v171 offset:32768
	ds_read_b128 v[188:191], v171 offset:33792
	ds_read_b128 v[204:207], v171 offset:34816
	ds_read_b128 v[208:211], v171 offset:35840
	ds_read_b128 v[212:215], v171 offset:36864
	ds_read_b128 v[216:219], v171 offset:37888
	ds_read_b128 v[220:223], v171 offset:38912
	ds_read_b128 v[224:227], v171 offset:39936
	global_load_lds_dwordx4 v[244:245], off
	v_lshl_add_u64 v[244:245], s[48:49], 0, v[150:151]
	s_mov_b32 m0, s53
	s_nop 0
	global_load_lds_dwordx4 v[244:245], off
	s_waitcnt vmcnt(8)
	s_waitcnt lgkmcnt(0)
	s_barrier
	s_setprio 1
	s_waitcnt lgkmcnt(0)
	v_mfma_i32_16x16x64_i8 v[136:139], v[60:63], v[184:187], v[136:139]
	v_mfma_i32_16x16x64_i8 v[128:131], v[140:143], v[184:187], v[128:131]
	v_mfma_i32_16x16x64_i8 v[120:123], v[60:63], v[204:207], v[120:123]
	v_mfma_i32_16x16x64_i8 v[112:115], v[140:143], v[204:207], v[112:115]
	v_mfma_i32_16x16x64_i8 v[104:107], v[60:63], v[212:215], v[104:107]
	v_mfma_i32_16x16x64_i8 v[96:99], v[140:143], v[212:215], v[96:99]
	v_mfma_i32_16x16x64_i8 v[88:91], v[60:63], v[220:223], v[88:91]
	v_mfma_i32_16x16x64_i8 v[80:83], v[140:143], v[220:223], v[80:83]
	v_mfma_i32_16x16x64_i8 v[136:139], v[68:71], v[188:191], v[136:139]
	v_mfma_i32_16x16x64_i8 v[128:131], v[144:147], v[188:191], v[128:131]
	v_mfma_i32_16x16x64_i8 v[120:123], v[68:71], v[208:211], v[120:123]
	v_mfma_i32_16x16x64_i8 v[112:115], v[144:147], v[208:211], v[112:115]
	v_mfma_i32_16x16x64_i8 v[104:107], v[68:71], v[216:219], v[104:107]
	v_mfma_i32_16x16x64_i8 v[96:99], v[144:147], v[216:219], v[96:99]
	v_mfma_i32_16x16x64_i8 v[88:91], v[68:71], v[224:227], v[88:91]
	v_mfma_i32_16x16x64_i8 v[80:83], v[144:147], v[224:227], v[80:83]
	s_setprio 0
	s_setprio 1
	v_mfma_i32_16x16x64_i8 v[132:135], v[160:163], v[184:187], v[132:135]
	v_mfma_i32_16x16x64_i8 v[124:127], v[176:179], v[184:187], v[124:127]
	v_mfma_i32_16x16x64_i8 v[116:119], v[160:163], v[204:207], v[116:119]
	v_mfma_i32_16x16x64_i8 v[108:111], v[176:179], v[204:207], v[108:111]
	v_mfma_i32_16x16x64_i8 v[100:103], v[160:163], v[212:215], v[100:103]
	v_mfma_i32_16x16x64_i8 v[92:95], v[176:179], v[212:215], v[92:95]
	v_mfma_i32_16x16x64_i8 v[84:87], v[160:163], v[220:223], v[84:87]
	v_mfma_i32_16x16x64_i8 v[76:79], v[176:179], v[220:223], v[76:79]
	v_mfma_i32_16x16x64_i8 v[132:135], v[172:175], v[188:191], v[132:135]
	v_mfma_i32_16x16x64_i8 v[124:127], v[180:183], v[188:191], v[124:127]
	v_mfma_i32_16x16x64_i8 v[116:119], v[172:175], v[208:211], v[116:119]
	v_mfma_i32_16x16x64_i8 v[108:111], v[180:183], v[208:211], v[108:111]
	v_mfma_i32_16x16x64_i8 v[100:103], v[172:175], v[216:219], v[100:103]
	v_mfma_i32_16x16x64_i8 v[92:95], v[180:183], v[216:219], v[92:95]
	v_mfma_i32_16x16x64_i8 v[84:87], v[172:175], v[224:227], v[84:87]
	v_mfma_i32_16x16x64_i8 v[76:79], v[180:183], v[224:227], v[76:79]
	s_setprio 0
	s_barrier
; #define PG8_STAGE(bufoff, gbase, voff) do { _Pragma("unroll") for (int _i = 0; _i < 2; ++_i) \
;         __builtin_amdgcn_global_load_lds((const unsigned*)((const char*)(gbase) + (voff)[_i]), (PG8_LAS unsigned*)(lds + (bufoff) + ldsw + _i * 8192), 16, 0, 0); } while (0)
; #define PG8_LDA(dst, b, h) do { _Pragma("unroll") for (int m = 0; m < 4; ++m) _Pragma("unroll") for (int k = 0; k < 2; ++k) dst[m][k] = *(const PG8_LAS bf16x8*)(lds + PG8_SA(b, h) + aoff + m * 2048 + k * 1024); } while (0)
; #define PG8_WAIT_V(n) asm volatile("s_waitcnt vmcnt(" #n ")" ::: "memory")
; #define PG8_WAIT_L(n) asm volatile("s_waitcnt lgkmcnt(" #n ")" ::: "memory")
; #define PG8_BAR __builtin_amdgcn_s_barrier()
; #define PG8_SCHED __builtin_amdgcn_sched_barrier(0)
; template <class Epi, class Sched, bool ALIGN_EPI = false, bool SP2 = false, bool I8 = false>
; __device__ __forceinline__ void gemm_phase(PG8_LAS unsigned char* lds, const Gemm g, const Sched& S, const Epi& E) {
;     ...
;             PG8_LDA(At, 1, 1); PG8_STAGE(PG8_SB(1, 0), b3, voffB); PG8_STAGE(PG8_SB(1, 1), b3 + hstep, voffB); PG8_STAGE(PG8_SA(1, 0), a3, voffA);
;             PG8_WAIT_V(8); PG8_WAIT_L(0); PG8_BAR; PG8_MMA(1, 0, At, B0); PG8_MMA(1, 1, At, B1); PG8_BAR; PG8_SCHED;
	s_add_i32 s48, s64, s47
	v_lshl_add_u64 v[164:165], v[164:165], 0, s[84:85]
	s_mov_b32 m0, s48
	ds_read_b128 v[184:187], v171 offset:49152
	ds_read_b128 v[188:191], v171 offset:50176
	ds_read_b128 v[204:207], v171 offset:51200
	ds_read_b128 v[208:211], v171 offset:52224
	ds_read_b128 v[212:215], v171 offset:53248
	ds_read_b128 v[216:219], v171 offset:54272
	ds_read_b128 v[220:223], v171 offset:55296
	ds_read_b128 v[224:227], v171 offset:56320
	global_load_lds_dwordx4 v[164:165], off
	s_add_i32 m0, s48, 0x2000
	s_add_u32 s44, s44, 0x80080
	v_lshl_add_u64 v[164:165], v[228:229], 0, s[84:85]
	s_addc_u32 s45, s45, 0
	s_add_i32 s48, s65, s47
	global_load_lds_dwordx4 v[164:165], off
	v_lshl_add_u64 v[164:165], s[44:45], 0, v[2:3]
	s_mov_b32 m0, s48
	s_nop 0
	global_load_lds_dwordx4 v[164:165], off
	v_lshl_add_u64 v[164:165], s[44:45], 0, v[148:149]
	s_add_i32 m0, s48, 0x2000
	s_nop 0
	global_load_lds_dwordx4 v[164:165], off
	v_lshl_add_u64 v[164:165], v[240:241], 0, s[84:85]
	s_mov_b32 m0, s54
	s_nop 0
	global_load_lds_dwordx4 v[164:165], off
	v_lshl_add_u64 v[164:165], v[242:243], 0, s[84:85]
	s_mov_b32 m0, s55
	s_nop 0
	global_load_lds_dwordx4 v[164:165], off
	s_waitcnt vmcnt(8)
	s_waitcnt lgkmcnt(0)
	s_barrier
	s_setprio 1
	s_waitcnt lgkmcnt(0)
	v_mfma_i32_16x16x64_i8 v[72:75], v[60:63], v[184:187], v[72:75]
	v_mfma_i32_16x16x64_i8 v[64:67], v[140:143], v[184:187], v[64:67]
	v_mfma_i32_16x16x64_i8 v[56:59], v[60:63], v[204:207], v[56:59]
	v_mfma_i32_16x16x64_i8 v[48:51], v[140:143], v[204:207], v[48:51]
	v_mfma_i32_16x16x64_i8 v[32:35], v[60:63], v[212:215], v[32:35]
	v_mfma_i32_16x16x64_i8 v[24:27], v[140:143], v[212:215], v[24:27]
	v_mfma_i32_16x16x64_i8 v[16:19], v[60:63], v[220:223], v[16:19]
	v_mfma_i32_16x16x64_i8 v[8:11], v[140:143], v[220:223], v[8:11]
	v_mfma_i32_16x16x64_i8 v[72:75], v[68:71], v[188:191], v[72:75]
	v_mfma_i32_16x16x64_i8 v[64:67], v[144:147], v[188:191], v[64:67]
	v_mfma_i32_16x16x64_i8 v[56:59], v[68:71], v[208:211], v[56:59]
	v_mfma_i32_16x16x64_i8 v[48:51], v[144:147], v[208:211], v[48:51]
	v_mfma_i32_16x16x64_i8 v[32:35], v[68:71], v[216:219], v[32:35]
	v_mfma_i32_16x16x64_i8 v[24:27], v[144:147], v[216:219], v[24:27]
	v_mfma_i32_16x16x64_i8 v[16:19], v[68:71], v[224:227], v[16:19]
	v_mfma_i32_16x16x64_i8 v[8:11], v[144:147], v[224:227], v[8:11]
	s_setprio 0
	s_setprio 1
	v_mfma_i32_16x16x64_i8 v[36:39], v[160:163], v[184:187], v[36:39]
	v_mfma_i32_16x16x64_i8 v[68:71], v[172:175], v[188:191], v[36:39]
	v_mfma_i32_16x16x64_i8 v[36:39], v[176:179], v[184:187], v[44:47]
	v_mfma_i32_16x16x64_i8 v[60:63], v[180:183], v[188:191], v[36:39]
	v_mfma_i32_16x16x64_i8 v[36:39], v[160:163], v[204:207], v[52:55]
	v_mfma_i32_16x16x64_i8 v[52:55], v[172:175], v[208:211], v[36:39]
	v_mfma_i32_16x16x64_i8 v[36:39], v[176:179], v[204:207], v[40:43]
	v_mfma_i32_16x16x64_i8 v[28:31], v[160:163], v[212:215], v[28:31]
	v_mfma_i32_16x16x64_i8 v[20:23], v[176:179], v[212:215], v[20:23]
	v_mfma_i32_16x16x64_i8 v[12:15], v[160:163], v[220:223], v[12:15]
	v_mfma_i32_16x16x64_i8 v[4:7], v[176:179], v[220:223], v[4:7]
	v_mfma_i32_16x16x64_i8 v[40:43], v[180:183], v[208:211], v[36:39]
	v_mfma_i32_16x16x64_i8 v[28:31], v[172:175], v[216:219], v[28:31]
	v_mfma_i32_16x16x64_i8 v[20:23], v[180:183], v[216:219], v[20:23]
	v_mfma_i32_16x16x64_i8 v[12:15], v[172:175], v[224:227], v[12:15]
	v_mfma_i32_16x16x64_i8 v[4:7], v[180:183], v[224:227], v[4:7]
	s_setprio 0
	s_barrier
	s_add_i32 s61, s61, 2
	s_add_u32 s40, s40, 0x100
	s_addc_u32 s41, s41, 0
	s_add_u32 s59, s59, 0x100
	s_addc_u32 s60, s60, 0
	s_cmp_gt_u32 s61, 29
	s_cbranch_scc1 .Lkloop_exit_3

; #define PG8_BAR __builtin_amdgcn_s_barrier()
; template <class Epi, class Sched, bool ALIGN_EPI = false, bool SP2 = false, bool I8 = false>
; __device__ __forceinline__ void gemm_phase(PG8_LAS unsigned char* lds, const Gemm g, const Sched& S, const Epi& E) {
;     ...
;         }
;         if constexpr (ALIGN_EPI) { if (wr == 0) PG8_BAR; }
;         if constexpr (!Epi::AFTER_DRAIN) { E(acc, cur, wr, wc, fr, fq); S.done(cur); }
.Lkloop_exit_3:
	s_and_b64 vcc, exec, s[20:21]
	s_cbranch_vccz .LBB0_1594
	s_barrier

; #define PG8_STAGE(bufoff, gbase, voff) do { _Pragma("unroll") for (int _i = 0; _i < 2; ++_i) \
;         __builtin_amdgcn_global_load_lds((const unsigned*)((const char*)(gbase) + (voff)[_i]), (PG8_LAS unsigned*)(lds + (bufoff) + ldsw + _i * 8192), 16, 0, 0); } while (0)
; #define PG8_LDA(dst, b, h) do { _Pragma("unroll") for (int m = 0; m < 4; ++m) _Pragma("unroll") for (int k = 0; k < 2; ++k) dst[m][k] = *(const PG8_LAS bf16x8*)(lds + PG8_SA(b, h) + aoff + m * 2048 + k * 1024); } while (0)
; #define PG8_LDB(dst, b, h) do { _Pragma("unroll") for (int n = 0; n < 2; ++n) _Pragma("unroll") for (int k = 0; k < 2; ++k) dst[n][k] = *(const PG8_LAS bf16x8*)(lds + PG8_SB(b, h) + boff + n * 2048 + k * 1024); } while (0)
; #define PG8_SCHED __builtin_amdgcn_sched_barrier(0)
; template <class Epi, class Sched, bool ALIGN_EPI = false, bool SP2 = false, bool I8 = false>
; __device__ __forceinline__ void gemm_phase(PG8_LAS unsigned char* lds, const Gemm g, const Sched& S, const Epi& E) {
;     ...
;         const char* nA = has_next ? (const char*)g.A + (size_t)nxt.pm * tstep : cA; const char* nB = has_next ? (const char*)g.Bt + (size_t)nxt.pn * tstep : cB;
;         for (int t = 0; t < nt; t += 2) {
;             const bool last = (t == nt - 2);
;             const char* a1 = cA + (size_t)(t + 1) * kstep;
;             const char* a2 = last ? nA : cA + (size_t)(t + 2) * kstep; const char* b2 = last ? nB : cB + (size_t)(t + 2) * kstep;
;             const char* a3 = a2 + kstep; const char* b3 = b2 + kstep;
;             if (last && has_next) S.a_ready(nxt);
;             if constexpr (SP2) {
;             PG8_LDB(B0, 0, 0); PG8_LDB(B1, 0, 1); PG8_SCHED; PG8_LDA(At, 0, 0); PG8_STAGE(PG8_SA(1, 1), a1 + hstep, voffA);
;     ...
; #pragma unroll
;         for (int a = 0; a < 2; ++a)
; #pragma unroll
;             for (int b = 0; b < 2; ++b)
; #pragma unroll
;                 for (int m = 0; m < 4; ++m)
; #pragma unroll
;                     for (int n = 0; n < 2; ++n) acc[a][b][m][n] = (acc_t){0, 0, 0, 0};
.LBB0_1621:
	v_mov_b32_e32 v127, 0
	s_andn2_b64 vcc, exec, s[26:27]
	v_mov_b32_e32 v126, v127
	v_mov_b32_e32 v125, v127
	v_mov_b32_e32 v124, v127
	v_mov_b32_e32 v131, v127
	v_mov_b32_e32 v130, v127
	v_mov_b32_e32 v129, v127
	v_mov_b32_e32 v128, v127
	v_mov_b32_e32 v115, v127
	v_mov_b32_e32 v114, v127
	v_mov_b32_e32 v113, v127
	v_mov_b32_e32 v112, v127
	v_mov_b32_e32 v111, v127
	v_mov_b32_e32 v110, v127
	v_mov_b32_e32 v109, v127
	v_mov_b32_e32 v108, v127
	v_mov_b32_e32 v99, v127
	v_mov_b32_e32 v98, v127
	v_mov_b32_e32 v97, v127
	v_mov_b32_e32 v96, v127
	v_mov_b32_e32 v95, v127
	v_mov_b32_e32 v94, v127
	v_mov_b32_e32 v93, v127
	v_mov_b32_e32 v92, v127
	v_mov_b32_e32 v83, v127
	v_mov_b32_e32 v82, v127
	v_mov_b32_e32 v81, v127
	v_mov_b32_e32 v80, v127
	v_mov_b32_e32 v79, v127
	v_mov_b32_e32 v78, v127
	v_mov_b32_e32 v77, v127
	v_mov_b32_e32 v76, v127
	v_mov_b32_e32 v123, v127
	v_mov_b32_e32 v122, v127
	v_mov_b32_e32 v121, v127
	v_mov_b32_e32 v120, v127
	v_mov_b32_e32 v119, v127
	v_mov_b32_e32 v118, v127
	v_mov_b32_e32 v117, v127
	v_mov_b32_e32 v116, v127
	v_mov_b32_e32 v107, v127
	v_mov_b32_e32 v106, v127
	v_mov_b32_e32 v105, v127
	v_mov_b32_e32 v104, v127
	v_mov_b32_e32 v103, v127
	v_mov_b32_e32 v102, v127
	v_mov_b32_e32 v101, v127
	v_mov_b32_e32 v100, v127
	v_mov_b32_e32 v91, v127
	v_mov_b32_e32 v90, v127
	v_mov_b32_e32 v89, v127
	v_mov_b32_e32 v88, v127
	v_mov_b32_e32 v87, v127
	v_mov_b32_e32 v86, v127
	v_mov_b32_e32 v85, v127
	v_mov_b32_e32 v84, v127
	v_mov_b32_e32 v75, v127
	v_mov_b32_e32 v74, v127
	v_mov_b32_e32 v73, v127
	v_mov_b32_e32 v72, v127
	v_mov_b32_e32 v71, v127
	v_mov_b32_e32 v70, v127
	v_mov_b32_e32 v69, v127
	v_mov_b32_e32 v68, v127
	v_mov_b32_e32 v67, v127
	v_mov_b32_e32 v66, v127
	v_mov_b32_e32 v65, v127
	v_mov_b32_e32 v64, v127
	v_mov_b32_e32 v63, v127
	v_mov_b32_e32 v62, v127
	v_mov_b32_e32 v61, v127
	v_mov_b32_e32 v60, v127
	v_mov_b32_e32 v51, v127
	v_mov_b32_e32 v50, v127
	v_mov_b32_e32 v49, v127
	v_mov_b32_e32 v48, v127
	v_mov_b32_e32 v47, v127
	v_mov_b32_e32 v46, v127
	v_mov_b32_e32 v45, v127
	v_mov_b32_e32 v44, v127
	v_mov_b32_e32 v35, v127
	v_mov_b32_e32 v34, v127
	v_mov_b32_e32 v33, v127
	v_mov_b32_e32 v32, v127
	v_mov_b32_e32 v31, v127
	v_mov_b32_e32 v30, v127
	v_mov_b32_e32 v29, v127
	v_mov_b32_e32 v28, v127
	v_mov_b32_e32 v19, v127
	v_mov_b32_e32 v18, v127
	v_mov_b32_e32 v17, v127
	v_mov_b32_e32 v16, v127
	v_mov_b32_e32 v15, v127
	v_mov_b32_e32 v14, v127
	v_mov_b32_e32 v13, v127
	v_mov_b32_e32 v12, v127
	v_mov_b32_e32 v59, v127
	v_mov_b32_e32 v58, v127
	v_mov_b32_e32 v57, v127
	v_mov_b32_e32 v56, v127
	v_mov_b32_e32 v55, v127
	v_mov_b32_e32 v54, v127
	v_mov_b32_e32 v53, v127
	v_mov_b32_e32 v52, v127
	v_mov_b32_e32 v43, v127
	v_mov_b32_e32 v42, v127
	v_mov_b32_e32 v41, v127
	v_mov_b32_e32 v40, v127
	v_mov_b32_e32 v39, v127
	v_mov_b32_e32 v38, v127
	v_mov_b32_e32 v37, v127
	v_mov_b32_e32 v36, v127
	v_mov_b32_e32 v27, v127
	v_mov_b32_e32 v26, v127
	v_mov_b32_e32 v25, v127
	v_mov_b32_e32 v24, v127
	v_mov_b32_e32 v23, v127
	v_mov_b32_e32 v22, v127
	v_mov_b32_e32 v21, v127
	v_mov_b32_e32 v20, v127
	v_mov_b32_e32 v11, v127
	v_mov_b32_e32 v10, v127
	v_mov_b32_e32 v9, v127
	v_mov_b32_e32 v8, v127
	v_mov_b32_e32 v7, v127
	v_mov_b32_e32 v6, v127
	v_mov_b32_e32 v5, v127
	v_mov_b32_e32 v4, v127
	s_cbranch_vccnz .LBB0_1625
	s_add_u32 s44, s44, 0x80
	s_addc_u32 s45, s45, 0
	s_add_u32 s65, s48, 0x100
	s_addc_u32 s67, s49, 0
	s_mov_b32 s48, 0
	s_add_i32 s72, s48, 2
	s_add_u32 s73, s44, 0x80
	s_addc_u32 s49, s45, 0
	s_add_i32 s86, 0, 0x10000
	s_cmp_eq_u32 s57, s48
	s_cselect_b32 s49, s13, s49
	s_cselect_b32 s48, s12, s73
	s_cselect_b32 s77, s41, s67
	s_cselect_b32 s76, s40, s65
	s_add_i32 s73, 0, 0x14000
	v_add_u32_e32 v158, s86, v143
	v_add_u32_e32 v174, s73, v143
	ds_read_b128 v[146:149], v158
	ds_read_b128 v[150:153], v158 offset:1024
	ds_read_b128 v[154:157], v158 offset:2048
	ds_read_b128 v[158:161], v158 offset:3072
	ds_read_b128 v[162:165], v174
	ds_read_b128 v[166:169], v174 offset:1024
	ds_read_b128 v[170:173], v174 offset:2048
	ds_read_b128 v[174:177], v174 offset:3072
	v_lshl_add_u64 v[190:191], s[44:45], 0, v[138:139]
	s_add_i32 m0, s47, 0xc000
	ds_read_b128 v[178:181], v145
	ds_read_b128 v[182:185], v145 offset:1024
	ds_read_b128 v[186:189], v145 offset:2048
	ds_read_b128 v[204:207], v145 offset:3072
	ds_read_b128 v[208:211], v145 offset:4096
	ds_read_b128 v[212:215], v145 offset:5120
	ds_read_b128 v[216:219], v145 offset:6144
	ds_read_b128 v[220:223], v145 offset:7168
	global_load_lds_dwordx4 v[190:191], off
	v_lshl_add_u64 v[190:191], s[44:45], 0, v[140:141]
	s_add_i32 m0, s47, 0xe000
	s_nop 0
	global_load_lds_dwordx4 v[190:191], off
	s_waitcnt vmcnt(8)
	s_waitcnt lgkmcnt(0)
	s_barrier
; #define PG8_STAGE(bufoff, gbase, voff) do { _Pragma("unroll") for (int _i = 0; _i < 2; ++_i) \
;         __builtin_amdgcn_global_load_lds((const unsigned*)((const char*)(gbase) + (voff)[_i]), (PG8_LAS unsigned*)(lds + (bufoff) + ldsw + _i * 8192), 16, 0, 0); } while (0)
; #define PG8_LDA(dst, b, h) do { _Pragma("unroll") for (int m = 0; m < 4; ++m) _Pragma("unroll") for (int k = 0; k < 2; ++k) dst[m][k] = *(const PG8_LAS bf16x8*)(lds + PG8_SA(b, h) + aoff + m * 2048 + k * 1024); } while (0)
; #define PG8_WAIT_V(n) asm volatile("s_waitcnt vmcnt(" #n ")" ::: "memory")
; #define PG8_WAIT_L(n) asm volatile("s_waitcnt lgkmcnt(" #n ")" ::: "memory")
; #define PG8_BAR __builtin_amdgcn_s_barrier()
; #define PG8_SCHED __builtin_amdgcn_sched_barrier(0)
; template <class Epi, class Sched, bool ALIGN_EPI = false, bool SP2 = false, bool I8 = false>
; __device__ __forceinline__ void gemm_phase(PG8_LAS unsigned char* lds, const Gemm g, const Sched& S, const Epi& E) {
;     ...
;             PG8_WAIT_V(8); PG8_WAIT_L(0); PG8_BAR; PG8_MMA(0, 0, At, B0); PG8_MMA(0, 1, At, B1); PG8_BAR; PG8_SCHED;
;             PG8_LDA(At, 0, 1); PG8_STAGE(PG8_SB(0, 0), b2, voffB); PG8_STAGE(PG8_SB(0, 1), b2 + hstep, voffB); PG8_STAGE(PG8_SA(0, 0), a2, voffA);
;             PG8_WAIT_V(8); PG8_WAIT_L(0); PG8_BAR; PG8_MMA(1, 0, At, B0); PG8_MMA(1, 1, At, B1); PG8_BAR; PG8_SCHED;
	s_setprio 1
	s_waitcnt lgkmcnt(0)
	v_mfma_f32_16x16x32_bf16 v[124:127], v[146:149], v[178:181], 0
	v_mfma_f32_16x16x32_bf16 v[128:131], v[154:157], v[178:181], 0
	v_mfma_f32_16x16x32_bf16 v[112:115], v[146:149], v[186:189], 0
	v_mfma_f32_16x16x32_bf16 v[108:111], v[154:157], v[186:189], 0
	v_mfma_f32_16x16x32_bf16 v[96:99], v[146:149], v[208:211], 0
	v_mfma_f32_16x16x32_bf16 v[92:95], v[154:157], v[208:211], 0
	v_mfma_f32_16x16x32_bf16 v[80:83], v[146:149], v[216:219], 0
	v_mfma_f32_16x16x32_bf16 v[76:79], v[154:157], v[216:219], 0
	v_mfma_f32_16x16x32_bf16 v[124:127], v[150:153], v[182:185], v[124:127]
	v_mfma_f32_16x16x32_bf16 v[128:131], v[158:161], v[182:185], v[128:131]
	v_mfma_f32_16x16x32_bf16 v[112:115], v[150:153], v[204:207], v[112:115]
	v_mfma_f32_16x16x32_bf16 v[108:111], v[158:161], v[204:207], v[108:111]
	v_mfma_f32_16x16x32_bf16 v[96:99], v[150:153], v[212:215], v[96:99]
	v_mfma_f32_16x16x32_bf16 v[92:95], v[158:161], v[212:215], v[92:95]
	v_mfma_f32_16x16x32_bf16 v[80:83], v[150:153], v[220:223], v[80:83]
	v_mfma_f32_16x16x32_bf16 v[76:79], v[158:161], v[220:223], v[76:79]
	s_setprio 0
	s_setprio 1
	v_mfma_f32_16x16x32_bf16 v[120:123], v[162:165], v[178:181], 0
	v_mfma_f32_16x16x32_bf16 v[116:119], v[170:173], v[178:181], 0
	v_mfma_f32_16x16x32_bf16 v[104:107], v[162:165], v[186:189], 0
	v_mfma_f32_16x16x32_bf16 v[100:103], v[170:173], v[186:189], 0
	v_mfma_f32_16x16x32_bf16 v[88:91], v[162:165], v[208:211], 0
	v_mfma_f32_16x16x32_bf16 v[84:87], v[170:173], v[208:211], 0
	v_mfma_f32_16x16x32_bf16 v[72:75], v[162:165], v[216:219], 0
	v_mfma_f32_16x16x32_bf16 v[68:71], v[170:173], v[216:219], 0
	v_mfma_f32_16x16x32_bf16 v[120:123], v[166:169], v[182:185], v[120:123]
	v_mfma_f32_16x16x32_bf16 v[116:119], v[174:177], v[182:185], v[116:119]
	v_mfma_f32_16x16x32_bf16 v[104:107], v[166:169], v[204:207], v[104:107]
	v_mfma_f32_16x16x32_bf16 v[100:103], v[174:177], v[204:207], v[100:103]
	v_mfma_f32_16x16x32_bf16 v[88:91], v[166:169], v[212:215], v[88:91]
	v_mfma_f32_16x16x32_bf16 v[84:87], v[174:177], v[212:215], v[84:87]
	v_mfma_f32_16x16x32_bf16 v[72:75], v[166:169], v[220:223], v[72:75]
	v_mfma_f32_16x16x32_bf16 v[68:71], v[174:177], v[220:223], v[68:71]
	s_setprio 0
	s_barrier
	s_add_i32 s86, s86, s28
	v_lshl_add_u64 v[190:191], s[76:77], 0, v[2:3]
	s_mov_b32 m0, s86
	ds_read_b128 v[178:181], v145 offset:16384
	ds_read_b128 v[182:185], v145 offset:17408
	ds_read_b128 v[186:189], v145 offset:18432
	ds_read_b128 v[204:207], v145 offset:19456
	ds_read_b128 v[208:211], v145 offset:20480
	ds_read_b128 v[212:215], v145 offset:21504
	ds_read_b128 v[216:219], v145 offset:22528
	ds_read_b128 v[220:223], v145 offset:23552
	global_load_lds_dwordx4 v[190:191], off
	s_add_i32 m0, s86, 0x2000
	v_lshl_add_u64 v[224:225], s[76:77], 0, v[136:137]
	s_add_u32 s76, s76, s18
	s_addc_u32 s77, s77, s19
	s_add_i32 s73, s73, s28
	global_load_lds_dwordx4 v[224:225], off
	v_lshl_add_u64 v[226:227], s[76:77], 0, v[2:3]
	s_mov_b32 m0, s73
	v_lshl_add_u64 v[228:229], s[76:77], 0, v[136:137]
	global_load_lds_dwordx4 v[226:227], off
	s_add_i32 m0, s73, 0x2000
	v_lshl_add_u64 v[240:241], s[48:49], 0, v[132:133]
	global_load_lds_dwordx4 v[228:229], off
	s_mov_b32 m0, s47
	v_lshl_add_u64 v[242:243], s[48:49], 0, v[134:135]
	global_load_lds_dwordx4 v[240:241], off
	s_mov_b32 m0, s50
	s_nop 0
	global_load_lds_dwordx4 v[242:243], off
	s_waitcnt vmcnt(8)
	s_waitcnt lgkmcnt(0)
	s_barrier
	s_setprio 1
	s_waitcnt lgkmcnt(0)
	v_mfma_f32_16x16x32_bf16 v[64:67], v[146:149], v[178:181], 0
	v_mfma_f32_16x16x32_bf16 v[60:63], v[154:157], v[178:181], 0
	v_mfma_f32_16x16x32_bf16 v[48:51], v[146:149], v[186:189], 0
	v_mfma_f32_16x16x32_bf16 v[44:47], v[154:157], v[186:189], 0
	v_mfma_f32_16x16x32_bf16 v[32:35], v[146:149], v[208:211], 0
	v_mfma_f32_16x16x32_bf16 v[28:31], v[154:157], v[208:211], 0
	v_mfma_f32_16x16x32_bf16 v[16:19], v[146:149], v[216:219], 0
	v_mfma_f32_16x16x32_bf16 v[12:15], v[154:157], v[216:219], 0
	v_mfma_f32_16x16x32_bf16 v[64:67], v[150:153], v[182:185], v[64:67]
	v_mfma_f32_16x16x32_bf16 v[60:63], v[158:161], v[182:185], v[60:63]
	v_mfma_f32_16x16x32_bf16 v[48:51], v[150:153], v[204:207], v[48:51]
	v_mfma_f32_16x16x32_bf16 v[44:47], v[158:161], v[204:207], v[44:47]
	v_mfma_f32_16x16x32_bf16 v[32:35], v[150:153], v[212:215], v[32:35]
	v_mfma_f32_16x16x32_bf16 v[28:31], v[158:161], v[212:215], v[28:31]
	v_mfma_f32_16x16x32_bf16 v[16:19], v[150:153], v[220:223], v[16:19]
	v_mfma_f32_16x16x32_bf16 v[12:15], v[158:161], v[220:223], v[12:15]
	s_setprio 0
	s_setprio 1
	v_mfma_f32_16x16x32_bf16 v[56:59], v[162:165], v[178:181], 0
	v_mfma_f32_16x16x32_bf16 v[52:55], v[170:173], v[178:181], 0
	v_mfma_f32_16x16x32_bf16 v[40:43], v[162:165], v[186:189], 0
	v_mfma_f32_16x16x32_bf16 v[36:39], v[170:173], v[186:189], 0
	v_mfma_f32_16x16x32_bf16 v[24:27], v[162:165], v[208:211], 0
	v_mfma_f32_16x16x32_bf16 v[20:23], v[170:173], v[208:211], 0
	v_mfma_f32_16x16x32_bf16 v[8:11], v[162:165], v[216:219], 0
	v_mfma_f32_16x16x32_bf16 v[4:7], v[170:173], v[216:219], 0
	v_mfma_f32_16x16x32_bf16 v[56:59], v[166:169], v[182:185], v[56:59]
	v_mfma_f32_16x16x32_bf16 v[52:55], v[174:177], v[182:185], v[52:55]
	v_mfma_f32_16x16x32_bf16 v[40:43], v[166:169], v[204:207], v[40:43]
	v_mfma_f32_16x16x32_bf16 v[36:39], v[174:177], v[204:207], v[36:39]
	v_mfma_f32_16x16x32_bf16 v[24:27], v[166:169], v[212:215], v[24:27]
	v_mfma_f32_16x16x32_bf16 v[20:23], v[174:177], v[212:215], v[20:23]
	v_mfma_f32_16x16x32_bf16 v[8:11], v[166:169], v[220:223], v[8:11]
	v_mfma_f32_16x16x32_bf16 v[4:7], v[174:177], v[220:223], v[4:7]
	s_setprio 0
	s_barrier
; #define PG8_STAGE(bufoff, gbase, voff) do { _Pragma("unroll") for (int _i = 0; _i < 2; ++_i) \
;         __builtin_amdgcn_global_load_lds((const unsigned*)((const char*)(gbase) + (voff)[_i]), (PG8_LAS unsigned*)(lds + (bufoff) + ldsw + _i * 8192), 16, 0, 0); } while (0)
; #define PG8_LDA(dst, b, h) do { _Pragma("unroll") for (int m = 0; m < 4; ++m) _Pragma("unroll") for (int k = 0; k < 2; ++k) dst[m][k] = *(const PG8_LAS bf16x8*)(lds + PG8_SA(b, h) + aoff + m * 2048 + k * 1024); } while (0)
; #define PG8_LDB(dst, b, h) do { _Pragma("unroll") for (int n = 0; n < 2; ++n) _Pragma("unroll") for (int k = 0; k < 2; ++k) dst[n][k] = *(const PG8_LAS bf16x8*)(lds + PG8_SB(b, h) + boff + n * 2048 + k * 1024); } while (0)
; #define PG8_WAIT_V(n) asm volatile("s_waitcnt vmcnt(" #n ")" ::: "memory")
; #define PG8_WAIT_L(n) asm volatile("s_waitcnt lgkmcnt(" #n ")" ::: "memory")
; #define PG8_BAR __builtin_amdgcn_s_barrier()
; #define PG8_SCHED __builtin_amdgcn_sched_barrier(0)
; template <class Epi, class Sched, bool ALIGN_EPI = false, bool SP2 = false, bool I8 = false>
; __device__ __forceinline__ void gemm_phase(PG8_LAS unsigned char* lds, const Gemm g, const Sched& S, const Epi& E) {
;     ...
;             PG8_LDB(B0, 1, 0); PG8_LDB(B1, 1, 1); PG8_SCHED; PG8_LDA(At, 1, 0); PG8_STAGE(PG8_SA(0, 1), a2 + hstep, voffA);
;             PG8_WAIT_V(8); PG8_WAIT_L(0); PG8_BAR; PG8_MMA(0, 0, At, B0); PG8_MMA(0, 1, At, B1); PG8_BAR; PG8_SCHED;
	s_add_i32 s73, 0, 0x18000
	s_add_i32 s76, 0, 0x1c000
	v_add_u32_e32 v158, s73, v143
	v_add_u32_e32 v174, s76, v143
	ds_read_b128 v[146:149], v158
	ds_read_b128 v[150:153], v158 offset:1024
	ds_read_b128 v[154:157], v158 offset:2048
	ds_read_b128 v[158:161], v158 offset:3072
	ds_read_b128 v[162:165], v174
	ds_read_b128 v[166:169], v174 offset:1024
	ds_read_b128 v[170:173], v174 offset:2048
	ds_read_b128 v[174:177], v174 offset:3072
	s_add_u32 s48, s48, s18
	s_addc_u32 s49, s49, s19
	s_mov_b32 m0, s51
	v_lshl_add_u64 v[244:245], s[48:49], 0, v[132:133]
	ds_read_b128 v[178:181], v145 offset:32768
	ds_read_b128 v[182:185], v145 offset:33792
	ds_read_b128 v[186:189], v145 offset:34816
	ds_read_b128 v[204:207], v145 offset:35840
	ds_read_b128 v[208:211], v145 offset:36864
	ds_read_b128 v[212:215], v145 offset:37888
	ds_read_b128 v[216:219], v145 offset:38912
	ds_read_b128 v[220:223], v145 offset:39936
	global_load_lds_dwordx4 v[244:245], off
	v_lshl_add_u64 v[244:245], s[48:49], 0, v[134:135]
	s_mov_b32 m0, s52
	s_nop 0
	global_load_lds_dwordx4 v[244:245], off
	s_waitcnt vmcnt(8)
	s_waitcnt lgkmcnt(0)
	s_barrier
	s_setprio 1
	s_waitcnt lgkmcnt(0)
	v_mfma_f32_16x16x32_bf16 v[124:127], v[146:149], v[178:181], v[124:127]
	v_mfma_f32_16x16x32_bf16 v[128:131], v[154:157], v[178:181], v[128:131]
	v_mfma_f32_16x16x32_bf16 v[112:115], v[146:149], v[186:189], v[112:115]
	v_mfma_f32_16x16x32_bf16 v[108:111], v[154:157], v[186:189], v[108:111]
	v_mfma_f32_16x16x32_bf16 v[96:99], v[146:149], v[208:211], v[96:99]
	v_mfma_f32_16x16x32_bf16 v[92:95], v[154:157], v[208:211], v[92:95]
	v_mfma_f32_16x16x32_bf16 v[80:83], v[146:149], v[216:219], v[80:83]
	v_mfma_f32_16x16x32_bf16 v[76:79], v[154:157], v[216:219], v[76:79]
	v_mfma_f32_16x16x32_bf16 v[124:127], v[150:153], v[182:185], v[124:127]
	v_mfma_f32_16x16x32_bf16 v[128:131], v[158:161], v[182:185], v[128:131]
	v_mfma_f32_16x16x32_bf16 v[112:115], v[150:153], v[204:207], v[112:115]
	v_mfma_f32_16x16x32_bf16 v[108:111], v[158:161], v[204:207], v[108:111]
	v_mfma_f32_16x16x32_bf16 v[96:99], v[150:153], v[212:215], v[96:99]
	v_mfma_f32_16x16x32_bf16 v[92:95], v[158:161], v[212:215], v[92:95]
	v_mfma_f32_16x16x32_bf16 v[80:83], v[150:153], v[220:223], v[80:83]
	v_mfma_f32_16x16x32_bf16 v[76:79], v[158:161], v[220:223], v[76:79]
	s_setprio 0
	s_setprio 1
	v_mfma_f32_16x16x32_bf16 v[120:123], v[162:165], v[178:181], v[120:123]
	v_mfma_f32_16x16x32_bf16 v[116:119], v[170:173], v[178:181], v[116:119]
	v_mfma_f32_16x16x32_bf16 v[104:107], v[162:165], v[186:189], v[104:107]
	v_mfma_f32_16x16x32_bf16 v[100:103], v[170:173], v[186:189], v[100:103]
	v_mfma_f32_16x16x32_bf16 v[88:91], v[162:165], v[208:211], v[88:91]
	v_mfma_f32_16x16x32_bf16 v[84:87], v[170:173], v[208:211], v[84:87]
	v_mfma_f32_16x16x32_bf16 v[72:75], v[162:165], v[216:219], v[72:75]
	v_mfma_f32_16x16x32_bf16 v[68:71], v[170:173], v[216:219], v[68:71]
	v_mfma_f32_16x16x32_bf16 v[120:123], v[166:169], v[182:185], v[120:123]
	v_mfma_f32_16x16x32_bf16 v[116:119], v[174:177], v[182:185], v[116:119]
	v_mfma_f32_16x16x32_bf16 v[104:107], v[166:169], v[204:207], v[104:107]
	v_mfma_f32_16x16x32_bf16 v[100:103], v[174:177], v[204:207], v[100:103]
	v_mfma_f32_16x16x32_bf16 v[88:91], v[166:169], v[212:215], v[88:91]
	v_mfma_f32_16x16x32_bf16 v[84:87], v[174:177], v[212:215], v[84:87]
	v_mfma_f32_16x16x32_bf16 v[72:75], v[166:169], v[220:223], v[72:75]
	v_mfma_f32_16x16x32_bf16 v[68:71], v[174:177], v[220:223], v[68:71]
	s_setprio 0
	s_barrier
; #define PG8_STAGE(bufoff, gbase, voff) do { _Pragma("unroll") for (int _i = 0; _i < 2; ++_i) \
;         __builtin_amdgcn_global_load_lds((const unsigned*)((const char*)(gbase) + (voff)[_i]), (PG8_LAS unsigned*)(lds + (bufoff) + ldsw + _i * 8192), 16, 0, 0); } while (0)
; #define PG8_LDA(dst, b, h) do { _Pragma("unroll") for (int m = 0; m < 4; ++m) _Pragma("unroll") for (int k = 0; k < 2; ++k) dst[m][k] = *(const PG8_LAS bf16x8*)(lds + PG8_SA(b, h) + aoff + m * 2048 + k * 1024); } while (0)
; #define PG8_WAIT_V(n) asm volatile("s_waitcnt vmcnt(" #n ")" ::: "memory")
; #define PG8_WAIT_L(n) asm volatile("s_waitcnt lgkmcnt(" #n ")" ::: "memory")
; #define PG8_BAR __builtin_amdgcn_s_barrier()
; #define PG8_SCHED __builtin_amdgcn_sched_barrier(0)
; template <class Epi, class Sched, bool ALIGN_EPI = false, bool SP2 = false, bool I8 = false>
; __device__ __forceinline__ void gemm_phase(PG8_LAS unsigned char* lds, const Gemm g, const Sched& S, const Epi& E) {
;     ...
;             PG8_LDA(At, 1, 1); PG8_STAGE(PG8_SB(1, 0), b3, voffB); PG8_STAGE(PG8_SB(1, 1), b3 + hstep, voffB); PG8_STAGE(PG8_SA(1, 0), a3, voffA);
;             PG8_WAIT_V(8); PG8_WAIT_L(0); PG8_BAR; PG8_MMA(1, 0, At, B0); PG8_MMA(1, 1, At, B1); PG8_BAR; PG8_SCHED;
	s_add_i32 s48, s73, s28
	v_lshl_add_u64 v[190:191], v[190:191], 0, s[84:85]
	s_mov_b32 m0, s48
	ds_read_b128 v[178:181], v145 offset:49152
	ds_read_b128 v[182:185], v145 offset:50176
	ds_read_b128 v[186:189], v145 offset:51200
	ds_read_b128 v[204:207], v145 offset:52224
	ds_read_b128 v[208:211], v145 offset:53248
	ds_read_b128 v[212:215], v145 offset:54272
	ds_read_b128 v[216:219], v145 offset:55296
	ds_read_b128 v[220:223], v145 offset:56320
	global_load_lds_dwordx4 v[190:191], off
	v_lshl_add_u64 v[190:191], v[224:225], 0, s[84:85]
	s_add_i32 m0, s48, 0x2000
	s_add_i32 s48, s76, s28
	global_load_lds_dwordx4 v[190:191], off
	v_lshl_add_u64 v[190:191], v[226:227], 0, s[84:85]
	s_mov_b32 m0, s48
	s_nop 0
	global_load_lds_dwordx4 v[190:191], off
	v_lshl_add_u64 v[190:191], v[228:229], 0, s[84:85]
	s_add_i32 m0, s48, 0x2000
	s_nop 0
	global_load_lds_dwordx4 v[190:191], off
	v_lshl_add_u64 v[190:191], v[240:241], 0, s[84:85]
	s_mov_b32 m0, s55
	s_nop 0
	global_load_lds_dwordx4 v[190:191], off
	v_lshl_add_u64 v[190:191], v[242:243], 0, s[84:85]
	s_mov_b32 m0, s56
	s_nop 0
	global_load_lds_dwordx4 v[190:191], off
	s_waitcnt vmcnt(8)
	s_waitcnt lgkmcnt(0)
	s_barrier
	s_setprio 1
	s_waitcnt lgkmcnt(0)
	v_mfma_f32_16x16x32_bf16 v[64:67], v[146:149], v[178:181], v[64:67]
	v_mfma_f32_16x16x32_bf16 v[60:63], v[154:157], v[178:181], v[60:63]
	v_mfma_f32_16x16x32_bf16 v[48:51], v[146:149], v[186:189], v[48:51]
	v_mfma_f32_16x16x32_bf16 v[44:47], v[154:157], v[186:189], v[44:47]
	v_mfma_f32_16x16x32_bf16 v[32:35], v[146:149], v[208:211], v[32:35]
	v_mfma_f32_16x16x32_bf16 v[28:31], v[154:157], v[208:211], v[28:31]
	v_mfma_f32_16x16x32_bf16 v[16:19], v[146:149], v[216:219], v[16:19]
	v_mfma_f32_16x16x32_bf16 v[12:15], v[154:157], v[216:219], v[12:15]
	v_mfma_f32_16x16x32_bf16 v[64:67], v[150:153], v[182:185], v[64:67]
	v_mfma_f32_16x16x32_bf16 v[60:63], v[158:161], v[182:185], v[60:63]
	v_mfma_f32_16x16x32_bf16 v[48:51], v[150:153], v[204:207], v[48:51]
	v_mfma_f32_16x16x32_bf16 v[44:47], v[158:161], v[204:207], v[44:47]
	v_mfma_f32_16x16x32_bf16 v[32:35], v[150:153], v[212:215], v[32:35]
	v_mfma_f32_16x16x32_bf16 v[28:31], v[158:161], v[212:215], v[28:31]
	v_mfma_f32_16x16x32_bf16 v[16:19], v[150:153], v[220:223], v[16:19]
	v_mfma_f32_16x16x32_bf16 v[12:15], v[158:161], v[220:223], v[12:15]
	s_setprio 0
	s_setprio 1
	v_mfma_f32_16x16x32_bf16 v[56:59], v[162:165], v[178:181], v[56:59]
	v_mfma_f32_16x16x32_bf16 v[52:55], v[170:173], v[178:181], v[52:55]
	v_mfma_f32_16x16x32_bf16 v[40:43], v[162:165], v[186:189], v[40:43]
	v_mfma_f32_16x16x32_bf16 v[36:39], v[170:173], v[186:189], v[36:39]
	v_mfma_f32_16x16x32_bf16 v[24:27], v[162:165], v[208:211], v[24:27]
	v_mfma_f32_16x16x32_bf16 v[20:23], v[170:173], v[208:211], v[20:23]
	v_mfma_f32_16x16x32_bf16 v[8:11], v[162:165], v[216:219], v[8:11]
	v_mfma_f32_16x16x32_bf16 v[4:7], v[170:173], v[216:219], v[4:7]
	v_mfma_f32_16x16x32_bf16 v[56:59], v[166:169], v[182:185], v[56:59]
	v_mfma_f32_16x16x32_bf16 v[52:55], v[174:177], v[182:185], v[52:55]
	v_mfma_f32_16x16x32_bf16 v[40:43], v[166:169], v[204:207], v[40:43]
	v_mfma_f32_16x16x32_bf16 v[36:39], v[174:177], v[204:207], v[36:39]
	v_mfma_f32_16x16x32_bf16 v[24:27], v[166:169], v[212:215], v[24:27]
	v_mfma_f32_16x16x32_bf16 v[20:23], v[174:177], v[212:215], v[20:23]
	v_mfma_f32_16x16x32_bf16 v[8:11], v[166:169], v[220:223], v[8:11]
	v_mfma_f32_16x16x32_bf16 v[4:7], v[174:177], v[220:223], v[4:7]
	s_setprio 0
	s_barrier
	s_add_u32 s44, s44, 0x100
	s_addc_u32 s45, s45, 0
	s_add_u32 s65, s65, 0x100
	s_addc_u32 s67, s67, 0
	s_cmp_ge_i32 s72, s53
	s_mov_b32 s48, s72
	s_cbranch_scc1 .Lkloop_exit_4

; #define PG8_BAR __builtin_amdgcn_s_barrier()
; template <class Epi, class Sched, bool ALIGN_EPI = false, bool SP2 = false, bool I8 = false>
; __device__ __forceinline__ void gemm_phase(PG8_LAS unsigned char* lds, const Gemm g, const Sched& S, const Epi& E) {
;     ...
;         }
;         if constexpr (ALIGN_EPI) { if (wr == 0) PG8_BAR; }
;         if constexpr (!Epi::AFTER_DRAIN) { E(acc, cur, wr, wc, fr, fq); S.done(cur); }
.Lkloop_exit_4:
	s_mov_b32 s67, 0x40000

; #define PG8_STAGE(bufoff, gbase, voff) do { _Pragma("unroll") for (int _i = 0; _i < 2; ++_i) \
;         __builtin_amdgcn_global_load_lds((const unsigned*)((const char*)(gbase) + (voff)[_i]), (PG8_LAS unsigned*)(lds + (bufoff) + ldsw + _i * 8192), 16, 0, 0); } while (0)
; #define PG8_LDA(dst, b, h) do { _Pragma("unroll") for (int m = 0; m < 4; ++m) _Pragma("unroll") for (int k = 0; k < 2; ++k) dst[m][k] = *(const PG8_LAS bf16x8*)(lds + PG8_SA(b, h) + aoff + m * 2048 + k * 1024); } while (0)
; #define PG8_LDB(dst, b, h) do { _Pragma("unroll") for (int n = 0; n < 2; ++n) _Pragma("unroll") for (int k = 0; k < 2; ++k) dst[n][k] = *(const PG8_LAS bf16x8*)(lds + PG8_SB(b, h) + boff + n * 2048 + k * 1024); } while (0)
; #define PG8_WAIT_V(n) asm volatile("s_waitcnt vmcnt(" #n ")" ::: "memory")
; #define PG8_WAIT_L(n) asm volatile("s_waitcnt lgkmcnt(" #n ")" ::: "memory")
; #define PG8_BAR __builtin_amdgcn_s_barrier()
; #define PG8_SCHED __builtin_amdgcn_sched_barrier(0)
; template <class Epi, class Sched, bool ALIGN_EPI = false, bool SP2 = false, bool I8 = false>
; __device__ __forceinline__ void gemm_phase(PG8_LAS unsigned char* lds, const Gemm g, const Sched& S, const Epi& E) {
;     ...
;         const char* nA = has_next ? (const char*)g.A + (size_t)nxt.pm * tstep : cA; const char* nB = has_next ? (const char*)g.Bt + (size_t)nxt.pn * tstep : cB;
;         for (int t = 0; t < nt; t += 2) {
;             const bool last = (t == nt - 2);
;             const char* a1 = cA + (size_t)(t + 1) * kstep;
;             const char* a2 = last ? nA : cA + (size_t)(t + 2) * kstep; const char* b2 = last ? nB : cB + (size_t)(t + 2) * kstep;
;             const char* a3 = a2 + kstep; const char* b3 = b2 + kstep;
;             if (last && has_next) S.a_ready(nxt);
;             if constexpr (SP2) {
;             PG8_LDB(B0, 0, 0); PG8_LDB(B1, 0, 1); PG8_SCHED; PG8_LDA(At, 0, 0); PG8_STAGE(PG8_SA(1, 1), a1 + hstep, voffA);
;             PG8_WAIT_V(8); PG8_WAIT_L(0); PG8_BAR; PG8_MMA(0, 0, At, B0); PG8_MMA(0, 1, At, B1); PG8_BAR; PG8_SCHED;
;             PG8_LDA(At, 0, 1); PG8_STAGE(PG8_SB(0, 0), b2, voffB); PG8_STAGE(PG8_SB(0, 1), b2 + hstep, voffB); PG8_STAGE(PG8_SA(0, 0), a2, voffA);
;             PG8_WAIT_V(8); PG8_WAIT_L(0); PG8_BAR; PG8_MMA(1, 0, At, B0); PG8_MMA(1, 1, At, B1); PG8_BAR; PG8_SCHED;
.LBB0_1699:
	s_add_u32 s53, s24, 0x100
	s_addc_u32 s54, s25, 0
	s_mov_b32 s55, -2
	s_add_u32 s24, s22, 0x100
	s_addc_u32 s25, s23, 0
	s_add_i32 s56, 0, 0x10000
	s_cmpk_eq_i32 s55, 0xa8
	s_cselect_b32 s37, s13, s25
	s_cselect_b32 s36, s12, s24
	s_cselect_b32 s27, s21, s54
	s_cselect_b32 s26, s20, s53
	s_add_i32 s57, 0, 0x14000
	v_add_u32_e32 v144, s56, v240
	v_add_u32_e32 v160, s57, v240
	ds_read_b128 v[124:127], v144
	ds_read_b128 v[128:131], v144 offset:1024
	ds_read_b128 v[132:135], v144 offset:2048
	ds_read_b128 v[144:147], v144 offset:3072
	ds_read_b128 v[148:151], v160
	ds_read_b128 v[152:155], v160 offset:1024
	ds_read_b128 v[156:159], v160 offset:2048
	ds_read_b128 v[160:163], v160 offset:3072
	v_lshl_add_u64 v[218:219], s[22:23], 0, v[210:211]
	s_add_i32 m0, s42, 0xc000
	ds_read_b128 v[164:167], v242
	ds_read_b128 v[168:171], v242 offset:1024
	ds_read_b128 v[172:175], v242 offset:2048
	ds_read_b128 v[176:179], v242 offset:3072
	ds_read_b128 v[180:183], v242 offset:4096
	ds_read_b128 v[184:187], v242 offset:5120
	ds_read_b128 v[188:191], v242 offset:6144
	ds_read_b128 v[214:217], v242 offset:7168
	global_load_lds_dwordx4 v[218:219], off
	v_lshl_add_u64 v[218:219], s[22:23], 0, v[212:213]
	s_add_i32 m0, s42, 0xe000
	s_nop 0
	global_load_lds_dwordx4 v[218:219], off
	s_waitcnt vmcnt(8)
	s_waitcnt lgkmcnt(0)
	s_barrier
	s_setprio 1
	s_waitcnt lgkmcnt(0)
	v_mfma_f32_16x16x32_bf16 v[140:143], v[124:127], v[164:167], 0
	v_mfma_f32_16x16x32_bf16 v[136:139], v[132:135], v[164:167], 0
	v_mfma_f32_16x16x32_bf16 v[112:115], v[124:127], v[172:175], 0
	v_mfma_f32_16x16x32_bf16 v[108:111], v[132:135], v[172:175], 0
	v_mfma_f32_16x16x32_bf16 v[96:99], v[124:127], v[180:183], 0
	v_mfma_f32_16x16x32_bf16 v[92:95], v[132:135], v[180:183], 0
	v_mfma_f32_16x16x32_bf16 v[80:83], v[124:127], v[188:191], 0
	v_mfma_f32_16x16x32_bf16 v[76:79], v[132:135], v[188:191], 0
	v_mfma_f32_16x16x32_bf16 v[140:143], v[128:131], v[168:171], v[140:143]
	v_mfma_f32_16x16x32_bf16 v[136:139], v[144:147], v[168:171], v[136:139]
	v_mfma_f32_16x16x32_bf16 v[112:115], v[128:131], v[176:179], v[112:115]
	v_mfma_f32_16x16x32_bf16 v[108:111], v[144:147], v[176:179], v[108:111]
	v_mfma_f32_16x16x32_bf16 v[96:99], v[128:131], v[184:187], v[96:99]
	v_mfma_f32_16x16x32_bf16 v[92:95], v[144:147], v[184:187], v[92:95]
	v_mfma_f32_16x16x32_bf16 v[80:83], v[128:131], v[214:217], v[80:83]
	v_mfma_f32_16x16x32_bf16 v[76:79], v[144:147], v[214:217], v[76:79]
	s_setprio 0
	s_setprio 1
	v_mfma_f32_16x16x32_bf16 v[120:123], v[148:151], v[164:167], 0
	v_mfma_f32_16x16x32_bf16 v[116:119], v[156:159], v[164:167], 0
	v_mfma_f32_16x16x32_bf16 v[104:107], v[148:151], v[172:175], 0
	v_mfma_f32_16x16x32_bf16 v[100:103], v[156:159], v[172:175], 0
	v_mfma_f32_16x16x32_bf16 v[88:91], v[148:151], v[180:183], 0
	v_mfma_f32_16x16x32_bf16 v[84:87], v[156:159], v[180:183], 0
	v_mfma_f32_16x16x32_bf16 v[72:75], v[148:151], v[188:191], 0
	v_mfma_f32_16x16x32_bf16 v[68:71], v[156:159], v[188:191], 0
	v_mfma_f32_16x16x32_bf16 v[120:123], v[152:155], v[168:171], v[120:123]
	v_mfma_f32_16x16x32_bf16 v[116:119], v[160:163], v[168:171], v[116:119]
	v_mfma_f32_16x16x32_bf16 v[104:107], v[152:155], v[176:179], v[104:107]
	v_mfma_f32_16x16x32_bf16 v[100:103], v[160:163], v[176:179], v[100:103]
	v_mfma_f32_16x16x32_bf16 v[88:91], v[152:155], v[184:187], v[88:91]
	v_mfma_f32_16x16x32_bf16 v[84:87], v[160:163], v[184:187], v[84:87]
	v_mfma_f32_16x16x32_bf16 v[72:75], v[152:155], v[214:217], v[72:75]
	v_mfma_f32_16x16x32_bf16 v[68:71], v[160:163], v[214:217], v[68:71]
	s_setprio 0
	s_barrier
	s_add_i32 s22, s56, s41
	v_lshl_add_u64 v[218:219], s[26:27], 0, v[2:3]
	s_mov_b32 m0, s22
	ds_read_b128 v[164:167], v242 offset:16384
	ds_read_b128 v[168:171], v242 offset:17408
	ds_read_b128 v[172:175], v242 offset:18432
	ds_read_b128 v[176:179], v242 offset:19456
	ds_read_b128 v[180:183], v242 offset:20480
	ds_read_b128 v[184:187], v242 offset:21504
	ds_read_b128 v[188:191], v242 offset:22528
	ds_read_b128 v[214:217], v242 offset:23552
	global_load_lds_dwordx4 v[218:219], off
	s_add_i32 m0, s22, 0x2000
	s_add_u32 s22, s26, 0x2b0000
	v_lshl_add_u64 v[220:221], s[26:27], 0, v[204:205]
	s_addc_u32 s23, s27, 0
	s_add_i32 s56, s57, s41
	global_load_lds_dwordx4 v[220:221], off
	v_lshl_add_u64 v[222:223], s[22:23], 0, v[2:3]
	s_mov_b32 m0, s56
	v_lshl_add_u64 v[224:225], s[36:37], 0, v[206:207]
	global_load_lds_dwordx4 v[222:223], off
	v_lshl_add_u64 v[222:223], s[22:23], 0, v[204:205]
	s_add_i32 m0, s56, 0x2000
	s_nop 0
	global_load_lds_dwordx4 v[222:223], off
	v_lshl_add_u64 v[222:223], s[36:37], 0, v[208:209]
	s_mov_b32 m0, s42
	s_nop 0
	global_load_lds_dwordx4 v[222:223], off
	s_mov_b32 m0, s43
	s_nop 0
	global_load_lds_dwordx4 v[224:225], off
	s_waitcnt vmcnt(8)
	s_waitcnt lgkmcnt(0)
	s_barrier
; #define PG8_STAGE(bufoff, gbase, voff) do { _Pragma("unroll") for (int _i = 0; _i < 2; ++_i) \
;         __builtin_amdgcn_global_load_lds((const unsigned*)((const char*)(gbase) + (voff)[_i]), (PG8_LAS unsigned*)(lds + (bufoff) + ldsw + _i * 8192), 16, 0, 0); } while (0)
; #define PG8_LDA(dst, b, h) do { _Pragma("unroll") for (int m = 0; m < 4; ++m) _Pragma("unroll") for (int k = 0; k < 2; ++k) dst[m][k] = *(const PG8_LAS bf16x8*)(lds + PG8_SA(b, h) + aoff + m * 2048 + k * 1024); } while (0)
; #define PG8_LDB(dst, b, h) do { _Pragma("unroll") for (int n = 0; n < 2; ++n) _Pragma("unroll") for (int k = 0; k < 2; ++k) dst[n][k] = *(const PG8_LAS bf16x8*)(lds + PG8_SB(b, h) + boff + n * 2048 + k * 1024); } while (0)
; #define PG8_WAIT_V(n) asm volatile("s_waitcnt vmcnt(" #n ")" ::: "memory")
; #define PG8_WAIT_L(n) asm volatile("s_waitcnt lgkmcnt(" #n ")" ::: "memory")
; #define PG8_BAR __builtin_amdgcn_s_barrier()
; #define PG8_SCHED __builtin_amdgcn_sched_barrier(0)
; template <class Epi, class Sched, bool ALIGN_EPI = false, bool SP2 = false, bool I8 = false>
; __device__ __forceinline__ void gemm_phase(PG8_LAS unsigned char* lds, const Gemm g, const Sched& S, const Epi& E) {
;     ...
;             PG8_WAIT_V(8); PG8_WAIT_L(0); PG8_BAR; PG8_MMA(1, 0, At, B0); PG8_MMA(1, 1, At, B1); PG8_BAR; PG8_SCHED;
;             PG8_LDB(B0, 1, 0); PG8_LDB(B1, 1, 1); PG8_SCHED; PG8_LDA(At, 1, 0); PG8_STAGE(PG8_SA(0, 1), a2 + hstep, voffA);
;             PG8_WAIT_V(8); PG8_WAIT_L(0); PG8_BAR; PG8_MMA(0, 0, At, B0); PG8_MMA(0, 1, At, B1); PG8_BAR; PG8_SCHED;
	s_setprio 1
	s_waitcnt lgkmcnt(0)
	v_mfma_f32_16x16x32_bf16 v[64:67], v[124:127], v[164:167], 0
	v_mfma_f32_16x16x32_bf16 v[60:63], v[132:135], v[164:167], 0
	v_mfma_f32_16x16x32_bf16 v[48:51], v[124:127], v[172:175], 0
	v_mfma_f32_16x16x32_bf16 v[44:47], v[132:135], v[172:175], 0
	v_mfma_f32_16x16x32_bf16 v[32:35], v[124:127], v[180:183], 0
	v_mfma_f32_16x16x32_bf16 v[28:31], v[132:135], v[180:183], 0
	v_mfma_f32_16x16x32_bf16 v[16:19], v[124:127], v[188:191], 0
	v_mfma_f32_16x16x32_bf16 v[12:15], v[132:135], v[188:191], 0
	v_mfma_f32_16x16x32_bf16 v[64:67], v[128:131], v[168:171], v[64:67]
	v_mfma_f32_16x16x32_bf16 v[60:63], v[144:147], v[168:171], v[60:63]
	v_mfma_f32_16x16x32_bf16 v[48:51], v[128:131], v[176:179], v[48:51]
	v_mfma_f32_16x16x32_bf16 v[44:47], v[144:147], v[176:179], v[44:47]
	v_mfma_f32_16x16x32_bf16 v[32:35], v[128:131], v[184:187], v[32:35]
	v_mfma_f32_16x16x32_bf16 v[28:31], v[144:147], v[184:187], v[28:31]
	v_mfma_f32_16x16x32_bf16 v[16:19], v[128:131], v[214:217], v[16:19]
	v_mfma_f32_16x16x32_bf16 v[12:15], v[144:147], v[214:217], v[12:15]
	s_setprio 0
	s_setprio 1
	v_mfma_f32_16x16x32_bf16 v[56:59], v[148:151], v[164:167], 0
	v_mfma_f32_16x16x32_bf16 v[52:55], v[156:159], v[164:167], 0
	v_mfma_f32_16x16x32_bf16 v[40:43], v[148:151], v[172:175], 0
	v_mfma_f32_16x16x32_bf16 v[36:39], v[156:159], v[172:175], 0
	v_mfma_f32_16x16x32_bf16 v[24:27], v[148:151], v[180:183], 0
	v_mfma_f32_16x16x32_bf16 v[20:23], v[156:159], v[180:183], 0
	v_mfma_f32_16x16x32_bf16 v[8:11], v[148:151], v[188:191], 0
	v_mfma_f32_16x16x32_bf16 v[4:7], v[156:159], v[188:191], 0
	v_mfma_f32_16x16x32_bf16 v[56:59], v[152:155], v[168:171], v[56:59]
	v_mfma_f32_16x16x32_bf16 v[52:55], v[160:163], v[168:171], v[52:55]
	v_mfma_f32_16x16x32_bf16 v[40:43], v[152:155], v[176:179], v[40:43]
	v_mfma_f32_16x16x32_bf16 v[36:39], v[160:163], v[176:179], v[36:39]
	v_mfma_f32_16x16x32_bf16 v[24:27], v[152:155], v[184:187], v[24:27]
	v_mfma_f32_16x16x32_bf16 v[20:23], v[160:163], v[184:187], v[20:23]
	v_mfma_f32_16x16x32_bf16 v[8:11], v[152:155], v[214:217], v[8:11]
	v_mfma_f32_16x16x32_bf16 v[4:7], v[160:163], v[214:217], v[4:7]
	s_setprio 0
	s_barrier
	s_add_i32 s56, 0, 0x18000
	s_add_i32 s57, 0, 0x1c000
	v_add_u32_e32 v144, s56, v240
	v_add_u32_e32 v160, s57, v240
	ds_read_b128 v[124:127], v144
	ds_read_b128 v[128:131], v144 offset:1024
	ds_read_b128 v[132:135], v144 offset:2048
	ds_read_b128 v[144:147], v144 offset:3072
	ds_read_b128 v[148:151], v160
	ds_read_b128 v[152:155], v160 offset:1024
	ds_read_b128 v[156:159], v160 offset:2048
	ds_read_b128 v[160:163], v160 offset:3072
	s_add_u32 s22, s36, 0x2b0000
	s_addc_u32 s23, s37, 0
	s_mov_b32 m0, s44
	v_lshl_add_u64 v[226:227], s[22:23], 0, v[208:209]
	ds_read_b128 v[164:167], v242 offset:32768
	ds_read_b128 v[168:171], v242 offset:33792
	ds_read_b128 v[172:175], v242 offset:34816
	ds_read_b128 v[176:179], v242 offset:35840
	ds_read_b128 v[180:183], v242 offset:36864
	ds_read_b128 v[184:187], v242 offset:37888
	ds_read_b128 v[188:191], v242 offset:38912
	ds_read_b128 v[214:217], v242 offset:39936
	global_load_lds_dwordx4 v[226:227], off
	v_lshl_add_u64 v[226:227], s[22:23], 0, v[206:207]
	s_mov_b32 m0, s45
	s_nop 0
	global_load_lds_dwordx4 v[226:227], off
	s_waitcnt vmcnt(8)
	s_waitcnt lgkmcnt(0)
	s_barrier
	s_setprio 1
	s_waitcnt lgkmcnt(0)
	v_mfma_f32_16x16x32_bf16 v[140:143], v[124:127], v[164:167], v[140:143]
	v_mfma_f32_16x16x32_bf16 v[136:139], v[132:135], v[164:167], v[136:139]
	v_mfma_f32_16x16x32_bf16 v[112:115], v[124:127], v[172:175], v[112:115]
	v_mfma_f32_16x16x32_bf16 v[108:111], v[132:135], v[172:175], v[108:111]
	v_mfma_f32_16x16x32_bf16 v[96:99], v[124:127], v[180:183], v[96:99]
	v_mfma_f32_16x16x32_bf16 v[92:95], v[132:135], v[180:183], v[92:95]
	v_mfma_f32_16x16x32_bf16 v[80:83], v[124:127], v[188:191], v[80:83]
	v_mfma_f32_16x16x32_bf16 v[76:79], v[132:135], v[188:191], v[76:79]
	v_mfma_f32_16x16x32_bf16 v[140:143], v[128:131], v[168:171], v[140:143]
	v_mfma_f32_16x16x32_bf16 v[136:139], v[144:147], v[168:171], v[136:139]
	v_mfma_f32_16x16x32_bf16 v[112:115], v[128:131], v[176:179], v[112:115]
	v_mfma_f32_16x16x32_bf16 v[108:111], v[144:147], v[176:179], v[108:111]
	v_mfma_f32_16x16x32_bf16 v[96:99], v[128:131], v[184:187], v[96:99]
	v_mfma_f32_16x16x32_bf16 v[92:95], v[144:147], v[184:187], v[92:95]
	v_mfma_f32_16x16x32_bf16 v[80:83], v[128:131], v[214:217], v[80:83]
	v_mfma_f32_16x16x32_bf16 v[76:79], v[144:147], v[214:217], v[76:79]
	s_setprio 0
	s_setprio 1
	v_mfma_f32_16x16x32_bf16 v[120:123], v[148:151], v[164:167], v[120:123]
	v_mfma_f32_16x16x32_bf16 v[116:119], v[156:159], v[164:167], v[116:119]
	v_mfma_f32_16x16x32_bf16 v[104:107], v[148:151], v[172:175], v[104:107]
	v_mfma_f32_16x16x32_bf16 v[100:103], v[156:159], v[172:175], v[100:103]
	v_mfma_f32_16x16x32_bf16 v[88:91], v[148:151], v[180:183], v[88:91]
	v_mfma_f32_16x16x32_bf16 v[84:87], v[156:159], v[180:183], v[84:87]
	v_mfma_f32_16x16x32_bf16 v[72:75], v[148:151], v[188:191], v[72:75]
	v_mfma_f32_16x16x32_bf16 v[68:71], v[156:159], v[188:191], v[68:71]
	v_mfma_f32_16x16x32_bf16 v[120:123], v[152:155], v[168:171], v[120:123]
	v_mfma_f32_16x16x32_bf16 v[116:119], v[160:163], v[168:171], v[116:119]
	v_mfma_f32_16x16x32_bf16 v[104:107], v[152:155], v[176:179], v[104:107]
	v_mfma_f32_16x16x32_bf16 v[100:103], v[160:163], v[176:179], v[100:103]
	v_mfma_f32_16x16x32_bf16 v[88:91], v[152:155], v[184:187], v[88:91]
	v_mfma_f32_16x16x32_bf16 v[84:87], v[160:163], v[184:187], v[84:87]
	v_mfma_f32_16x16x32_bf16 v[72:75], v[152:155], v[214:217], v[72:75]
	v_mfma_f32_16x16x32_bf16 v[68:71], v[160:163], v[214:217], v[68:71]
	s_setprio 0
	s_barrier
; #define PG8_STAGE(bufoff, gbase, voff) do { _Pragma("unroll") for (int _i = 0; _i < 2; ++_i) \
;         __builtin_amdgcn_global_load_lds((const unsigned*)((const char*)(gbase) + (voff)[_i]), (PG8_LAS unsigned*)(lds + (bufoff) + ldsw + _i * 8192), 16, 0, 0); } while (0)
; #define PG8_LDA(dst, b, h) do { _Pragma("unroll") for (int m = 0; m < 4; ++m) _Pragma("unroll") for (int k = 0; k < 2; ++k) dst[m][k] = *(const PG8_LAS bf16x8*)(lds + PG8_SA(b, h) + aoff + m * 2048 + k * 1024); } while (0)
; #define PG8_WAIT_V(n) asm volatile("s_waitcnt vmcnt(" #n ")" ::: "memory")
; #define PG8_WAIT_L(n) asm volatile("s_waitcnt lgkmcnt(" #n ")" ::: "memory")
; #define PG8_BAR __builtin_amdgcn_s_barrier()
; #define PG8_SCHED __builtin_amdgcn_sched_barrier(0)
; template <class Epi, class Sched, bool ALIGN_EPI = false, bool SP2 = false, bool I8 = false>
; __device__ __forceinline__ void gemm_phase(PG8_LAS unsigned char* lds, const Gemm g, const Sched& S, const Epi& E) {
;     ...
;             PG8_LDA(At, 1, 1); PG8_STAGE(PG8_SB(1, 0), b3, voffB); PG8_STAGE(PG8_SB(1, 1), b3 + hstep, voffB); PG8_STAGE(PG8_SA(1, 0), a3, voffA);
;             PG8_WAIT_V(8); PG8_WAIT_L(0); PG8_BAR; PG8_MMA(1, 0, At, B0); PG8_MMA(1, 1, At, B1); PG8_BAR; PG8_SCHED;
	s_add_i32 s22, s56, s41
	v_lshl_add_u64 v[218:219], v[218:219], 0, s[84:85]
	s_mov_b32 m0, s22
	ds_read_b128 v[164:167], v242 offset:49152
	ds_read_b128 v[168:171], v242 offset:50176
	ds_read_b128 v[172:175], v242 offset:51200
	ds_read_b128 v[176:179], v242 offset:52224
	ds_read_b128 v[180:183], v242 offset:53248
	ds_read_b128 v[184:187], v242 offset:54272
	ds_read_b128 v[188:191], v242 offset:55296
	ds_read_b128 v[214:217], v242 offset:56320
	global_load_lds_dwordx4 v[218:219], off
	s_add_i32 m0, s22, 0x2000
	s_add_u32 s22, s26, 0x2b0080
	v_lshl_add_u64 v[218:219], v[220:221], 0, s[84:85]
	s_addc_u32 s23, s27, 0
	s_add_i32 s26, s57, s41
	global_load_lds_dwordx4 v[218:219], off
	v_lshl_add_u64 v[218:219], s[22:23], 0, v[2:3]
	s_mov_b32 m0, s26
	s_nop 0
	global_load_lds_dwordx4 v[218:219], off
	v_lshl_add_u64 v[218:219], s[22:23], 0, v[204:205]
	s_add_i32 m0, s26, 0x2000
	s_nop 0
	global_load_lds_dwordx4 v[218:219], off
	v_lshl_add_u64 v[218:219], v[222:223], 0, s[84:85]
	s_mov_b32 m0, s46
	s_nop 0
	global_load_lds_dwordx4 v[218:219], off
	v_lshl_add_u64 v[218:219], v[224:225], 0, s[84:85]
	s_mov_b32 m0, s47
	s_nop 0
	global_load_lds_dwordx4 v[218:219], off
	s_waitcnt vmcnt(8)
	s_waitcnt lgkmcnt(0)
	s_barrier
	s_setprio 1
	s_waitcnt lgkmcnt(0)
	v_mfma_f32_16x16x32_bf16 v[64:67], v[124:127], v[164:167], v[64:67]
	v_mfma_f32_16x16x32_bf16 v[60:63], v[132:135], v[164:167], v[60:63]
	v_mfma_f32_16x16x32_bf16 v[48:51], v[124:127], v[172:175], v[48:51]
	v_mfma_f32_16x16x32_bf16 v[44:47], v[132:135], v[172:175], v[44:47]
	v_mfma_f32_16x16x32_bf16 v[32:35], v[124:127], v[180:183], v[32:35]
	v_mfma_f32_16x16x32_bf16 v[28:31], v[132:135], v[180:183], v[28:31]
	v_mfma_f32_16x16x32_bf16 v[16:19], v[124:127], v[188:191], v[16:19]
	v_mfma_f32_16x16x32_bf16 v[12:15], v[132:135], v[188:191], v[12:15]
	v_mfma_f32_16x16x32_bf16 v[64:67], v[128:131], v[168:171], v[64:67]
	v_mfma_f32_16x16x32_bf16 v[60:63], v[144:147], v[168:171], v[60:63]
	v_mfma_f32_16x16x32_bf16 v[48:51], v[128:131], v[176:179], v[48:51]
	v_mfma_f32_16x16x32_bf16 v[44:47], v[144:147], v[176:179], v[44:47]
	v_mfma_f32_16x16x32_bf16 v[32:35], v[128:131], v[184:187], v[32:35]
	v_mfma_f32_16x16x32_bf16 v[28:31], v[144:147], v[184:187], v[28:31]
	v_mfma_f32_16x16x32_bf16 v[16:19], v[128:131], v[214:217], v[16:19]
	v_mfma_f32_16x16x32_bf16 v[12:15], v[144:147], v[214:217], v[12:15]
	s_setprio 0
	s_setprio 1
	v_mfma_f32_16x16x32_bf16 v[56:59], v[148:151], v[164:167], v[56:59]
	v_mfma_f32_16x16x32_bf16 v[52:55], v[156:159], v[164:167], v[52:55]
	v_mfma_f32_16x16x32_bf16 v[40:43], v[148:151], v[172:175], v[40:43]
	v_mfma_f32_16x16x32_bf16 v[36:39], v[156:159], v[172:175], v[36:39]
	v_mfma_f32_16x16x32_bf16 v[24:27], v[148:151], v[180:183], v[24:27]
	v_mfma_f32_16x16x32_bf16 v[20:23], v[156:159], v[180:183], v[20:23]
	v_mfma_f32_16x16x32_bf16 v[8:11], v[148:151], v[188:191], v[8:11]
	v_mfma_f32_16x16x32_bf16 v[4:7], v[156:159], v[188:191], v[4:7]
	v_mfma_f32_16x16x32_bf16 v[56:59], v[152:155], v[168:171], v[56:59]
	v_mfma_f32_16x16x32_bf16 v[52:55], v[160:163], v[168:171], v[52:55]
	v_mfma_f32_16x16x32_bf16 v[40:43], v[152:155], v[176:179], v[40:43]
	v_mfma_f32_16x16x32_bf16 v[36:39], v[160:163], v[176:179], v[36:39]
	v_mfma_f32_16x16x32_bf16 v[24:27], v[152:155], v[184:187], v[24:27]
	v_mfma_f32_16x16x32_bf16 v[20:23], v[160:163], v[184:187], v[20:23]
	v_mfma_f32_16x16x32_bf16 v[8:11], v[152:155], v[214:217], v[8:11]
	v_mfma_f32_16x16x32_bf16 v[4:7], v[160:163], v[214:217], v[4:7]
	s_setprio 0
	s_barrier
	s_add_i32 s55, s55, 2
	s_add_u32 s53, s53, 0x100
	s_addc_u32 s54, s54, 0
	s_cmpk_gt_u32 s55, 0xa9
	s_mov_b64 s[22:23], s[24:25]
	s_cbranch_scc1 .Lkloop_exit_5

; #define PG8_BAR __builtin_amdgcn_s_barrier()
; template <class Epi, class Sched, bool ALIGN_EPI = false, bool SP2 = false, bool I8 = false>
; __device__ __forceinline__ void gemm_phase(PG8_LAS unsigned char* lds, const Gemm g, const Sched& S, const Epi& E) {
;     ...
;         }
;         if constexpr (ALIGN_EPI) { if (wr == 0) PG8_BAR; }
;         if constexpr (!Epi::AFTER_DRAIN) { E(acc, cur, wr, wc, fr, fq); S.done(cur); }
.Lkloop_exit_5:
	s_and_b64 vcc, exec, s[18:19]
	s_cbranch_vccz .LBB0_1703
	s_barrier

; #define PG8_STAGE(bufoff, gbase, voff) do { _Pragma("unroll") for (int _i = 0; _i < 2; ++_i) \
;         __builtin_amdgcn_global_load_lds((const unsigned*)((const char*)(gbase) + (voff)[_i]), (PG8_LAS unsigned*)(lds + (bufoff) + ldsw + _i * 8192), 16, 0, 0); } while (0)
; #define PG8_LDA(dst, b, h) do { _Pragma("unroll") for (int m = 0; m < 4; ++m) _Pragma("unroll") for (int k = 0; k < 2; ++k) dst[m][k] = *(const PG8_LAS bf16x8*)(lds + PG8_SA(b, h) + aoff + m * 2048 + k * 1024); } while (0)
; #define PG8_LDB(dst, b, h) do { _Pragma("unroll") for (int n = 0; n < 2; ++n) _Pragma("unroll") for (int k = 0; k < 2; ++k) dst[n][k] = *(const PG8_LAS bf16x8*)(lds + PG8_SB(b, h) + boff + n * 2048 + k * 1024); } while (0)
; #define PG8_WAIT_V(n) asm volatile("s_waitcnt vmcnt(" #n ")" ::: "memory")
; #define PG8_WAIT_L(n) asm volatile("s_waitcnt lgkmcnt(" #n ")" ::: "memory")
; #define PG8_BAR __builtin_amdgcn_s_barrier()
; #define PG8_SCHED __builtin_amdgcn_sched_barrier(0)
; template <class Epi, class Sched, bool ALIGN_EPI = false, bool SP2 = false, bool I8 = false>
; __device__ __forceinline__ void gemm_phase(PG8_LAS unsigned char* lds, const Gemm g, const Sched& S, const Epi& E) {
;     ...
;         const char* nA = has_next ? (const char*)g.A + (size_t)nxt.pm * tstep : cA; const char* nB = has_next ? (const char*)g.Bt + (size_t)nxt.pn * tstep : cB;
;         for (int t = 0; t < nt; t += 2) {
;             const bool last = (t == nt - 2);
;             const char* a1 = cA + (size_t)(t + 1) * kstep;
;             const char* a2 = last ? nA : cA + (size_t)(t + 2) * kstep; const char* b2 = last ? nB : cB + (size_t)(t + 2) * kstep;
;             const char* a3 = a2 + kstep; const char* b3 = b2 + kstep;
;             if (last && has_next) S.a_ready(nxt);
;             if constexpr (SP2) {
;             PG8_LDB(B0, 0, 0); PG8_LDB(B1, 0, 1); PG8_SCHED; PG8_LDA(At, 0, 0); PG8_STAGE(PG8_SA(1, 1), a1 + hstep, voffA);
;             PG8_WAIT_V(8); PG8_WAIT_L(0); PG8_BAR; PG8_MMA(0, 0, At, B0); PG8_MMA(0, 1, At, B1); PG8_BAR; PG8_SCHED;
;             PG8_LDA(At, 0, 1); PG8_STAGE(PG8_SB(0, 0), b2, voffB); PG8_STAGE(PG8_SB(0, 1), b2 + hstep, voffB); PG8_STAGE(PG8_SA(0, 0), a2, voffA);
;             PG8_WAIT_V(8); PG8_WAIT_L(0); PG8_BAR; PG8_MMA(1, 0, At, B0); PG8_MMA(1, 1, At, B1); PG8_BAR; PG8_SCHED;
.LBB0_1842:
	s_ashr_i32 s45, s44, 31
	s_lshl_b64 s[34:35], s[44:45], 20
	s_add_u32 s50, s47, s34
	s_addc_u32 s51, s52, s35
	s_and_b64 s[34:35], s[8:9], exec
	s_cselect_b32 s11, s51, s55
	s_cselect_b32 s13, s50, s54
	s_ashr_i32 s49, s48, 31
	s_lshl_b64 s[34:35], s[48:49], 20
	s_add_u32 s56, s53, s34
	s_addc_u32 s57, s64, s35
	s_and_b64 s[34:35], s[8:9], exec
	s_cselect_b32 s34, s57, s59
	s_cselect_b32 s35, s56, s58
	s_add_u32 s54, s54, 0x80080
	s_addc_u32 s55, s55, 0
	s_add_u32 s45, s58, 0x100
	s_addc_u32 s49, s59, 0
	s_mov_b32 s86, -2
	s_waitcnt lgkmcnt(0)
	s_add_u32 s58, s54, 0xfff80080
	s_addc_u32 s59, s55, -1
	s_add_i32 s87, 0, 0x10000
	s_cmp_eq_u32 s86, 28
	s_cselect_b32 s61, s11, s59
	s_cselect_b32 s60, s13, s58
	s_cselect_b32 s59, s34, s49
	s_cselect_b32 s58, s35, s45
	s_add_i32 vcc_lo, 0, 0x14000
	v_add_u32_e32 v40, s87, v217
	v_add_u32_e32 v160, vcc_lo, v217
	ds_read_b128 v[28:31], v40
	ds_read_b128 v[32:35], v40 offset:1024
	ds_read_b128 v[36:39], v40 offset:2048
	ds_read_b128 v[40:43], v40 offset:3072
	ds_read_b128 v[140:143], v160
	ds_read_b128 v[144:147], v160 offset:1024
	ds_read_b128 v[156:159], v160 offset:2048
	ds_read_b128 v[160:163], v160 offset:3072
	v_lshl_add_u64 v[190:191], s[54:55], 0, v[186:187]
	s_add_i32 m0, s65, 0xc000
	ds_read_b128 v[164:167], v219
	ds_read_b128 v[168:171], v219 offset:1024
	ds_read_b128 v[172:175], v219 offset:2048
	ds_read_b128 v[176:179], v219 offset:3072
	ds_read_b128 v[204:207], v219 offset:4096
	ds_read_b128 v[208:211], v219 offset:5120
	ds_read_b128 v[212:215], v219 offset:6144
	ds_read_b128 v[220:223], v219 offset:7168
	global_load_lds_dwordx4 v[190:191], off
	v_lshl_add_u64 v[190:191], s[54:55], 0, v[188:189]
	s_add_i32 m0, s65, 0xe000
	s_nop 0
	global_load_lds_dwordx4 v[190:191], off
	s_waitcnt vmcnt(8)
	s_waitcnt lgkmcnt(0)
	s_barrier
	s_setprio 1
	s_waitcnt lgkmcnt(0)
	v_mfma_i32_16x16x64_i8 v[152:155], v[28:31], v[164:167], 0
	v_mfma_i32_16x16x64_i8 v[148:151], v[36:39], v[164:167], 0
	v_mfma_i32_16x16x64_i8 v[128:131], v[28:31], v[172:175], 0
	v_mfma_i32_16x16x64_i8 v[124:127], v[36:39], v[172:175], 0
	v_mfma_i32_16x16x64_i8 v[112:115], v[28:31], v[204:207], 0
	v_mfma_i32_16x16x64_i8 v[108:111], v[36:39], v[204:207], 0
	v_mfma_i32_16x16x64_i8 v[96:99], v[28:31], v[212:215], 0
	v_mfma_i32_16x16x64_i8 v[92:95], v[36:39], v[212:215], 0
	v_mfma_i32_16x16x64_i8 v[152:155], v[32:35], v[168:171], v[152:155]
	v_mfma_i32_16x16x64_i8 v[148:151], v[40:43], v[168:171], v[148:151]
	v_mfma_i32_16x16x64_i8 v[128:131], v[32:35], v[176:179], v[128:131]
	v_mfma_i32_16x16x64_i8 v[124:127], v[40:43], v[176:179], v[124:127]
	v_mfma_i32_16x16x64_i8 v[112:115], v[32:35], v[208:211], v[112:115]
	v_mfma_i32_16x16x64_i8 v[108:111], v[40:43], v[208:211], v[108:111]
	v_mfma_i32_16x16x64_i8 v[96:99], v[32:35], v[220:223], v[96:99]
	v_mfma_i32_16x16x64_i8 v[92:95], v[40:43], v[220:223], v[92:95]
	s_setprio 0
	s_setprio 1
	v_mfma_i32_16x16x64_i8 v[136:139], v[140:143], v[164:167], 0
	v_mfma_i32_16x16x64_i8 v[132:135], v[156:159], v[164:167], 0
	v_mfma_i32_16x16x64_i8 v[120:123], v[140:143], v[172:175], 0
	v_mfma_i32_16x16x64_i8 v[116:119], v[156:159], v[172:175], 0
	v_mfma_i32_16x16x64_i8 v[104:107], v[140:143], v[204:207], 0
	v_mfma_i32_16x16x64_i8 v[100:103], v[156:159], v[204:207], 0
	v_mfma_i32_16x16x64_i8 v[88:91], v[140:143], v[212:215], 0
	v_mfma_i32_16x16x64_i8 v[84:87], v[156:159], v[212:215], 0
	v_mfma_i32_16x16x64_i8 v[136:139], v[144:147], v[168:171], v[136:139]
	v_mfma_i32_16x16x64_i8 v[132:135], v[160:163], v[168:171], v[132:135]
	v_mfma_i32_16x16x64_i8 v[120:123], v[144:147], v[176:179], v[120:123]
	v_mfma_i32_16x16x64_i8 v[116:119], v[160:163], v[176:179], v[116:119]
	v_mfma_i32_16x16x64_i8 v[104:107], v[144:147], v[208:211], v[104:107]
	v_mfma_i32_16x16x64_i8 v[100:103], v[160:163], v[208:211], v[100:103]
	v_mfma_i32_16x16x64_i8 v[88:91], v[144:147], v[220:223], v[88:91]
	v_mfma_i32_16x16x64_i8 v[84:87], v[160:163], v[220:223], v[84:87]
	s_setprio 0
	s_barrier
	s_add_i32 s87, s87, s46
	v_lshl_add_u64 v[190:191], s[58:59], 0, v[2:3]
	s_mov_b32 m0, s87
	ds_read_b128 v[164:167], v219 offset:16384
	ds_read_b128 v[168:171], v219 offset:17408
	ds_read_b128 v[172:175], v219 offset:18432
	ds_read_b128 v[176:179], v219 offset:19456
	ds_read_b128 v[204:207], v219 offset:20480
	ds_read_b128 v[208:211], v219 offset:21504
	ds_read_b128 v[212:215], v219 offset:22528
	ds_read_b128 v[220:223], v219 offset:23552
	global_load_lds_dwordx4 v[190:191], off
	s_add_i32 m0, s87, 0x2000
	s_add_u32 s96, s58, 0x80000
	v_lshl_add_u64 v[224:225], s[58:59], 0, v[184:185]
	s_addc_u32 s97, s59, 0
	s_add_i32 s87, vcc_lo, s46
	global_load_lds_dwordx4 v[224:225], off
	v_lshl_add_u64 v[226:227], s[96:97], 0, v[2:3]
	s_mov_b32 m0, s87
	v_lshl_add_u64 v[228:229], s[60:61], 0, v[182:183]
	global_load_lds_dwordx4 v[226:227], off
	v_lshl_add_u64 v[226:227], s[96:97], 0, v[184:185]
	s_add_i32 m0, s87, 0x2000
	s_nop 0
	global_load_lds_dwordx4 v[226:227], off
	v_lshl_add_u64 v[226:227], s[60:61], 0, v[180:181]
	s_mov_b32 m0, s65
	s_nop 0
	global_load_lds_dwordx4 v[226:227], off
	s_mov_b32 m0, s67
	s_nop 0
	global_load_lds_dwordx4 v[228:229], off
	s_waitcnt vmcnt(8)
	s_waitcnt lgkmcnt(0)
	s_barrier
; #define PG8_STAGE(bufoff, gbase, voff) do { _Pragma("unroll") for (int _i = 0; _i < 2; ++_i) \
;         __builtin_amdgcn_global_load_lds((const unsigned*)((const char*)(gbase) + (voff)[_i]), (PG8_LAS unsigned*)(lds + (bufoff) + ldsw + _i * 8192), 16, 0, 0); } while (0)
; #define PG8_LDA(dst, b, h) do { _Pragma("unroll") for (int m = 0; m < 4; ++m) _Pragma("unroll") for (int k = 0; k < 2; ++k) dst[m][k] = *(const PG8_LAS bf16x8*)(lds + PG8_SA(b, h) + aoff + m * 2048 + k * 1024); } while (0)
; #define PG8_LDB(dst, b, h) do { _Pragma("unroll") for (int n = 0; n < 2; ++n) _Pragma("unroll") for (int k = 0; k < 2; ++k) dst[n][k] = *(const PG8_LAS bf16x8*)(lds + PG8_SB(b, h) + boff + n * 2048 + k * 1024); } while (0)
; #define PG8_WAIT_V(n) asm volatile("s_waitcnt vmcnt(" #n ")" ::: "memory")
; #define PG8_WAIT_L(n) asm volatile("s_waitcnt lgkmcnt(" #n ")" ::: "memory")
; #define PG8_BAR __builtin_amdgcn_s_barrier()
; #define PG8_SCHED __builtin_amdgcn_sched_barrier(0)
; template <class Epi, class Sched, bool ALIGN_EPI = false, bool SP2 = false, bool I8 = false>
; __device__ __forceinline__ void gemm_phase(PG8_LAS unsigned char* lds, const Gemm g, const Sched& S, const Epi& E) {
;     ...
;             PG8_WAIT_V(8); PG8_WAIT_L(0); PG8_BAR; PG8_MMA(1, 0, At, B0); PG8_MMA(1, 1, At, B1); PG8_BAR; PG8_SCHED;
;             PG8_LDB(B0, 1, 0); PG8_LDB(B1, 1, 1); PG8_SCHED; PG8_LDA(At, 1, 0); PG8_STAGE(PG8_SA(0, 1), a2 + hstep, voffA);
;             PG8_WAIT_V(8); PG8_WAIT_L(0); PG8_BAR; PG8_MMA(0, 0, At, B0); PG8_MMA(0, 1, At, B1); PG8_BAR; PG8_SCHED;
	s_setprio 1
	s_waitcnt lgkmcnt(0)
	v_mfma_i32_16x16x64_i8 v[80:83], v[28:31], v[164:167], 0
	v_mfma_i32_16x16x64_i8 v[76:79], v[36:39], v[164:167], 0
	v_mfma_i32_16x16x64_i8 v[64:67], v[28:31], v[172:175], 0
	v_mfma_i32_16x16x64_i8 v[60:63], v[36:39], v[172:175], 0
	v_mfma_i32_16x16x64_i8 v[48:51], v[28:31], v[204:207], 0
	v_mfma_i32_16x16x64_i8 v[44:47], v[36:39], v[204:207], 0
	v_mfma_i32_16x16x64_i8 v[16:19], v[28:31], v[212:215], 0
	v_mfma_i32_16x16x64_i8 v[12:15], v[36:39], v[212:215], 0
	v_mfma_i32_16x16x64_i8 v[80:83], v[32:35], v[168:171], v[80:83]
	v_mfma_i32_16x16x64_i8 v[76:79], v[40:43], v[168:171], v[76:79]
	v_mfma_i32_16x16x64_i8 v[64:67], v[32:35], v[176:179], v[64:67]
	v_mfma_i32_16x16x64_i8 v[60:63], v[40:43], v[176:179], v[60:63]
	v_mfma_i32_16x16x64_i8 v[48:51], v[32:35], v[208:211], v[48:51]
	v_mfma_i32_16x16x64_i8 v[44:47], v[40:43], v[208:211], v[44:47]
	v_mfma_i32_16x16x64_i8 v[16:19], v[32:35], v[220:223], v[16:19]
	v_mfma_i32_16x16x64_i8 v[12:15], v[40:43], v[220:223], v[12:15]
	s_setprio 0
	s_setprio 1
	v_mfma_i32_16x16x64_i8 v[24:27], v[140:143], v[204:207], 0
	v_mfma_i32_16x16x64_i8 v[20:23], v[156:159], v[204:207], 0
	v_mfma_i32_16x16x64_i8 v[8:11], v[140:143], v[212:215], 0
	v_mfma_i32_16x16x64_i8 v[4:7], v[156:159], v[212:215], 0
	v_mfma_i32_16x16x64_i8 v[28:31], v[140:143], v[164:167], 0
	v_mfma_i32_16x16x64_i8 v[32:35], v[156:159], v[164:167], 0
	v_mfma_i32_16x16x64_i8 v[36:39], v[140:143], v[172:175], 0
	v_mfma_i32_16x16x64_i8 v[40:43], v[156:159], v[172:175], 0
	v_mfma_i32_16x16x64_i8 v[24:27], v[144:147], v[208:211], v[24:27]
	v_mfma_i32_16x16x64_i8 v[20:23], v[160:163], v[208:211], v[20:23]
	v_mfma_i32_16x16x64_i8 v[8:11], v[144:147], v[220:223], v[8:11]
	v_mfma_i32_16x16x64_i8 v[4:7], v[160:163], v[220:223], v[4:7]
	v_mfma_i32_16x16x64_i8 v[28:31], v[144:147], v[168:171], v[28:31]
	v_mfma_i32_16x16x64_i8 v[32:35], v[160:163], v[168:171], v[32:35]
	v_mfma_i32_16x16x64_i8 v[36:39], v[144:147], v[176:179], v[36:39]
	v_mfma_i32_16x16x64_i8 v[40:43], v[160:163], v[176:179], v[40:43]
	s_setprio 0
	s_barrier
	s_add_i32 s87, 0, 0x18000
	s_add_i32 s96, 0, 0x1c000
	v_add_u32_e32 v72, s87, v217
	v_add_u32_e32 v160, s96, v217
	ds_read_b128 v[52:55], v72
	ds_read_b128 v[56:59], v72 offset:1024
	ds_read_b128 v[68:71], v72 offset:2048
	ds_read_b128 v[72:75], v72 offset:3072
	ds_read_b128 v[140:143], v160
	ds_read_b128 v[144:147], v160 offset:1024
	ds_read_b128 v[156:159], v160 offset:2048
	ds_read_b128 v[160:163], v160 offset:3072
	s_add_u32 s60, s60, 0x80000
	s_addc_u32 s61, s61, 0
	s_mov_b32 m0, s72
	v_lshl_add_u64 v[240:241], s[60:61], 0, v[180:181]
	ds_read_b128 v[164:167], v219 offset:32768
	ds_read_b128 v[168:171], v219 offset:33792
	ds_read_b128 v[172:175], v219 offset:34816
	ds_read_b128 v[176:179], v219 offset:35840
	ds_read_b128 v[204:207], v219 offset:36864
	ds_read_b128 v[208:211], v219 offset:37888
	ds_read_b128 v[212:215], v219 offset:38912
	ds_read_b128 v[220:223], v219 offset:39936
	global_load_lds_dwordx4 v[240:241], off
	v_lshl_add_u64 v[240:241], s[60:61], 0, v[182:183]
	s_mov_b32 m0, s73
	s_nop 0
	global_load_lds_dwordx4 v[240:241], off
	s_waitcnt vmcnt(8)
	s_waitcnt lgkmcnt(0)
	s_barrier
	s_setprio 1
	s_waitcnt lgkmcnt(0)
	v_mfma_i32_16x16x64_i8 v[152:155], v[52:55], v[164:167], v[152:155]
	v_mfma_i32_16x16x64_i8 v[148:151], v[68:71], v[164:167], v[148:151]
	v_mfma_i32_16x16x64_i8 v[128:131], v[52:55], v[172:175], v[128:131]
	v_mfma_i32_16x16x64_i8 v[124:127], v[68:71], v[172:175], v[124:127]
	v_mfma_i32_16x16x64_i8 v[112:115], v[52:55], v[204:207], v[112:115]
	v_mfma_i32_16x16x64_i8 v[108:111], v[68:71], v[204:207], v[108:111]
	v_mfma_i32_16x16x64_i8 v[96:99], v[52:55], v[212:215], v[96:99]
	v_mfma_i32_16x16x64_i8 v[92:95], v[68:71], v[212:215], v[92:95]
	v_mfma_i32_16x16x64_i8 v[152:155], v[56:59], v[168:171], v[152:155]
	v_mfma_i32_16x16x64_i8 v[148:151], v[72:75], v[168:171], v[148:151]
	v_mfma_i32_16x16x64_i8 v[128:131], v[56:59], v[176:179], v[128:131]
	v_mfma_i32_16x16x64_i8 v[124:127], v[72:75], v[176:179], v[124:127]
	v_mfma_i32_16x16x64_i8 v[112:115], v[56:59], v[208:211], v[112:115]
	v_mfma_i32_16x16x64_i8 v[108:111], v[72:75], v[208:211], v[108:111]
	v_mfma_i32_16x16x64_i8 v[96:99], v[56:59], v[220:223], v[96:99]
	v_mfma_i32_16x16x64_i8 v[92:95], v[72:75], v[220:223], v[92:95]
	s_setprio 0
	s_setprio 1
	v_mfma_i32_16x16x64_i8 v[136:139], v[140:143], v[164:167], v[136:139]
	v_mfma_i32_16x16x64_i8 v[132:135], v[156:159], v[164:167], v[132:135]
	v_mfma_i32_16x16x64_i8 v[120:123], v[140:143], v[172:175], v[120:123]
	v_mfma_i32_16x16x64_i8 v[116:119], v[156:159], v[172:175], v[116:119]
	v_mfma_i32_16x16x64_i8 v[104:107], v[140:143], v[204:207], v[104:107]
	v_mfma_i32_16x16x64_i8 v[100:103], v[156:159], v[204:207], v[100:103]
	v_mfma_i32_16x16x64_i8 v[88:91], v[140:143], v[212:215], v[88:91]
	v_mfma_i32_16x16x64_i8 v[84:87], v[156:159], v[212:215], v[84:87]
	v_mfma_i32_16x16x64_i8 v[136:139], v[144:147], v[168:171], v[136:139]
	v_mfma_i32_16x16x64_i8 v[132:135], v[160:163], v[168:171], v[132:135]
	v_mfma_i32_16x16x64_i8 v[120:123], v[144:147], v[176:179], v[120:123]
	v_mfma_i32_16x16x64_i8 v[116:119], v[160:163], v[176:179], v[116:119]
	v_mfma_i32_16x16x64_i8 v[104:107], v[144:147], v[208:211], v[104:107]
	v_mfma_i32_16x16x64_i8 v[100:103], v[160:163], v[208:211], v[100:103]
	v_mfma_i32_16x16x64_i8 v[88:91], v[144:147], v[220:223], v[88:91]
	v_mfma_i32_16x16x64_i8 v[84:87], v[160:163], v[220:223], v[84:87]
	s_setprio 0
	s_barrier
; #define PG8_STAGE(bufoff, gbase, voff) do { _Pragma("unroll") for (int _i = 0; _i < 2; ++_i) \
;         __builtin_amdgcn_global_load_lds((const unsigned*)((const char*)(gbase) + (voff)[_i]), (PG8_LAS unsigned*)(lds + (bufoff) + ldsw + _i * 8192), 16, 0, 0); } while (0)
; #define PG8_LDA(dst, b, h) do { _Pragma("unroll") for (int m = 0; m < 4; ++m) _Pragma("unroll") for (int k = 0; k < 2; ++k) dst[m][k] = *(const PG8_LAS bf16x8*)(lds + PG8_SA(b, h) + aoff + m * 2048 + k * 1024); } while (0)
; #define PG8_WAIT_V(n) asm volatile("s_waitcnt vmcnt(" #n ")" ::: "memory")
; #define PG8_WAIT_L(n) asm volatile("s_waitcnt lgkmcnt(" #n ")" ::: "memory")
; #define PG8_BAR __builtin_amdgcn_s_barrier()
; #define PG8_SCHED __builtin_amdgcn_sched_barrier(0)
; template <class Epi, class Sched, bool ALIGN_EPI = false, bool SP2 = false, bool I8 = false>
; __device__ __forceinline__ void gemm_phase(PG8_LAS unsigned char* lds, const Gemm g, const Sched& S, const Epi& E) {
;     ...
;             PG8_LDA(At, 1, 1); PG8_STAGE(PG8_SB(1, 0), b3, voffB); PG8_STAGE(PG8_SB(1, 1), b3 + hstep, voffB); PG8_STAGE(PG8_SA(1, 0), a3, voffA);
;             PG8_WAIT_V(8); PG8_WAIT_L(0); PG8_BAR; PG8_MMA(1, 0, At, B0); PG8_MMA(1, 1, At, B1); PG8_BAR; PG8_SCHED;
	s_add_i32 s60, s87, s46
	v_lshl_add_u64 v[190:191], v[190:191], 0, s[84:85]
	s_mov_b32 m0, s60
	ds_read_b128 v[164:167], v219 offset:49152
	ds_read_b128 v[168:171], v219 offset:50176
	ds_read_b128 v[172:175], v219 offset:51200
	ds_read_b128 v[176:179], v219 offset:52224
	ds_read_b128 v[204:207], v219 offset:53248
	ds_read_b128 v[208:211], v219 offset:54272
	ds_read_b128 v[212:215], v219 offset:55296
	ds_read_b128 v[220:223], v219 offset:56320
	global_load_lds_dwordx4 v[190:191], off
	s_add_i32 m0, s60, 0x2000
	s_add_u32 s58, s58, 0x80080
	v_lshl_add_u64 v[190:191], v[224:225], 0, s[84:85]
	s_addc_u32 s59, s59, 0
	s_add_i32 s60, s96, s46
	global_load_lds_dwordx4 v[190:191], off
	v_lshl_add_u64 v[190:191], s[58:59], 0, v[2:3]
	s_mov_b32 m0, s60
	s_nop 0
	global_load_lds_dwordx4 v[190:191], off
	v_lshl_add_u64 v[190:191], s[58:59], 0, v[184:185]
	s_add_i32 m0, s60, 0x2000
	s_nop 0
	global_load_lds_dwordx4 v[190:191], off
	v_lshl_add_u64 v[190:191], v[226:227], 0, s[84:85]
	s_mov_b32 m0, s28
	s_nop 0
	global_load_lds_dwordx4 v[190:191], off
	v_lshl_add_u64 v[190:191], v[228:229], 0, s[84:85]
	s_mov_b32 m0, s77
	s_nop 0
	global_load_lds_dwordx4 v[190:191], off
	s_waitcnt vmcnt(8)
	s_waitcnt lgkmcnt(0)
	s_barrier
	s_setprio 1
	s_waitcnt lgkmcnt(0)
	v_mfma_i32_16x16x64_i8 v[80:83], v[52:55], v[164:167], v[80:83]
	v_mfma_i32_16x16x64_i8 v[76:79], v[68:71], v[164:167], v[76:79]
	v_mfma_i32_16x16x64_i8 v[64:67], v[52:55], v[172:175], v[64:67]
	v_mfma_i32_16x16x64_i8 v[60:63], v[68:71], v[172:175], v[60:63]
	v_mfma_i32_16x16x64_i8 v[48:51], v[52:55], v[204:207], v[48:51]
	v_mfma_i32_16x16x64_i8 v[44:47], v[68:71], v[204:207], v[44:47]
	v_mfma_i32_16x16x64_i8 v[16:19], v[52:55], v[212:215], v[16:19]
	v_mfma_i32_16x16x64_i8 v[12:15], v[68:71], v[212:215], v[12:15]
	v_mfma_i32_16x16x64_i8 v[80:83], v[56:59], v[168:171], v[80:83]
	v_mfma_i32_16x16x64_i8 v[76:79], v[72:75], v[168:171], v[76:79]
	v_mfma_i32_16x16x64_i8 v[64:67], v[56:59], v[176:179], v[64:67]
	v_mfma_i32_16x16x64_i8 v[60:63], v[72:75], v[176:179], v[60:63]
	v_mfma_i32_16x16x64_i8 v[48:51], v[56:59], v[208:211], v[48:51]
	v_mfma_i32_16x16x64_i8 v[44:47], v[72:75], v[208:211], v[44:47]
	v_mfma_i32_16x16x64_i8 v[16:19], v[56:59], v[220:223], v[16:19]
	v_mfma_i32_16x16x64_i8 v[12:15], v[72:75], v[220:223], v[12:15]
	s_setprio 0
	s_setprio 1
	v_mfma_i32_16x16x64_i8 v[28:31], v[140:143], v[164:167], v[28:31]
	v_mfma_i32_16x16x64_i8 v[72:75], v[144:147], v[168:171], v[28:31]
	v_mfma_i32_16x16x64_i8 v[28:31], v[156:159], v[164:167], v[32:35]
	v_mfma_i32_16x16x64_i8 v[68:71], v[160:163], v[168:171], v[28:31]
	v_mfma_i32_16x16x64_i8 v[28:31], v[140:143], v[172:175], v[36:39]
	v_mfma_i32_16x16x64_i8 v[56:59], v[144:147], v[176:179], v[28:31]
	v_mfma_i32_16x16x64_i8 v[28:31], v[156:159], v[172:175], v[40:43]
	v_mfma_i32_16x16x64_i8 v[24:27], v[140:143], v[204:207], v[24:27]
	v_mfma_i32_16x16x64_i8 v[20:23], v[156:159], v[204:207], v[20:23]
	v_mfma_i32_16x16x64_i8 v[8:11], v[140:143], v[212:215], v[8:11]
	v_mfma_i32_16x16x64_i8 v[4:7], v[156:159], v[212:215], v[4:7]
	v_mfma_i32_16x16x64_i8 v[52:55], v[160:163], v[176:179], v[28:31]
	v_mfma_i32_16x16x64_i8 v[24:27], v[144:147], v[208:211], v[24:27]
	v_mfma_i32_16x16x64_i8 v[20:23], v[160:163], v[208:211], v[20:23]
	v_mfma_i32_16x16x64_i8 v[8:11], v[144:147], v[220:223], v[8:11]
	v_mfma_i32_16x16x64_i8 v[4:7], v[160:163], v[220:223], v[4:7]
	s_setprio 0
	s_barrier
	s_add_i32 s86, s86, 2
	s_add_u32 s54, s54, 0x100
	s_addc_u32 s55, s55, 0
	s_add_u32 s45, s45, 0x100
	s_addc_u32 s49, s49, 0
	s_cmp_gt_u32 s86, 29
	s_cbranch_scc1 .Lkloop_exit_6

; #define PG8_BAR __builtin_amdgcn_s_barrier()
; template <class Epi, class Sched, bool ALIGN_EPI = false, bool SP2 = false, bool I8 = false>
; __device__ __forceinline__ void gemm_phase(PG8_LAS unsigned char* lds, const Gemm g, const Sched& S, const Epi& E) {
;     ...
;         }
;         if constexpr (ALIGN_EPI) { if (wr == 0) PG8_BAR; }
;         if constexpr (!Epi::AFTER_DRAIN) { E(acc, cur, wr, wc, fr, fq); S.done(cur); }
.Lkloop_exit_6:
	s_and_b64 vcc, exec, s[38:39]
	s_cbranch_vccz .LBB0_1846
	s_barrier
